# scan loops: compiler vmcnt waits neutralized (top-of-step counted waits govern), k=2 fin loads retargeted, finish-step stores retire one step later
# speedup vs baseline: 1.0026x; 1.0026x over previous
; #define LAS __attribute__((address_space(3)))
; __device__ __forceinline__ f32x4 unpack4(const v2u w) { f32x4 r; r[0] = bflo(w.x); r[1] = bfhi(w.x); r[2] = bflo(w.y); r[3] = bfhi(w.y); return r; }
; template <bool GDN, int NT> __device__ __forceinline__ void scan_load(const Frame& F, int b, int h, int dir, const ScanLane& L, int s, ScanOps<NT>& o) {
;     ...
;         const char* zq = upin((const char*)F.Z + ((size_t)chunk_row0(b, cidx) * ZW + ZC_LQ + h * 64) * 2);
; #pragma unroll
;         for (int ks = 0; ks < 2; ++ks) { o.Qf[ks] = ldu<bf16x8>(zq + ks * 64, L.zq); o.Mf[ks] = o.Qf[ks]; }
;         const char* base = (const char*)F.PM + (size_t)ud * 20480;
;         const char* bO = upin(base); const char* bB = upin(base + 10240);
; #pragma unroll
;         for (int pr = 0; pr < 2; ++pr) { const v4u qb = ldun<v4u>(bB + pr * 1024, L.o16p), qo = ldun<v4u>(bO + pr * 1024, L.o16p);
;             o.bv[2 * pr] = (v2u){qb.x, qb.y}; o.bv[2 * pr + 1] = (v2u){qb.z, qb.w}; o.ov[2 * pr] = (v2u){qo.x, qo.y}; o.ov[2 * pr + 1] = (v2u){qo.z, qo.w}; }
;         o.bv[4] = ldun<v2u>(bB + 2048, L.o8); o.ov[4] = ldun<v2u>(bO + 2048, L.o8);
;         o.wi = ldu<f32x4>(upin((const char*)F.WI + (size_t)ud * 256), L.wi);
;     ...
;     const float gl = ((const LAS float*)(St + 4 * 80 * 72))[(dir ? (s < 4 ? 3 - s : 39 - s) : s) * 2 + dir];
;     f32x4 O[NT];
; #pragma unroll
;     for (int t = 0; t < NT; ++t) {
;         const LAS bf16_t* sp2 = Sb + (16 * t + lr) * 72 + 8 * lq;
;         const bf16x8 s0 = *(const LAS bf16x8*)sp2, s1 = *(const LAS bf16x8*)(sp2 + 32);
;         const f32x4 bv = unpack4(use.bv[t]), ov = unpack4(use.ov[t]);
;         if (GDN) {
;             f32x4 o = ov, sn = S[t] * gl + bv;
;             o = __builtin_amdgcn_mfma_f32_16x16x32_bf16(use.Qf[0], s0, o, 0, 0, 0); o = __builtin_amdgcn_mfma_f32_16x16x32_bf16(use.Qf[1], s1, o, 0, 0, 0);
;             sn = __builtin_amdgcn_mfma_f32_16x16x32_bf16(use.Mf[0], s0, sn, 0, 0, 0); sn = __builtin_amdgcn_mfma_f32_16x16x32_bf16(use.Mf[1], s1, sn, 0, 0, 0);
;             S[t] = sn; O[t] = o;
;         } else {
;             f32x4 o = {0.f, 0.f, 0.f, 0.f};
;             o = __builtin_amdgcn_mfma_f32_16x16x32_bf16(use.Qf[0], s0, o, 0, 0, 0); o = __builtin_amdgcn_mfma_f32_16x16x32_bf16(use.Qf[1], s1, o, 0, 0, 0);
;             S[t] = S[t] * gl + bv; O[t] = o * use.wi + ov; }
.LBB0_346:
	s_add_i32 s0, s25, 5
	s_min_u32 s3, s0, 33
	s_add_i32 s6, s3, 2
	s_sub_i32 s3, 37, s3
	s_and_b64 s[4:5], s[90:91], exec
	s_cselect_b32 s3, s6, s3
	s_lshl_b32 s4, s3, 6
	s_add_i32 s4, s4, s33
	s_add_i32 s3, s3, s31
	s_mulk_i32 s4, 0xd00
	s_lshl_b32 s3, s3, 1
	s_or_b32 s4, s36, s4
	s_mov_b32 s5, s37
	s_add_i32 s92, s3, s68
	s_lshl_b64 s[4:5], s[4:5], 1
	s_add_u32 s4, s16, s4
	s_addc_u32 s5, s17, s5
	global_load_dwordx4 v[24:27], v28, s[4:5]
	global_load_dwordx4 v[20:23], v28, s[4:5] offset:64
	s_mul_i32 s4, s92, 0x5000
	v_readlane_b32 s5, v254, 46
	s_mul_hi_u32 s3, s92, 0x5000
	s_add_u32 s4, s5, s4
	v_readlane_b32 s5, v254, 47
	s_addc_u32 s5, s5, s3
	s_mov_b64 s[6:7], s[4:5]
	s_add_u32 s4, s4, 0x2800
	s_addc_u32 s5, s5, 0
	s_nop 0
	global_load_dwordx4 v[44:47], v32, s[4:5] nt
	global_load_dwordx4 v[28:31], v32, s[4:5] offset:1024 nt
	global_load_dwordx4 v[52:55], v32, s[6:7] nt
	s_nop 0
	global_load_dwordx4 v[32:35], v32, s[6:7] offset:1024 nt
	s_nop 0
	global_load_dwordx2 v[140:141], v100, s[4:5] offset:2048 nt
	global_load_dwordx2 v[138:139], v100, s[6:7] offset:2048 nt
	s_lshl_b64 s[4:5], s[92:93], 8
	v_readlane_b32 s6, v254, 52
	v_readlane_b32 s7, v254, 53
	s_add_u32 s4, s6, s4
	s_addc_u32 s5, s7, s5
	s_add_i32 s3, s24, 37
	v_lshl_add_u64 v[184:185], s[4:5], 0, v[0:1]
	s_and_b64 s[4:5], s[90:91], exec
	s_cselect_b32 s0, s0, s3
	s_lshl_b32 s0, s0, 3
	s_add_i32 s0, s34, s0
	v_mov_b32_e32 v0, s0
	ds_read_b32 v0, v0 offset:46080
	ds_read_b128 v[100:103], v203 offset:11520
	ds_read_b128 v[104:107], v203 offset:11584
	s_waitcnt lgkmcnt(1)
	v_mfma_f32_16x16x32_bf16 v[100:103], v[56:59], v[100:103], 0
	s_waitcnt vmcnt(63)
	v_lshlrev_b32_e32 v108, 16, v84
	v_and_b32_e32 v109, 0xffff0000, v84
	v_lshlrev_b32_e32 v110, 16, v85
	s_waitcnt lgkmcnt(0)
	v_mfma_f32_16x16x32_bf16 v[100:103], v[48:51], v[104:107], v[100:103]
	v_and_b32_e32 v111, 0xffff0000, v85
	s_waitcnt vmcnt(63)
	v_lshlrev_b32_e32 v112, 16, v88
	v_and_b32_e32 v113, 0xffff0000, v88
	v_lshlrev_b32_e32 v114, 16, v89
	v_and_b32_e32 v115, 0xffff0000, v89
	v_pk_fma_f32 v[150:151], v[192:193], v[0:1], v[110:111] op_sel_hi:[1,0,1]
	v_pk_fma_f32 v[148:149], v[190:191], v[0:1], v[108:109] op_sel_hi:[1,0,1]
	s_waitcnt vmcnt(63)
	v_pk_fma_f32 v[108:109], v[74:75], v[102:103], v[114:115]
	v_pk_fma_f32 v[110:111], v[72:73], v[100:101], v[112:113]
	ds_read_b128 v[100:103], v203 offset:13824
	ds_read_b128 v[104:107], v203 offset:13888
	s_waitcnt lgkmcnt(1)
	v_mfma_f32_16x16x32_bf16 v[100:103], v[56:59], v[100:103], 0
	v_lshlrev_b32_e32 v112, 16, v86
	v_and_b32_e32 v113, 0xffff0000, v86
	v_lshlrev_b32_e32 v114, 16, v87
	s_waitcnt lgkmcnt(0)
	v_mfma_f32_16x16x32_bf16 v[100:103], v[48:51], v[104:107], v[100:103]
	v_and_b32_e32 v115, 0xffff0000, v87
	v_lshlrev_b32_e32 v116, 16, v90
	v_and_b32_e32 v117, 0xffff0000, v90
	v_lshlrev_b32_e32 v118, 16, v91
	v_and_b32_e32 v119, 0xffff0000, v91
	v_pk_fma_f32 v[152:153], v[188:189], v[0:1], v[114:115] op_sel_hi:[1,0,1]
	v_pk_fma_f32 v[154:155], v[154:155], v[0:1], v[112:113] op_sel_hi:[1,0,1]
	s_nop 0
	v_pk_fma_f32 v[112:113], v[74:75], v[102:103], v[118:119]
	v_pk_fma_f32 v[114:115], v[72:73], v[100:101], v[116:117]
	ds_read_b128 v[100:103], v203 offset:16128
	ds_read_b128 v[104:107], v203 offset:16192
	s_waitcnt lgkmcnt(1)
	v_mfma_f32_16x16x32_bf16 v[100:103], v[56:59], v[100:103], 0
	v_lshlrev_b32_e32 v116, 16, v76
	v_and_b32_e32 v117, 0xffff0000, v76
	v_lshlrev_b32_e32 v118, 16, v77
	s_waitcnt lgkmcnt(0)
; #define LAS __attribute__((address_space(3)))
; template <int N> __device__ __forceinline__ float row16_bcast(float v) { return dppf<0x150 + N>(v); }
; __device__ __forceinline__ float frcp(float x) { return __builtin_amdgcn_rcpf(x); }
; __device__ __forceinline__ f32x4 unpack4(const v2u w) { f32x4 r; r[0] = bflo(w.x); r[1] = bfhi(w.x); r[2] = bflo(w.y); r[3] = bfhi(w.y); return r; }
;     ...
;     for (int t = 0; t < NT; ++t) {
;         const LAS bf16_t* sp2 = Sb + (16 * t + lr) * 72 + 8 * lq;
;         const bf16x8 s0 = *(const LAS bf16x8*)sp2, s1 = *(const LAS bf16x8*)(sp2 + 32);
;         const f32x4 bv = unpack4(use.bv[t]), ov = unpack4(use.ov[t]);
;         if (GDN) {
;             f32x4 o = ov, sn = S[t] * gl + bv;
;             o = __builtin_amdgcn_mfma_f32_16x16x32_bf16(use.Qf[0], s0, o, 0, 0, 0); o = __builtin_amdgcn_mfma_f32_16x16x32_bf16(use.Qf[1], s1, o, 0, 0, 0);
;             sn = __builtin_amdgcn_mfma_f32_16x16x32_bf16(use.Mf[0], s0, sn, 0, 0, 0); sn = __builtin_amdgcn_mfma_f32_16x16x32_bf16(use.Mf[1], s1, sn, 0, 0, 0);
;             S[t] = sn; O[t] = o;
;         } else {
;             f32x4 o = {0.f, 0.f, 0.f, 0.f};
;             o = __builtin_amdgcn_mfma_f32_16x16x32_bf16(use.Qf[0], s0, o, 0, 0, 0); o = __builtin_amdgcn_mfma_f32_16x16x32_bf16(use.Qf[1], s1, o, 0, 0, 0);
;             S[t] = S[t] * gl + bv; O[t] = o * use.wi + ov; }
;     }
;     if (!GDN) {
; #pragma unroll
;         for (int i = 0; i < 4; ++i) { const float den = row16_bcast<0>(O[NT - 1][i]), fl = row16_bcast<1>(O[NT - 1][i]); const float dv = frcp(fmaxf(fabsf(den), fl));
; #pragma unroll
;             for (int t = 0; t < 4; ++t) O[t][i] *= dv; }
;     }
; #pragma unroll
;     for (int t = 0; t < 4; ++t) Oprev[t] = O[t];
	v_mfma_f32_16x16x32_bf16 v[100:103], v[48:51], v[104:107], v[100:103]
	v_and_b32_e32 v119, 0xffff0000, v77
	v_lshlrev_b32_e32 v160, 16, v80
	v_and_b32_e32 v161, 0xffff0000, v80
	v_lshlrev_b32_e32 v166, 16, v81
	v_and_b32_e32 v167, 0xffff0000, v81
	v_pk_fma_f32 v[156:157], v[186:187], v[0:1], v[118:119] op_sel_hi:[1,0,1]
	v_pk_fma_f32 v[158:159], v[182:183], v[0:1], v[116:117] op_sel_hi:[1,0,1]
	s_nop 0
	v_pk_fma_f32 v[116:117], v[74:75], v[102:103], v[166:167]
	v_pk_fma_f32 v[118:119], v[72:73], v[100:101], v[160:161]
	ds_read_b128 v[100:103], v203 offset:18432
	ds_read_b128 v[104:107], v203 offset:18496
	s_waitcnt lgkmcnt(1)
	v_mfma_f32_16x16x32_bf16 v[100:103], v[56:59], v[100:103], 0
	v_lshlrev_b32_e32 v166, 16, v78
	v_and_b32_e32 v167, 0xffff0000, v78
	v_lshlrev_b32_e32 v160, 16, v79
	s_waitcnt lgkmcnt(0)
	v_mfma_f32_16x16x32_bf16 v[100:103], v[48:51], v[104:107], v[100:103]
	v_and_b32_e32 v161, 0xffff0000, v79
	v_lshlrev_b32_e32 v168, 16, v82
	v_and_b32_e32 v169, 0xffff0000, v82
	v_lshlrev_b32_e32 v170, 16, v83
	v_and_b32_e32 v171, 0xffff0000, v83
	v_pk_fma_f32 v[160:161], v[162:163], v[0:1], v[160:161] op_sel_hi:[1,0,1]
	v_pk_fma_f32 v[162:163], v[178:179], v[0:1], v[166:167] op_sel_hi:[1,0,1]
	s_nop 0
	v_pk_fma_f32 v[166:167], v[74:75], v[102:103], v[170:171]
	v_pk_fma_f32 v[168:169], v[72:73], v[100:101], v[168:169]
	ds_read_b128 v[100:103], v203 offset:20736
	ds_read_b128 v[104:107], v203 offset:20800
	s_waitcnt lgkmcnt(1)
	v_mfma_f32_16x16x32_bf16 v[100:103], v[56:59], v[100:103], 0
	v_lshlrev_b32_e32 v174, 16, v2
	v_and_b32_e32 v175, 0xffff0000, v2
	v_lshlrev_b32_e32 v176, 16, v3
	s_waitcnt lgkmcnt(0)
	v_mfma_f32_16x16x32_bf16 v[100:103], v[48:51], v[104:107], v[100:103]
	v_and_b32_e32 v177, 0xffff0000, v3
	v_lshlrev_b32_e32 v170, 16, v144
	v_and_b32_e32 v171, 0xffff0000, v144
	v_lshlrev_b32_e32 v172, 16, v145
	v_and_b32_e32 v173, 0xffff0000, v145
	s_nop 2
	v_pk_fma_f32 v[100:101], v[72:73], v[100:101], v[174:175]
	v_pk_fma_f32 v[102:103], v[74:75], v[102:103], v[176:177]
	v_pk_fma_f32 v[178:179], v[164:165], v[0:1], v[172:173] op_sel_hi:[1,0,1]
	v_mov_b32_dpp v104, v100 row_newbcast:0 row_mask:0xf bank_mask:0xf bound_ctrl:1
	v_mov_b32_dpp v100, v100 row_newbcast:1 row_mask:0xf bank_mask:0xf bound_ctrl:1
	v_max_f32_e32 v100, v100, v100
	v_max_f32_e64 v104, |v104|, |v104|
	v_max_f32_e32 v100, v104, v100
	v_rcp_f32_e32 v100, v100
	v_mov_b32_dpp v104, v101 row_newbcast:0 row_mask:0xf bank_mask:0xf bound_ctrl:1
	v_mov_b32_dpp v101, v101 row_newbcast:1 row_mask:0xf bank_mask:0xf bound_ctrl:1
	v_max_f32_e32 v101, v101, v101
	v_max_f32_e64 v104, |v104|, |v104|
	v_max_f32_e32 v101, v104, v101
	v_rcp_f32_e32 v101, v101
	v_mov_b32_dpp v104, v102 row_newbcast:0 row_mask:0xf bank_mask:0xf bound_ctrl:1
	v_mov_b32_dpp v102, v102 row_newbcast:1 row_mask:0xf bank_mask:0xf bound_ctrl:1
	v_max_f32_e32 v102, v102, v102
	v_max_f32_e64 v104, |v104|, |v104|
	v_max_f32_e32 v102, v104, v102
	v_rcp_f32_e32 v102, v102
	v_mov_b32_dpp v104, v103 row_newbcast:0 row_mask:0xf bank_mask:0xf bound_ctrl:1
	v_mov_b32_dpp v103, v103 row_newbcast:1 row_mask:0xf bank_mask:0xf bound_ctrl:1
	v_max_f32_e32 v103, v103, v103
	v_max_f32_e64 v104, |v104|, |v104|
	v_max_f32_e32 v103, v104, v103
	v_rcp_f32_e32 v103, v103
	v_pk_fma_f32 v[164:165], v[180:181], v[0:1], v[170:171] op_sel_hi:[1,0,1]
	v_pk_mul_f32 v[104:105], v[110:111], v[100:101]
	s_add_i32 s3, s24, -6
	v_pk_mul_f32 v[106:107], v[108:109], v[102:103]
	v_pk_mul_f32 v[108:109], v[114:115], v[100:101]
	v_pk_mul_f32 v[110:111], v[112:113], v[102:103]
	v_pk_mul_f32 v[112:113], v[118:119], v[100:101]
	v_pk_mul_f32 v[114:115], v[116:117], v[102:103]
	v_pk_mul_f32 v[116:117], v[168:169], v[100:101]
	v_pk_mul_f32 v[118:119], v[166:167], v[102:103]
	s_mov_b64 s[20:21], 0
	v_mov_b32_e32 v183, v179
	v_mov_b32_e32 v182, v178
	v_mov_b32_e32 v181, v165
	v_mov_b32_e32 v180, v164

; __device__ __forceinline__ float row16_sum(float v) { v += dppf<0xB1>(v); v += dppf<0x4E>(v); v += dppf<0x141>(v); v += dppf<0x140>(v); return v; }
; __device__ __forceinline__ float frsq(float x) { return __builtin_amdgcn_rsqf(x); }
; __device__ __forceinline__ v2u pack4(const f32x4 v) { v2u r; r.x = pk2(v[0], v[1]); r.y = pk2(v[2], v[3]); return r; }
; __device__ __forceinline__ f32x4 unpack4(const v2u w) { f32x4 r; r[0] = bflo(w.x); r[1] = bfhi(w.x); r[2] = bflo(w.y); r[3] = bfhi(w.y); return r; }
; __device__ __forceinline__ const char* upin(const char* p) { asm volatile("" : "+s"(p)); return p; }
; __device__ __forceinline__ char* upin(char* p) { asm volatile("" : "+s"(p)); return p; }
; template <bool GDN> __device__ __forceinline__ void scan_finish(const Frame& F, int b, int h, int dir, const ScanLane& L, int s, float* PEND, const f32x4 (&Oin)[4], const ScanFin& f) {
;     ...
;         f32x4 O[4]; float ss[4] = {0.f, 0.f, 0.f, 0.f};
; #pragma unroll
;         for (int t = 0; t < 4; ++t)
;             { const f32x4 pv = unpack4(f.pend[t]);
; #pragma unroll
;             for (int i = 0; i < 4; ++i) { O[t][i] = Oin[t][i] + pv[i]; ss[i] += O[t][i] * O[t][i]; } }
; #pragma unroll
;         for (int i = 0; i < 4; ++i) ss[i] = frsq(row16_sum(ss[i]) * (1.f / 64.f) + EPS);
;         char* mp = (char*)F.MIX + ((size_t)row0 * 1024 + (GDN ? 0 : 768) + h * 64) * 2;
; #pragma unroll
;         for (int i = 0; i < 4; ++i) { const f32x4 g = unpack4(f.gz[i]); f32x4 ov;
; #pragma unroll
;             for (int t = 0; t < 4; ++t) ov[t] = O[t][i] * ss[i] * g[t];
;             stu<v2u>(upin(mp + i * 2048), L.mix, pack4(ov)); }
;     ...
;     if (s == 21 || s == 3) asm volatile("s_waitcnt vmcnt(0)" ::: "memory");
;     else if (scan_needfin(s - 1)) { if (GDN) asm volatile("s_waitcnt vmcnt(14)" ::: "memory"); else asm volatile("s_waitcnt vmcnt(15)" ::: "memory"); }
;     else { if (GDN) asm volatile("s_waitcnt vmcnt(8)" ::: "memory"); else asm volatile("s_waitcnt vmcnt(9)" ::: "memory"); }
;     __syncthreads();
;     if (s > 0) {
;         const int sp = s - 1;
;         if (sp == 20 || sp == 2) { asm volatile("s_waitcnt vmcnt(0)" ::: "memory"); scan_fin_load<GDN>(F, b, h, dir, L, sp, PEND, fin); }
;         if (!nofin) scan_finish<GDN>(F, b, h, dir, L, sp, PEND, Oprev, fin);
;     }
.LBB0_351:
	s_waitcnt vmcnt(19)
.LBB0_352:
	s_add_i32 s0, s25, -1
	s_cmp_eq_u32 s25, 0
	s_cselect_b64 s[10:11], -1, 0
	s_and_b64 vcc, exec, s[10:11]
	s_waitcnt lgkmcnt(0)
	s_barrier
	s_cbranch_vccnz .LBB0_357
	s_add_i32 s1, s24, 43
	s_and_b64 s[4:5], s[90:91], exec
	s_cselect_b32 s1, s0, s1
	s_cmp_lt_u32 s25, 5
	s_cselect_b32 s3, 2, 20
	s_cmp_lt_u32 s0, s3
	s_mov_b64 s[12:13], -1
	s_cbranch_scc1 .LBB0_355
	s_waitcnt vmcnt(63)
	v_lshlrev_b32_e32 v173, 16, v14
	v_lshlrev_b32_e32 v172, 16, v12
	v_mov_b32_e32 v174, v104
	v_mov_b32_e32 v175, v108
	s_waitcnt vmcnt(63)
	v_lshlrev_b32_e32 v167, 16, v18
	v_lshlrev_b32_e32 v166, 16, v16
	v_mov_b32_e32 v168, v112
	v_mov_b32_e32 v169, v116
	v_pk_add_f32 v[172:173], v[174:175], v[172:173]
	v_pk_add_f32 v[166:167], v[168:169], v[166:167]
	v_pk_mul_f32 v[174:175], v[172:173], v[172:173]
	v_pk_mul_f32 v[168:169], v[166:167], v[166:167]
	v_add_f32_e32 v171, v175, v174
	v_add_f32_e32 v168, v168, v171
	v_add_f32_e32 v168, v169, v168
	s_lshl_b32 s3, s1, 6
	s_cmp_lt_i32 s1, 4
	v_add_f32_dpp v168, v168, v168 quad_perm:[1,0,3,2] row_mask:0xf bank_mask:0xf bound_ctrl:1
	s_cselect_b32 s4, s63, s33
	s_add_i32 s4, s4, s3
	v_add_f32_dpp v168, v168, v168 quad_perm:[2,3,0,1] row_mask:0xf bank_mask:0xf bound_ctrl:1
	s_ashr_i32 s5, s4, 31
	s_lshl_b64 s[4:5], s[4:5], 11
	v_add_f32_dpp v168, v168, v168 row_half_mirror row_mask:0xf bank_mask:0xf bound_ctrl:1
	s_add_u32 s3, s26, s4
	s_addc_u32 s4, s27, s5
	v_add_f32_dpp v168, v168, v168 row_mirror row_mask:0xf bank_mask:0xf bound_ctrl:1
	v_fmamk_f32 v168, v168, 0x3c800000, v231
	v_rsq_f32_e32 v168, v168
	s_waitcnt vmcnt(63)
	v_lshlrev_b32_e32 v170, 16, v131
	v_and_b32_e32 v171, 0xffff0000, v131
	v_lshlrev_b32_e32 v174, 16, v130
	v_and_b32_e32 v175, 0xffff0000, v130
	v_pk_mul_f32 v[172:173], v[172:173], v[168:169] op_sel_hi:[1,0]
	v_pk_mul_f32 v[166:167], v[166:167], v[168:169] op_sel_hi:[1,0]
	s_add_u32 s6, s3, 0x600
	v_pk_mul_f32 v[172:173], v[172:173], v[174:175]
	v_pk_mul_f32 v[166:167], v[166:167], v[170:171]
	s_addc_u32 s7, s4, 0
	v_cvt_pk_bf16_f32 v168, v172, v173
	v_cvt_pk_bf16_f32 v169, v166, v167
	v_and_b32_e32 v173, 0xffff0000, v14
	v_and_b32_e32 v172, 0xffff0000, v12
	v_mov_b32_e32 v174, v105
	v_mov_b32_e32 v175, v109
	global_store_dwordx2 v189, v[168:169], s[6:7]
	v_and_b32_e32 v167, 0xffff0000, v18
	v_and_b32_e32 v166, 0xffff0000, v16
	v_mov_b32_e32 v168, v113
	v_mov_b32_e32 v169, v117
	v_pk_add_f32 v[172:173], v[174:175], v[172:173]
	v_pk_add_f32 v[166:167], v[168:169], v[166:167]
	v_pk_mul_f32 v[174:175], v[172:173], v[172:173]
	v_pk_mul_f32 v[168:169], v[166:167], v[166:167]
	v_add_f32_e32 v171, v175, v174
	v_add_f32_e32 v168, v168, v171
	v_add_f32_e32 v168, v169, v168
	s_waitcnt vmcnt(63)
	v_lshlrev_b32_e32 v170, 16, v133
	v_and_b32_e32 v171, 0xffff0000, v133
	v_add_f32_dpp v168, v168, v168 quad_perm:[1,0,3,2] row_mask:0xf bank_mask:0xf bound_ctrl:1
	v_lshlrev_b32_e32 v174, 16, v132
	v_and_b32_e32 v175, 0xffff0000, v132
	v_add_f32_dpp v168, v168, v168 quad_perm:[2,3,0,1] row_mask:0xf bank_mask:0xf bound_ctrl:1
	s_add_u32 s6, s3, 0xe00
	s_addc_u32 s7, s4, 0
	v_add_f32_dpp v168, v168, v168 row_half_mirror row_mask:0xf bank_mask:0xf bound_ctrl:1
	s_mov_b64 s[12:13], 0
	s_nop 0
	v_add_f32_dpp v168, v168, v168 row_mirror row_mask:0xf bank_mask:0xf bound_ctrl:1
	v_fmamk_f32 v168, v168, 0x3c800000, v231
	v_rsq_f32_e32 v168, v168
	s_nop 0
	v_pk_mul_f32 v[172:173], v[172:173], v[168:169] op_sel_hi:[1,0]
	v_pk_mul_f32 v[166:167], v[166:167], v[168:169] op_sel_hi:[1,0]
	v_pk_mul_f32 v[172:173], v[172:173], v[174:175]
	v_pk_mul_f32 v[166:167], v[166:167], v[170:171]
	v_cvt_pk_bf16_f32 v168, v172, v173
	v_cvt_pk_bf16_f32 v169, v166, v167
	v_lshlrev_b32_e32 v173, 16, v15
	v_lshlrev_b32_e32 v172, 16, v13
	v_mov_b32_e32 v174, v106
	v_mov_b32_e32 v175, v110
	global_store_dwordx2 v189, v[168:169], s[6:7]
	v_lshlrev_b32_e32 v167, 16, v19
	v_lshlrev_b32_e32 v166, 16, v17
	v_mov_b32_e32 v168, v114
	v_mov_b32_e32 v169, v118
	v_pk_add_f32 v[172:173], v[174:175], v[172:173]
	v_pk_add_f32 v[166:167], v[168:169], v[166:167]
	v_pk_mul_f32 v[174:175], v[172:173], v[172:173]
	v_pk_mul_f32 v[168:169], v[166:167], v[166:167]
	v_add_f32_e32 v171, v175, v174
	v_add_f32_e32 v168, v168, v171
	v_add_f32_e32 v168, v169, v168
	s_waitcnt vmcnt(63)
	v_lshlrev_b32_e32 v170, 16, v135
	v_and_b32_e32 v171, 0xffff0000, v135
	v_add_f32_dpp v168, v168, v168 quad_perm:[1,0,3,2] row_mask:0xf bank_mask:0xf bound_ctrl:1
	v_lshlrev_b32_e32 v174, 16, v134
	v_and_b32_e32 v175, 0xffff0000, v134
	v_add_f32_dpp v168, v168, v168 quad_perm:[2,3,0,1] row_mask:0xf bank_mask:0xf bound_ctrl:1
	s_add_u32 s6, s3, 0x1600
	s_addc_u32 s7, s4, 0
	v_add_f32_dpp v168, v168, v168 row_half_mirror row_mask:0xf bank_mask:0xf bound_ctrl:1
	s_nop 1
	v_add_f32_dpp v168, v168, v168 row_mirror row_mask:0xf bank_mask:0xf bound_ctrl:1
	v_fmamk_f32 v168, v168, 0x3c800000, v231
	v_rsq_f32_e32 v168, v168
	s_nop 0
	v_pk_mul_f32 v[172:173], v[172:173], v[168:169] op_sel_hi:[1,0]
	v_pk_mul_f32 v[166:167], v[166:167], v[168:169] op_sel_hi:[1,0]
	v_pk_mul_f32 v[172:173], v[172:173], v[174:175]
	v_pk_mul_f32 v[166:167], v[166:167], v[170:171]
	v_cvt_pk_bf16_f32 v168, v172, v173
	v_cvt_pk_bf16_f32 v169, v166, v167
	v_and_b32_e32 v173, 0xffff0000, v15
	v_and_b32_e32 v172, 0xffff0000, v13
	v_mov_b32_e32 v174, v107
	v_mov_b32_e32 v175, v111
	global_store_dwordx2 v189, v[168:169], s[6:7]
	v_and_b32_e32 v167, 0xffff0000, v19
	v_and_b32_e32 v166, 0xffff0000, v17
	v_mov_b32_e32 v168, v115
	v_mov_b32_e32 v169, v119
	v_pk_add_f32 v[172:173], v[174:175], v[172:173]
	v_pk_add_f32 v[166:167], v[168:169], v[166:167]
	v_pk_mul_f32 v[174:175], v[172:173], v[172:173]
	v_pk_mul_f32 v[168:169], v[166:167], v[166:167]
	v_add_f32_e32 v171, v175, v174
	v_add_f32_e32 v168, v168, v171
	v_add_f32_e32 v168, v169, v168
	s_waitcnt vmcnt(63)
	v_lshlrev_b32_e32 v170, 16, v137
	v_and_b32_e32 v171, 0xffff0000, v137
	v_add_f32_dpp v168, v168, v168 quad_perm:[1,0,3,2] row_mask:0xf bank_mask:0xf bound_ctrl:1
	v_lshlrev_b32_e32 v174, 16, v136
	v_and_b32_e32 v175, 0xffff0000, v136
	v_add_f32_dpp v168, v168, v168 quad_perm:[2,3,0,1] row_mask:0xf bank_mask:0xf bound_ctrl:1
	s_add_u32 s6, s3, 0x1e00
	s_addc_u32 s7, s4, 0
	v_add_f32_dpp v168, v168, v168 row_half_mirror row_mask:0xf bank_mask:0xf bound_ctrl:1
	s_nop 1
	v_add_f32_dpp v168, v168, v168 row_mirror row_mask:0xf bank_mask:0xf bound_ctrl:1
	v_fmamk_f32 v168, v168, 0x3c800000, v231
	v_rsq_f32_e32 v168, v168
	s_nop 0
	v_pk_mul_f32 v[172:173], v[172:173], v[168:169] op_sel_hi:[1,0]
	v_pk_mul_f32 v[166:167], v[166:167], v[168:169] op_sel_hi:[1,0]
	v_pk_mul_f32 v[172:173], v[172:173], v[174:175]
	v_pk_mul_f32 v[166:167], v[166:167], v[170:171]
	v_cvt_pk_bf16_f32 v168, v172, v173
	v_cvt_pk_bf16_f32 v169, v166, v167
	global_store_dwordx2 v189, v[168:169], s[6:7]

; __device__ __forceinline__ bool scan_needfin(int s) { return s >= 0 && s < 35 && !scan_first(s + 1) && s + 1 != 20 && s + 1 != 2; }
;     ...
;     if (s == 21 || s == 3) asm volatile("s_waitcnt vmcnt(0)" ::: "memory");
;     else if (scan_needfin(s - 1)) { if (GDN) asm volatile("s_waitcnt vmcnt(14)" ::: "memory"); else asm volatile("s_waitcnt vmcnt(15)" ::: "memory"); }
;     else { if (GDN) asm volatile("s_waitcnt vmcnt(8)" ::: "memory"); else asm volatile("s_waitcnt vmcnt(9)" ::: "memory"); }
;     __syncthreads();
.LBB0_372:
	s_andn2_b64 vcc, exec, s[12:13]
	s_cbranch_vccnz .LBB0_374
	s_waitcnt vmcnt(19)

; __device__ __forceinline__ const char* upin(const char* p) { asm volatile("" : "+s"(p)); return p; }
; __device__ __forceinline__ char* upin(char* p) { asm volatile("" : "+s"(p)); return p; }
; template <bool GDN> __device__ __forceinline__ void scan_fin_load(const Frame& F, int b, int h, int dir, const ScanLane& L, int s, const float* PEND, ScanFin& f) {
;     const int cidx = dir ? (s < 4 ? 3 - s : 39 - s) : s; const int row0 = chunk_row0(b, cidx);
;     const char* pp = upin((const char*)PEND + (size_t)((b * 4 + h) * 36 + cidx) * 16384);
;     const char* gp = (const char*)F.Z + ((size_t)row0 * ZW + (GDN ? ZC_GZ : ZC_LO) + h * 64) * 2;
; #pragma unroll
;     for (int pr = 0; pr < 2; ++pr) { const v4u qp = ldu<v4u>(pp + pr * 1024, L.pend); f.pend[2 * pr] = (v2u){qp.x, qp.y}; f.pend[2 * pr + 1] = (v2u){qp.z, qp.w}; }
; #pragma unroll
;     for (int t = 0; t < 4; ++t) f.gz[t] = ldu<v2u>(upin(gp + (size_t)t * ZW * 2), L.gz);
; }
.LBB0_384:
	s_cmp_gt_u32 s25, 3
	s_cselect_b32 s1, 39, 3
	s_add_i32 s1, s1, s24
	s_add_i32 s1, s1, 3
	s_and_b64 s[6:7], s[90:91], exec
	s_cselect_b32 s1, s25, s1
	s_lshl_b32 s3, s1, 6
	s_or_b32 s5, s3, s63
	s_add_i32 s3, s3, s33
	s_cmp_lt_u32 s1, 4
	s_cselect_b32 s3, s5, s3
	s_add_i32 s92, s1, s31
	s_lshl_b64 s[6:7], s[92:93], 14
	v_readlane_b32 s12, v253, 25
	s_add_u32 s6, s22, s6
	s_mul_hi_u32 s9, s3, 0xd00
	s_mul_i32 s8, s3, 0xd00
	v_readlane_b32 s13, v253, 26
	s_addc_u32 s7, s23, s7
	s_or_b64 s[8:9], s[8:9], s[12:13]
	s_waitcnt vmcnt(0)
	s_lshl_b64 s[8:9], s[8:9], 1
	global_load_dwordx4 v[4:7], v38, s[6:7]
	global_load_dwordx4 v[8:11], v38, s[6:7] offset:1024
	s_add_u32 s6, s16, s8
	s_addc_u32 s7, s17, s9
	s_mov_b64 s[8:9], s[6:7]
	global_load_dwordx2 v[122:123], v37, s[8:9]
	s_add_u32 s8, s6, 0x1a00
	s_addc_u32 s9, s7, 0
	global_load_dwordx2 v[124:125], v37, s[8:9]
	s_add_u32 s8, s6, 0x3400
	s_addc_u32 s9, s7, 0
	s_add_u32 s6, s6, 0x4e00
	s_addc_u32 s7, s7, 0
	global_load_dwordx2 v[126:127], v37, s[8:9]
	global_load_dwordx2 v[128:129], v37, s[6:7]
	s_waitcnt vmcnt(0)
; __device__ __forceinline__ float row16_sum(float v) { v += dppf<0xB1>(v); v += dppf<0x4E>(v); v += dppf<0x141>(v); v += dppf<0x140>(v); return v; }
; __device__ __forceinline__ float frsq(float x) { return __builtin_amdgcn_rsqf(x); }
; __device__ __forceinline__ v2u pack4(const f32x4 v) { v2u r; r.x = pk2(v[0], v[1]); r.y = pk2(v[2], v[3]); return r; }
; __device__ __forceinline__ f32x4 unpack4(const v2u w) { f32x4 r; r[0] = bflo(w.x); r[1] = bfhi(w.x); r[2] = bflo(w.y); r[3] = bfhi(w.y); return r; }
; __device__ __forceinline__ const char* upin(const char* p) { asm volatile("" : "+s"(p)); return p; }
; __device__ __forceinline__ char* upin(char* p) { asm volatile("" : "+s"(p)); return p; }
; template <bool GDN> __device__ __forceinline__ void scan_finish(const Frame& F, int b, int h, int dir, const ScanLane& L, int s, float* PEND, const f32x4 (&Oin)[4], const ScanFin& f) {
;     ...
;         f32x4 O[4]; float ss[4] = {0.f, 0.f, 0.f, 0.f};
; #pragma unroll
;         for (int t = 0; t < 4; ++t)
;             { const f32x4 pv = unpack4(f.pend[t]);
; #pragma unroll
;             for (int i = 0; i < 4; ++i) { O[t][i] = Oin[t][i] + pv[i]; ss[i] += O[t][i] * O[t][i]; } }
; #pragma unroll
;         for (int i = 0; i < 4; ++i) ss[i] = frsq(row16_sum(ss[i]) * (1.f / 64.f) + EPS);
;         char* mp = (char*)F.MIX + ((size_t)row0 * 1024 + (GDN ? 0 : 768) + h * 64) * 2;
; #pragma unroll
;         for (int i = 0; i < 4; ++i) { const f32x4 g = unpack4(f.gz[i]); f32x4 ov;
; #pragma unroll
;             for (int t = 0; t < 4; ++t) ov[t] = O[t][i] * ss[i] * g[t];
;             stu<v2u>(upin(mp + i * 2048), L.mix, pack4(ov)); }
.LBB0_385:
	s_cmp_gt_u32 s25, 3
	s_cselect_b32 s5, 39, 3
	s_add_i32 s5, s5, s24
	s_add_i32 s1, s5, 3
	s_and_b64 s[6:7], s[90:91], exec
	s_cselect_b32 s1, s25, s1
	s_cmp_lt_u32 s4, 5
	s_cselect_b32 s3, 2, 20
	s_cmp_lt_u32 s25, s3
	s_mov_b64 s[12:13], -1
	s_cbranch_scc1 .LBB0_387
	s_waitcnt vmcnt(63)
	v_lshlrev_b32_e32 v65, 16, v6
	v_lshlrev_b32_e32 v64, 16, v4
	v_mov_b32_e32 v66, v104
	v_mov_b32_e32 v67, v108
	s_waitcnt vmcnt(63)
	v_lshlrev_b32_e32 v41, 16, v10
	v_lshlrev_b32_e32 v40, 16, v8
	v_mov_b32_e32 v42, v112
	v_mov_b32_e32 v43, v116
	v_pk_add_f32 v[64:65], v[66:67], v[64:65]
	v_pk_add_f32 v[40:41], v[42:43], v[40:41]
	v_pk_mul_f32 v[66:67], v[64:65], v[64:65]
	v_pk_mul_f32 v[42:43], v[40:41], v[40:41]
	v_add_f32_e32 v63, v67, v66
	v_add_f32_e32 v42, v42, v63
	v_add_f32_e32 v42, v43, v42
	s_lshl_b32 s3, s1, 6
	s_cmp_lt_i32 s1, 4
	v_add_f32_dpp v42, v42, v42 quad_perm:[1,0,3,2] row_mask:0xf bank_mask:0xf bound_ctrl:1
	s_cselect_b32 s6, s63, s33
	s_add_i32 s6, s6, s3
	v_add_f32_dpp v42, v42, v42 quad_perm:[2,3,0,1] row_mask:0xf bank_mask:0xf bound_ctrl:1
	s_ashr_i32 s7, s6, 31
	s_lshl_b64 s[6:7], s[6:7], 11
	v_add_f32_dpp v42, v42, v42 row_half_mirror row_mask:0xf bank_mask:0xf bound_ctrl:1
	s_add_u32 s3, s26, s6
	s_addc_u32 s6, s27, s7
	v_add_f32_dpp v42, v42, v42 row_mirror row_mask:0xf bank_mask:0xf bound_ctrl:1
	v_fmamk_f32 v42, v42, 0x3c800000, v231
	v_rsq_f32_e32 v42, v42
	s_waitcnt vmcnt(63)
	v_lshlrev_b32_e32 v62, 16, v123
	v_and_b32_e32 v63, 0xffff0000, v123
	v_lshlrev_b32_e32 v66, 16, v122
	v_and_b32_e32 v67, 0xffff0000, v122
	v_pk_mul_f32 v[64:65], v[64:65], v[42:43] op_sel_hi:[1,0]
	v_pk_mul_f32 v[40:41], v[40:41], v[42:43] op_sel_hi:[1,0]
	s_add_u32 s8, s3, 0x600
	v_pk_mul_f32 v[64:65], v[64:65], v[66:67]
	v_pk_mul_f32 v[40:41], v[40:41], v[62:63]
	s_addc_u32 s9, s6, 0
	v_cvt_pk_bf16_f32 v42, v64, v65
	v_cvt_pk_bf16_f32 v43, v40, v41
	v_and_b32_e32 v65, 0xffff0000, v6
	v_and_b32_e32 v64, 0xffff0000, v4
	v_mov_b32_e32 v66, v105
	v_mov_b32_e32 v67, v109
	global_store_dwordx2 v39, v[42:43], s[8:9]
	v_and_b32_e32 v41, 0xffff0000, v10
	v_and_b32_e32 v40, 0xffff0000, v8
	v_mov_b32_e32 v42, v113
	v_mov_b32_e32 v43, v117
	v_pk_add_f32 v[64:65], v[66:67], v[64:65]
	v_pk_add_f32 v[40:41], v[42:43], v[40:41]
	v_pk_mul_f32 v[66:67], v[64:65], v[64:65]
	v_pk_mul_f32 v[42:43], v[40:41], v[40:41]
	v_add_f32_e32 v63, v67, v66
	v_add_f32_e32 v42, v42, v63
	v_add_f32_e32 v42, v43, v42
	s_waitcnt vmcnt(63)
	v_lshlrev_b32_e32 v62, 16, v125
	v_and_b32_e32 v63, 0xffff0000, v125
	v_add_f32_dpp v42, v42, v42 quad_perm:[1,0,3,2] row_mask:0xf bank_mask:0xf bound_ctrl:1
	v_lshlrev_b32_e32 v66, 16, v124
	v_and_b32_e32 v67, 0xffff0000, v124
	v_add_f32_dpp v42, v42, v42 quad_perm:[2,3,0,1] row_mask:0xf bank_mask:0xf bound_ctrl:1
	s_add_u32 s8, s3, 0xe00
	s_addc_u32 s9, s6, 0
	v_add_f32_dpp v42, v42, v42 row_half_mirror row_mask:0xf bank_mask:0xf bound_ctrl:1
	s_mov_b64 s[12:13], 0
	s_nop 0
	v_add_f32_dpp v42, v42, v42 row_mirror row_mask:0xf bank_mask:0xf bound_ctrl:1
	v_fmamk_f32 v42, v42, 0x3c800000, v231
	v_rsq_f32_e32 v42, v42
	s_nop 0
	v_pk_mul_f32 v[64:65], v[64:65], v[42:43] op_sel_hi:[1,0]
	v_pk_mul_f32 v[40:41], v[40:41], v[42:43] op_sel_hi:[1,0]
	v_pk_mul_f32 v[64:65], v[64:65], v[66:67]
	v_pk_mul_f32 v[40:41], v[40:41], v[62:63]
	v_cvt_pk_bf16_f32 v42, v64, v65
	v_cvt_pk_bf16_f32 v43, v40, v41
	v_lshlrev_b32_e32 v65, 16, v7
	v_lshlrev_b32_e32 v64, 16, v5
	v_mov_b32_e32 v66, v106
	v_mov_b32_e32 v67, v110
	global_store_dwordx2 v39, v[42:43], s[8:9]
	v_lshlrev_b32_e32 v41, 16, v11
	v_lshlrev_b32_e32 v40, 16, v9
	v_mov_b32_e32 v42, v114
	v_mov_b32_e32 v43, v118
	v_pk_add_f32 v[64:65], v[66:67], v[64:65]
	v_pk_add_f32 v[40:41], v[42:43], v[40:41]
	v_pk_mul_f32 v[66:67], v[64:65], v[64:65]
	v_pk_mul_f32 v[42:43], v[40:41], v[40:41]
	v_add_f32_e32 v63, v67, v66
	v_add_f32_e32 v42, v42, v63
	v_add_f32_e32 v42, v43, v42
	s_waitcnt vmcnt(63)
	v_lshlrev_b32_e32 v62, 16, v127
	v_and_b32_e32 v63, 0xffff0000, v127
	v_add_f32_dpp v42, v42, v42 quad_perm:[1,0,3,2] row_mask:0xf bank_mask:0xf bound_ctrl:1
	v_lshlrev_b32_e32 v66, 16, v126
	v_and_b32_e32 v67, 0xffff0000, v126
	v_add_f32_dpp v42, v42, v42 quad_perm:[2,3,0,1] row_mask:0xf bank_mask:0xf bound_ctrl:1
	s_add_u32 s8, s3, 0x1600
	s_addc_u32 s9, s6, 0
	v_add_f32_dpp v42, v42, v42 row_half_mirror row_mask:0xf bank_mask:0xf bound_ctrl:1
	s_nop 1
	v_add_f32_dpp v42, v42, v42 row_mirror row_mask:0xf bank_mask:0xf bound_ctrl:1
	v_fmamk_f32 v42, v42, 0x3c800000, v231
	v_rsq_f32_e32 v42, v42
	s_nop 0
	v_pk_mul_f32 v[64:65], v[64:65], v[42:43] op_sel_hi:[1,0]
	v_pk_mul_f32 v[40:41], v[40:41], v[42:43] op_sel_hi:[1,0]
	v_pk_mul_f32 v[64:65], v[64:65], v[66:67]
	v_pk_mul_f32 v[40:41], v[40:41], v[62:63]
	v_cvt_pk_bf16_f32 v42, v64, v65
	v_cvt_pk_bf16_f32 v43, v40, v41
	v_and_b32_e32 v65, 0xffff0000, v7
	v_and_b32_e32 v64, 0xffff0000, v5
	v_mov_b32_e32 v66, v107
	v_mov_b32_e32 v67, v111
	global_store_dwordx2 v39, v[42:43], s[8:9]
	v_and_b32_e32 v41, 0xffff0000, v11
	v_and_b32_e32 v40, 0xffff0000, v9
	v_mov_b32_e32 v42, v115
	v_mov_b32_e32 v43, v119
	v_pk_add_f32 v[64:65], v[66:67], v[64:65]
	v_pk_add_f32 v[40:41], v[42:43], v[40:41]
	v_pk_mul_f32 v[66:67], v[64:65], v[64:65]
	v_pk_mul_f32 v[42:43], v[40:41], v[40:41]
	v_add_f32_e32 v63, v67, v66
	v_add_f32_e32 v42, v42, v63
	v_add_f32_e32 v42, v43, v42
	s_waitcnt vmcnt(63)
	v_lshlrev_b32_e32 v62, 16, v129
	v_and_b32_e32 v63, 0xffff0000, v129
	v_add_f32_dpp v42, v42, v42 quad_perm:[1,0,3,2] row_mask:0xf bank_mask:0xf bound_ctrl:1
	v_lshlrev_b32_e32 v66, 16, v128
	v_and_b32_e32 v67, 0xffff0000, v128
	v_add_f32_dpp v42, v42, v42 quad_perm:[2,3,0,1] row_mask:0xf bank_mask:0xf bound_ctrl:1
	s_add_u32 s8, s3, 0x1e00
	s_addc_u32 s9, s6, 0
	v_add_f32_dpp v42, v42, v42 row_half_mirror row_mask:0xf bank_mask:0xf bound_ctrl:1
	s_nop 1
	v_add_f32_dpp v42, v42, v42 row_mirror row_mask:0xf bank_mask:0xf bound_ctrl:1
	v_fmamk_f32 v42, v42, 0x3c800000, v231
	v_rsq_f32_e32 v42, v42
	s_nop 0
	v_pk_mul_f32 v[64:65], v[64:65], v[42:43] op_sel_hi:[1,0]
	v_pk_mul_f32 v[40:41], v[40:41], v[42:43] op_sel_hi:[1,0]
	v_pk_mul_f32 v[64:65], v[64:65], v[66:67]
	v_pk_mul_f32 v[40:41], v[40:41], v[62:63]
	v_cvt_pk_bf16_f32 v42, v64, v65
	v_cvt_pk_bf16_f32 v43, v40, v41
	global_store_dwordx2 v39, v[42:43], s[8:9]

; template <bool GDN, int NT> __device__ __forceinline__ void scan_load(const Frame& F, int b, int h, int dir, const ScanLane& L, int s, ScanOps<NT>& o) {
;     ...
;         const char* zq = upin((const char*)F.Z + ((size_t)chunk_row0(b, cidx) * ZW + ZC_LQ + h * 64) * 2);
; #pragma unroll
;         for (int ks = 0; ks < 2; ++ks) { o.Qf[ks] = ldu<bf16x8>(zq + ks * 64, L.zq); o.Mf[ks] = o.Qf[ks]; }
;         const char* base = (const char*)F.PM + (size_t)ud * 20480;
;         const char* bO = upin(base); const char* bB = upin(base + 10240);
; #pragma unroll
;         for (int pr = 0; pr < 2; ++pr) { const v4u qb = ldun<v4u>(bB + pr * 1024, L.o16p), qo = ldun<v4u>(bO + pr * 1024, L.o16p);
;             o.bv[2 * pr] = (v2u){qb.x, qb.y}; o.bv[2 * pr + 1] = (v2u){qb.z, qb.w}; o.ov[2 * pr] = (v2u){qo.x, qo.y}; o.ov[2 * pr + 1] = (v2u){qo.z, qo.w}; }
;         o.bv[4] = ldun<v2u>(bB + 2048, L.o8); o.ov[4] = ldun<v2u>(bO + 2048, L.o8);
;         o.wi = ldu<f32x4>(upin((const char*)F.WI + (size_t)ud * 256), L.wi);
;     ...
;     const float gl = ((const LAS float*)(St + 4 * 80 * 72))[(dir ? (s < 4 ? 3 - s : 39 - s) : s) * 2 + dir];
;     f32x4 O[NT];
; #pragma unroll
;     for (int t = 0; t < NT; ++t) {
;         const LAS bf16_t* sp2 = Sb + (16 * t + lr) * 72 + 8 * lq;
;         const bf16x8 s0 = *(const LAS bf16x8*)sp2, s1 = *(const LAS bf16x8*)(sp2 + 32);
;         const f32x4 bv = unpack4(use.bv[t]), ov = unpack4(use.ov[t]);
;         if (GDN) {
;             f32x4 o = ov, sn = S[t] * gl + bv;
;             o = __builtin_amdgcn_mfma_f32_16x16x32_bf16(use.Qf[0], s0, o, 0, 0, 0); o = __builtin_amdgcn_mfma_f32_16x16x32_bf16(use.Qf[1], s1, o, 0, 0, 0);
;             sn = __builtin_amdgcn_mfma_f32_16x16x32_bf16(use.Mf[0], s0, sn, 0, 0, 0); sn = __builtin_amdgcn_mfma_f32_16x16x32_bf16(use.Mf[1], s1, sn, 0, 0, 0);
;             S[t] = sn; O[t] = o;
;         } else {
;             f32x4 o = {0.f, 0.f, 0.f, 0.f};
;             o = __builtin_amdgcn_mfma_f32_16x16x32_bf16(use.Qf[0], s0, o, 0, 0, 0); o = __builtin_amdgcn_mfma_f32_16x16x32_bf16(use.Qf[1], s1, o, 0, 0, 0);
;             S[t] = S[t] * gl + bv; O[t] = o * use.wi + ov; }
;     }
;     if (!GDN) {
; #pragma unroll
;         for (int i = 0; i < 4; ++i) { const float den = row16_bcast<0>(O[NT - 1][i]), fl = row16_bcast<1>(O[NT - 1][i]); const float dv = frcp(fmaxf(fabsf(den), fl));
; #pragma unroll
.LBB0_396:
	s_min_u32 s1, s4, 33
	s_add_i32 s8, s1, 2
	s_and_b64 s[6:7], exec, s[10:11]
	s_cselect_b32 s1, 3, 39
	s_sub_i32 s9, s1, s8
	s_and_b64 s[6:7], s[90:91], exec
	s_cselect_b32 s6, s8, s9
	s_lshl_b32 s7, s6, 6
	s_cmp_lt_i32 s6, 4
	s_cselect_b32 s8, s63, s33
	s_add_i32 s7, s8, s7
	s_mul_i32 s8, s7, 0xd00
	s_add_i32 s6, s6, s31
	s_ashr_i32 s9, s8, 31
	s_lshl_b32 s6, s6, 1
	s_or_b64 s[8:9], s[36:37], s[8:9]
	s_add_i32 s6, s6, s68
	s_lshl_b64 s[8:9], s[8:9], 1
	s_add_u32 s8, s16, s8
	s_addc_u32 s9, s17, s9
	global_load_dwordx4 v[40:43], v36, s[8:9]
	s_nop 0
	global_load_dwordx4 v[36:39], v36, s[8:9] offset:64
	s_ashr_i32 s7, s6, 31
	s_mul_i32 s8, s6, 0x5000
	v_readlane_b32 s10, v254, 46
	s_mul_hi_i32 s9, s6, 0x5000
	s_add_u32 s8, s10, s8
	v_readlane_b32 s10, v254, 47
	s_addc_u32 s9, s10, s9
	s_mov_b64 s[10:11], s[8:9]
	s_add_u32 s8, s8, 0x2800
	s_addc_u32 s9, s9, 0
	global_load_dwordx4 v[92:95], v60, s[8:9] nt
	global_load_dwordx4 v[64:67], v60, s[8:9] offset:1024 nt
	global_load_dwordx4 v[96:99], v60, s[10:11] nt
	global_load_dwordx4 v[68:71], v60, s[10:11] offset:1024 nt
	global_load_dwordx2 v[146:147], v61, s[8:9] offset:2048 nt
	global_load_dwordx2 v[142:143], v61, s[10:11] offset:2048 nt
	s_lshl_b64 s[6:7], s[6:7], 8
	v_readlane_b32 s8, v254, 52
	v_readlane_b32 s9, v254, 53
	s_add_u32 s6, s8, s6
	s_addc_u32 s7, s9, s7
	global_load_dwordx4 v[60:63], v0, s[6:7]
	s_add_i32 s5, s5, 2
	s_and_b64 s[6:7], s[90:91], exec
	s_cselect_b32 s5, s4, s5
	s_lshl_b32 s6, s5, 3
	s_add_i32 s6, s34, s6
	v_mov_b32_e32 v0, s6
	v_add_u32_e32 v203, v201, v121
	ds_read_b128 v[104:107], v203 offset:11520
	ds_read_b32 v0, v0 offset:46080
	ds_read_b128 v[108:111], v203 offset:11584
	s_waitcnt lgkmcnt(2)
	v_mfma_f32_16x16x32_bf16 v[104:107], v[24:27], v[104:107], 0
	ds_read_b128 v[112:115], v203 offset:13824
	s_waitcnt vmcnt(63)
	v_lshlrev_b32_e32 v116, 16, v44
	v_and_b32_e32 v117, 0xffff0000, v44
	v_lshlrev_b32_e32 v118, 16, v45
	v_and_b32_e32 v119, 0xffff0000, v45
	s_waitcnt lgkmcnt(1)
	v_mfma_f32_16x16x32_bf16 v[104:107], v[20:23], v[108:111], v[104:107]
	ds_read_b128 v[108:111], v203 offset:13888
	v_pk_fma_f32 v[180:181], v[150:151], v[0:1], v[118:119] op_sel_hi:[1,0,1]
	v_pk_fma_f32 v[182:183], v[148:149], v[0:1], v[116:117] op_sel_hi:[1,0,1]
	s_waitcnt lgkmcnt(1)
	v_mfma_f32_16x16x32_bf16 v[112:115], v[24:27], v[112:115], 0
	ds_read_b128 v[116:119], v203 offset:16128
	ds_read_b128 v[166:169], v203 offset:18432
	v_lshlrev_b32_e32 v148, 16, v46
	s_waitcnt lgkmcnt(2)
	v_mfma_f32_16x16x32_bf16 v[108:111], v[20:23], v[108:111], v[112:115]
	v_and_b32_e32 v149, 0xffff0000, v46
	v_lshlrev_b32_e32 v150, 16, v47
	v_and_b32_e32 v151, 0xffff0000, v47
	ds_read_b128 v[112:115], v203 offset:16192
	s_waitcnt lgkmcnt(2)
	v_mfma_f32_16x16x32_bf16 v[116:119], v[24:27], v[116:119], 0
	v_fma_f32 v150, v152, v0, v150
	v_fma_f32 v151, v153, v0, v151
	v_pk_fma_f32 v[154:155], v[154:155], v[0:1], v[148:149] op_sel_hi:[1,0,1]
	s_waitcnt vmcnt(63)
	v_lshlrev_b32_e32 v152, 16, v28
	v_and_b32_e32 v153, 0xffff0000, v28
	v_lshlrev_b32_e32 v148, 16, v29
	v_and_b32_e32 v149, 0xffff0000, v29
	s_waitcnt lgkmcnt(0)
	v_mfma_f32_16x16x32_bf16 v[112:115], v[20:23], v[112:115], v[116:119]
	v_fma_f32 v148, v156, v0, v148
	v_fma_f32 v149, v157, v0, v149
	v_pk_fma_f32 v[152:153], v[158:159], v[0:1], v[152:153] op_sel_hi:[1,0,1]
	v_lshlrev_b32_e32 v170, 16, v30
	ds_read_b128 v[116:119], v203 offset:18496
	v_mfma_f32_16x16x32_bf16 v[156:159], v[24:27], v[166:169], 0
	ds_read_b128 v[166:169], v203 offset:20736
	v_and_b32_e32 v171, 0xffff0000, v30
	v_lshlrev_b32_e32 v172, 16, v31
	s_waitcnt lgkmcnt(1)
	v_mfma_f32_16x16x32_bf16 v[116:119], v[20:23], v[116:119], v[156:159]
	v_and_b32_e32 v173, 0xffff0000, v31
	v_pk_fma_f32 v[184:185], v[160:161], v[0:1], v[172:173] op_sel_hi:[1,0,1]
	v_pk_fma_f32 v[160:161], v[162:163], v[0:1], v[170:171] op_sel_hi:[1,0,1]
	ds_read_b128 v[156:159], v203 offset:20800
	s_waitcnt lgkmcnt(1)
	v_mfma_f32_16x16x32_bf16 v[166:169], v[24:27], v[166:169], 0
	s_waitcnt vmcnt(63)
	v_lshlrev_b32_e32 v162, 16, v140
	v_and_b32_e32 v163, 0xffff0000, v140
	s_waitcnt vmcnt(63)
	v_lshlrev_b32_e32 v172, 16, v138
	s_waitcnt lgkmcnt(0)
	v_mfma_f32_16x16x32_bf16 v[166:169], v[20:23], v[156:159], v[166:169]
	v_and_b32_e32 v173, 0xffff0000, v138
	v_lshlrev_b32_e32 v174, 16, v139
	v_and_b32_e32 v175, 0xffff0000, v139
	v_lshlrev_b32_e32 v170, 16, v141
	v_and_b32_e32 v171, 0xffff0000, v141
	v_pk_fma_f32 v[158:159], v[164:165], v[0:1], v[162:163] op_sel_hi:[1,0,1]
	s_waitcnt vmcnt(63)
	s_nop 0
	v_pk_fma_f32 v[168:169], v[102:103], v[168:169], v[174:175]
	v_pk_fma_f32 v[162:163], v[100:101], v[166:167], v[172:173]
	v_pk_fma_f32 v[156:157], v[178:179], v[0:1], v[170:171] op_sel_hi:[1,0,1]
	v_mov_b32_dpp v165, v168 row_newbcast:0 row_mask:0xf bank_mask:0xf bound_ctrl:1
	v_mov_b32_dpp v187, v162 row_newbcast:0 row_mask:0xf bank_mask:0xf bound_ctrl:1
	v_mov_b32_dpp v193, v162 row_newbcast:1 row_mask:0xf bank_mask:0xf bound_ctrl:1
	v_mov_b32_dpp v179, v163 row_newbcast:0 row_mask:0xf bank_mask:0xf bound_ctrl:1
	v_mov_b32_dpp v186, v163 row_newbcast:1 row_mask:0xf bank_mask:0xf bound_ctrl:1
	v_mov_b32_dpp v178, v168 row_newbcast:1 row_mask:0xf bank_mask:0xf bound_ctrl:1
	v_mov_b32_dpp v163, v169 row_newbcast:0 row_mask:0xf bank_mask:0xf bound_ctrl:1
	v_mov_b32_dpp v164, v169 row_newbcast:1 row_mask:0xf bank_mask:0xf bound_ctrl:1
	v_mov_b32_e32 v0, v120
	v_mov_b32_e32 v191, v197
	v_mov_b32_e32 v188, v194
	v_mov_b32_e32 v190, v196
	v_mov_b32_e32 v192, v199
	v_mov_b32_e32 v166, v198
	v_mov_b32_e32 v162, v200
	v_mov_b32_e32 v189, v195
	s_cmp_gt_u32 s25, 33
	s_cbranch_scc1 .LBB0_398
	v_cvt_pk_bf16_f32 v166, v182, v183
	v_cvt_pk_bf16_f32 v167, v180, v181
	ds_write_b64 v202, v[166:167]
	v_cvt_pk_bf16_f32 v166, v154, v155
	v_cvt_pk_bf16_f32 v167, v150, v151
	ds_write_b64 v202, v[166:167] offset:2304
	v_cvt_pk_bf16_f32 v166, v152, v153
	v_cvt_pk_bf16_f32 v167, v148, v149
	ds_write_b64 v202, v[166:167] offset:4608
	v_cvt_pk_bf16_f32 v166, v160, v161
	v_cvt_pk_bf16_f32 v167, v184, v185
	ds_write_b64 v202, v[166:167] offset:6912
	v_cvt_pk_bf16_f32 v166, v158, v159
	v_cvt_pk_bf16_f32 v167, v156, v157
	ds_write_b64 v202, v[166:167] offset:9216

; __device__ __forceinline__ bool scan_needfin(int s) { return s >= 0 && s < 35 && !scan_first(s + 1) && s + 1 != 20 && s + 1 != 2; }
;     ...
;     if (s == 21 || s == 3) asm volatile("s_waitcnt vmcnt(0)" ::: "memory");
;     else if (scan_needfin(s - 1)) { if (GDN) asm volatile("s_waitcnt vmcnt(14)" ::: "memory"); else asm volatile("s_waitcnt vmcnt(15)" ::: "memory"); }
;     else { if (GDN) asm volatile("s_waitcnt vmcnt(8)" ::: "memory"); else asm volatile("s_waitcnt vmcnt(9)" ::: "memory"); }
;     __syncthreads();
.LBB0_400:
	s_andn2_b64 vcc, exec, s[10:11]
	s_cbranch_vccnz .LBB0_402
	s_waitcnt vmcnt(19)

; __device__ __forceinline__ const char* upin(const char* p) { asm volatile("" : "+s"(p)); return p; }
; __device__ __forceinline__ char* upin(char* p) { asm volatile("" : "+s"(p)); return p; }
; template <bool GDN> __device__ __forceinline__ void scan_fin_load(const Frame& F, int b, int h, int dir, const ScanLane& L, int s, const float* PEND, ScanFin& f) {
;     const int cidx = dir ? (s < 4 ? 3 - s : 39 - s) : s; const int row0 = chunk_row0(b, cidx);
;     const char* pp = upin((const char*)PEND + (size_t)((b * 4 + h) * 36 + cidx) * 16384);
;     const char* gp = (const char*)F.Z + ((size_t)row0 * ZW + (GDN ? ZC_GZ : ZC_LO) + h * 64) * 2;
; #pragma unroll
;     for (int pr = 0; pr < 2; ++pr) { const v4u qp = ldu<v4u>(pp + pr * 1024, L.pend); f.pend[2 * pr] = (v2u){qp.x, qp.y}; f.pend[2 * pr + 1] = (v2u){qp.z, qp.w}; }
; #pragma unroll
;     for (int t = 0; t < 4; ++t) f.gz[t] = ldu<v2u>(upin(gp + (size_t)t * ZW * 2), L.gz);
; }
.LBB0_405:
	s_cmp_gt_u32 s25, 32
	s_cselect_b64 s[4:5], -1, 0
	s_cmp_lt_u32 s0, 16
	s_cselect_b64 s[6:7], -1, 0
	s_or_b64 s[4:5], s[4:5], s[6:7]
	s_andn2_b64 vcc, exec, s[4:5]
	s_mov_b64 s[10:11], -1
	s_cbranch_vccz .LBB0_407
	s_add_i32 s5, s25, 3
	s_add_i32 s4, s1, s24
	s_and_b64 s[6:7], s[90:91], exec
	s_cselect_b32 s5, s5, s4
	s_lshl_b32 s6, s5, 6
	s_or_b32 s7, s6, s63
	s_add_i32 s6, s6, s33
	s_cmp_lt_u32 s5, 4
	s_cselect_b32 s8, s7, s6
	s_add_i32 s92, s5, s31
	s_lshl_b64 s[6:7], s[92:93], 14
	v_readlane_b32 s10, v253, 25
	s_add_u32 s6, s22, s6
	s_mul_hi_u32 s9, s8, 0xd00
	s_mulk_i32 s8, 0xd00
	v_readlane_b32 s11, v253, 26
	s_addc_u32 s7, s23, s7
	s_or_b64 s[8:9], s[8:9], s[10:11]
	s_lshl_b64 s[8:9], s[8:9], 1
	global_load_dwordx4 v[12:15], v192, s[6:7]
	global_load_dwordx4 v[16:19], v192, s[6:7] offset:1024
	s_add_u32 s6, s16, s8
	s_addc_u32 s7, s17, s9
	s_mov_b64 s[8:9], s[6:7]
	global_load_dwordx2 v[130:131], v191, s[8:9]
	s_add_u32 s8, s6, 0x1a00
	s_addc_u32 s9, s7, 0
	global_load_dwordx2 v[132:133], v191, s[8:9]
	s_add_u32 s8, s6, 0x3400
	s_addc_u32 s9, s7, 0
	s_add_u32 s6, s6, 0x4e00
	s_addc_u32 s7, s7, 0
	global_load_dwordx2 v[134:135], v191, s[8:9]
	global_load_dwordx2 v[136:137], v191, s[6:7]
	s_mov_b64 s[10:11], 0

; template <bool GDN, int NT> __device__ __forceinline__ void scan_load(const Frame& F, int b, int h, int dir, const ScanLane& L, int s, ScanOps<NT>& o) {
;     ...
;         const char* zq = upin((const char*)F.Z + ((size_t)chunk_row0(b, cidx) * ZW + ZC_LQ + h * 64) * 2);
; #pragma unroll
;         for (int ks = 0; ks < 2; ++ks) { o.Qf[ks] = ldu<bf16x8>(zq + ks * 64, L.zq); o.Mf[ks] = o.Qf[ks]; }
;         const char* base = (const char*)F.PM + (size_t)ud * 20480;
;         const char* bO = upin(base); const char* bB = upin(base + 10240);
; #pragma unroll
;         for (int pr = 0; pr < 2; ++pr) { const v4u qb = ldun<v4u>(bB + pr * 1024, L.o16p), qo = ldun<v4u>(bO + pr * 1024, L.o16p);
;             o.bv[2 * pr] = (v2u){qb.x, qb.y}; o.bv[2 * pr + 1] = (v2u){qb.z, qb.w}; o.ov[2 * pr] = (v2u){qo.x, qo.y}; o.ov[2 * pr + 1] = (v2u){qo.z, qo.w}; }
;         o.bv[4] = ldun<v2u>(bB + 2048, L.o8); o.ov[4] = ldun<v2u>(bO + 2048, L.o8);
;         o.wi = ldu<f32x4>(upin((const char*)F.WI + (size_t)ud * 256), L.wi);
;     ...
;     const float gl = ((const LAS float*)(St + 4 * 80 * 72))[(dir ? (s < 4 ? 3 - s : 39 - s) : s) * 2 + dir];
;     f32x4 O[NT];
; #pragma unroll
;     for (int t = 0; t < NT; ++t) {
;         const LAS bf16_t* sp2 = Sb + (16 * t + lr) * 72 + 8 * lq;
;         const bf16x8 s0 = *(const LAS bf16x8*)sp2, s1 = *(const LAS bf16x8*)(sp2 + 32);
;         const f32x4 bv = unpack4(use.bv[t]), ov = unpack4(use.ov[t]);
;         if (GDN) {
;             f32x4 o = ov, sn = S[t] * gl + bv;
;             o = __builtin_amdgcn_mfma_f32_16x16x32_bf16(use.Qf[0], s0, o, 0, 0, 0); o = __builtin_amdgcn_mfma_f32_16x16x32_bf16(use.Qf[1], s1, o, 0, 0, 0);
;             sn = __builtin_amdgcn_mfma_f32_16x16x32_bf16(use.Mf[0], s0, sn, 0, 0, 0); sn = __builtin_amdgcn_mfma_f32_16x16x32_bf16(use.Mf[1], s1, sn, 0, 0, 0);
;             S[t] = sn; O[t] = o;
;         } else {
;             f32x4 o = {0.f, 0.f, 0.f, 0.f};
;             o = __builtin_amdgcn_mfma_f32_16x16x32_bf16(use.Qf[0], s0, o, 0, 0, 0); o = __builtin_amdgcn_mfma_f32_16x16x32_bf16(use.Qf[1], s1, o, 0, 0, 0);
;             S[t] = S[t] * gl + bv; O[t] = o * use.wi + ov; }
;     }
;     if (!GDN) {
; #pragma unroll
;         for (int i = 0; i < 4; ++i) { const float den = row16_bcast<0>(O[NT - 1][i]), fl = row16_bcast<1>(O[NT - 1][i]); const float dv = frcp(fmaxf(fabsf(den), fl));
; #pragma unroll
.LBB0_409:
	s_min_u32 s5, s3, 33
	s_add_i32 s8, s5, 2
	s_sub_i32 s5, 37, s5
	s_and_b64 s[6:7], s[90:91], exec
	s_cselect_b32 s5, s8, s5
	s_lshl_b32 s6, s5, 6
	s_add_i32 s6, s6, s33
	s_add_i32 s5, s5, s31
	s_mulk_i32 s6, 0xd00
	s_lshl_b32 s5, s5, 1
	s_or_b32 s6, s36, s6
	s_mov_b32 s7, s37
	s_add_i32 s92, s5, s68
	s_lshl_b64 s[6:7], s[6:7], 1
	s_add_u32 s6, s16, s6
	s_addc_u32 s7, s17, s7
	global_load_dwordx4 v[24:27], v190, s[6:7]
	global_load_dwordx4 v[20:23], v190, s[6:7] offset:64
	s_mul_i32 s6, s92, 0x5000
	v_readlane_b32 s7, v254, 46
	s_mul_hi_u32 s5, s92, 0x5000
	s_add_u32 s6, s7, s6
	v_readlane_b32 s7, v254, 47
	s_addc_u32 s7, s7, s5
	s_mov_b64 s[8:9], s[6:7]
	s_add_u32 s6, s6, 0x2800
	s_addc_u32 s7, s7, 0
	s_nop 0
	global_load_dwordx4 v[44:47], v189, s[6:7] nt
	global_load_dwordx4 v[28:31], v189, s[6:7] offset:1024 nt
	global_load_dwordx4 v[52:55], v189, s[8:9] nt
	global_load_dwordx4 v[32:35], v189, s[8:9] offset:1024 nt
	global_load_dwordx2 v[140:141], v188, s[6:7] offset:2048 nt
	global_load_dwordx2 v[138:139], v188, s[8:9] offset:2048 nt
	s_lshl_b64 s[6:7], s[92:93], 8
	v_readlane_b32 s8, v254, 52
	v_readlane_b32 s9, v254, 53
	s_add_u32 s6, s8, s6
	s_addc_u32 s7, s9, s7
	global_load_dwordx4 v[100:103], v0, s[6:7]
	s_add_i32 s6, s4, 1
	s_and_b64 s[4:5], s[90:91], exec
	s_cselect_b32 s4, s3, s6
	s_lshl_b32 s4, s4, 3
	s_add_i32 s4, s34, s4
	v_mov_b32_e32 v0, s4
	ds_read_b32 v0, v0 offset:46080
	ds_read_b128 v[204:207], v203
	ds_read_b128 v[208:211], v203 offset:64
	s_waitcnt lgkmcnt(1)
	v_mfma_f32_16x16x32_bf16 v[204:207], v[56:59], v[204:207], 0
	v_lshlrev_b32_e32 v112, 16, v84
	v_and_b32_e32 v113, 0xffff0000, v84
	v_lshlrev_b32_e32 v84, 16, v85
	s_waitcnt lgkmcnt(0)
	v_mfma_f32_16x16x32_bf16 v[204:207], v[48:51], v[208:211], v[204:207]
	v_and_b32_e32 v85, 0xffff0000, v85
	v_lshlrev_b32_e32 v114, 16, v88
	v_and_b32_e32 v115, 0xffff0000, v88
	v_lshlrev_b32_e32 v88, 16, v89
	v_and_b32_e32 v89, 0xffff0000, v89
	v_pk_fma_f32 v[180:181], v[180:181], v[0:1], v[84:85] op_sel_hi:[1,0,1]
	s_nop 1
	v_pk_fma_f32 v[84:85], v[72:73], v[204:205], v[114:115]
	v_pk_fma_f32 v[88:89], v[74:75], v[206:207], v[88:89]
	ds_read_b128 v[204:207], v203 offset:2304
	ds_read_b128 v[208:211], v203 offset:2368
	s_waitcnt lgkmcnt(1)
	v_mfma_f32_16x16x32_bf16 v[204:207], v[56:59], v[204:207], 0
	v_fma_f32 v182, v182, v0, v112
	v_fma_f32 v183, v183, v0, v113
	v_lshlrev_b32_e32 v112, 16, v86
	v_and_b32_e32 v113, 0xffff0000, v86
	s_waitcnt lgkmcnt(0)
	v_mfma_f32_16x16x32_bf16 v[204:207], v[48:51], v[208:211], v[204:207]
	v_lshlrev_b32_e32 v86, 16, v87
	v_and_b32_e32 v87, 0xffff0000, v87
	v_lshlrev_b32_e32 v114, 16, v90
	v_and_b32_e32 v115, 0xffff0000, v90
	v_lshlrev_b32_e32 v90, 16, v91
	v_and_b32_e32 v91, 0xffff0000, v91
	v_pk_fma_f32 v[150:151], v[150:151], v[0:1], v[86:87] op_sel_hi:[1,0,1]
	s_nop 0
	v_pk_fma_f32 v[86:87], v[72:73], v[204:205], v[114:115]
	v_pk_fma_f32 v[90:91], v[74:75], v[206:207], v[90:91]
	ds_read_b128 v[204:207], v203 offset:4608
	ds_read_b128 v[208:211], v203 offset:4672
	s_waitcnt lgkmcnt(1)
	v_mfma_f32_16x16x32_bf16 v[204:207], v[56:59], v[204:207], 0
	v_fma_f32 v154, v154, v0, v112
	v_fma_f32 v155, v155, v0, v113
	v_lshlrev_b32_e32 v112, 16, v76
	v_and_b32_e32 v113, 0xffff0000, v76
	s_waitcnt lgkmcnt(0)
	v_mfma_f32_16x16x32_bf16 v[204:207], v[48:51], v[208:211], v[204:207]
	v_lshlrev_b32_e32 v76, 16, v77
	v_and_b32_e32 v77, 0xffff0000, v77
	v_lshlrev_b32_e32 v114, 16, v80
	v_and_b32_e32 v115, 0xffff0000, v80
	v_lshlrev_b32_e32 v80, 16, v81
	v_and_b32_e32 v81, 0xffff0000, v81
	v_pk_fma_f32 v[148:149], v[148:149], v[0:1], v[76:77] op_sel_hi:[1,0,1]
	s_nop 0
	v_pk_fma_f32 v[76:77], v[72:73], v[204:205], v[114:115]
	v_pk_fma_f32 v[80:81], v[74:75], v[206:207], v[80:81]
	ds_read_b128 v[204:207], v203 offset:6912
	ds_read_b128 v[208:211], v203 offset:6976
	s_waitcnt lgkmcnt(1)
	v_mfma_f32_16x16x32_bf16 v[204:207], v[56:59], v[204:207], 0
	v_fma_f32 v152, v152, v0, v112
	v_fma_f32 v153, v153, v0, v113
	v_lshlrev_b32_e32 v112, 16, v78
	v_and_b32_e32 v113, 0xffff0000, v78
	s_waitcnt lgkmcnt(0)
	v_mfma_f32_16x16x32_bf16 v[204:207], v[48:51], v[208:211], v[204:207]
	v_lshlrev_b32_e32 v78, 16, v79
	v_and_b32_e32 v79, 0xffff0000, v79
	v_lshlrev_b32_e32 v114, 16, v82
	v_and_b32_e32 v115, 0xffff0000, v82
	v_lshlrev_b32_e32 v82, 16, v83
	v_and_b32_e32 v83, 0xffff0000, v83
	v_pk_fma_f32 v[184:185], v[184:185], v[0:1], v[78:79] op_sel_hi:[1,0,1]
	s_nop 0
	v_pk_fma_f32 v[78:79], v[72:73], v[204:205], v[114:115]
	v_pk_fma_f32 v[82:83], v[74:75], v[206:207], v[82:83]
	ds_read_b128 v[204:207], v203 offset:9216
	ds_read_b128 v[208:211], v203 offset:9280
	s_waitcnt lgkmcnt(1)
	v_mfma_f32_16x16x32_bf16 v[204:207], v[56:59], v[204:207], 0
	v_lshlrev_b32_e32 v116, 16, v2
	v_and_b32_e32 v117, 0xffff0000, v2
	v_lshlrev_b32_e32 v2, 16, v3
	s_waitcnt lgkmcnt(0)
	v_mfma_f32_16x16x32_bf16 v[204:207], v[48:51], v[208:211], v[204:207]
	v_and_b32_e32 v3, 0xffff0000, v3
	v_pk_fma_f32 v[160:161], v[160:161], v[0:1], v[112:113] op_sel_hi:[1,0,1]
	v_lshlrev_b32_e32 v112, 16, v144
	v_and_b32_e32 v113, 0xffff0000, v144
	v_lshlrev_b32_e32 v114, 16, v145
	s_nop 2
	v_pk_fma_f32 v[204:205], v[72:73], v[204:205], v[116:117]
	v_pk_fma_f32 v[2:3], v[74:75], v[206:207], v[2:3]
	v_and_b32_e32 v115, 0xffff0000, v145
	v_mov_b32_dpp v206, v204 row_newbcast:0 row_mask:0xf bank_mask:0xf bound_ctrl:1
	v_mov_b32_dpp v204, v204 row_newbcast:1 row_mask:0xf bank_mask:0xf bound_ctrl:1
	v_max_f32_e32 v204, v204, v204
	v_max_f32_e64 v206, |v206|, |v206|
	v_max_f32_e32 v204, v206, v204
	v_rcp_f32_e32 v204, v204
	v_mov_b32_dpp v206, v205 row_newbcast:0 row_mask:0xf bank_mask:0xf bound_ctrl:1
	v_mov_b32_dpp v205, v205 row_newbcast:1 row_mask:0xf bank_mask:0xf bound_ctrl:1
	v_max_f32_e32 v205, v205, v205
	v_max_f32_e64 v206, |v206|, |v206|
	v_max_f32_e32 v205, v206, v205
	v_rcp_f32_e32 v205, v205
	v_mov_b32_dpp v206, v2 row_newbcast:0 row_mask:0xf bank_mask:0xf bound_ctrl:1
	v_mov_b32_dpp v2, v2 row_newbcast:1 row_mask:0xf bank_mask:0xf bound_ctrl:1
	v_max_f32_e32 v2, v2, v2
	v_max_f32_e64 v206, |v206|, |v206|
	v_max_f32_e32 v2, v206, v2
	v_rcp_f32_e32 v206, v2
	v_pk_fma_f32 v[156:157], v[156:157], v[0:1], v[114:115] op_sel_hi:[1,0,1]
	v_mov_b32_dpp v2, v3 row_newbcast:0 row_mask:0xf bank_mask:0xf bound_ctrl:1
	v_mov_b32_dpp v3, v3 row_newbcast:1 row_mask:0xf bank_mask:0xf bound_ctrl:1
	v_max_f32_e32 v3, v3, v3
	v_max_f32_e64 v2, |v2|, |v2|
	v_max_f32_e32 v2, v2, v3
	v_rcp_f32_e32 v207, v2
	v_pk_fma_f32 v[158:159], v[158:159], v[0:1], v[112:113] op_sel_hi:[1,0,1]
	v_pk_mul_f32 v[50:51], v[84:85], v[204:205]
	v_pk_mul_f32 v[112:113], v[86:87], v[204:205]
	v_pk_mul_f32 v[2:3], v[88:89], v[206:207]
	v_pk_mul_f32 v[118:119], v[90:91], v[206:207]
	v_pk_mul_f32 v[48:49], v[80:81], v[206:207]
	v_pk_mul_f32 v[56:57], v[76:77], v[204:205]
	v_pk_mul_f32 v[116:117], v[82:83], v[206:207]
	v_pk_mul_f32 v[114:115], v[78:79], v[204:205]
	s_branch .LBB0_413

; __device__ __forceinline__ float row16_sum(float v) { v += dppf<0xB1>(v); v += dppf<0x4E>(v); v += dppf<0x141>(v); v += dppf<0x140>(v); return v; }
; __device__ __forceinline__ float frsq(float x) { return __builtin_amdgcn_rsqf(x); }
; __device__ __forceinline__ v2u pack4(const f32x4 v) { v2u r; r.x = pk2(v[0], v[1]); r.y = pk2(v[2], v[3]); return r; }
; __device__ __forceinline__ f32x4 unpack4(const v2u w) { f32x4 r; r[0] = bflo(w.x); r[1] = bfhi(w.x); r[2] = bflo(w.y); r[3] = bfhi(w.y); return r; }
; __device__ __forceinline__ const char* upin(const char* p) { asm volatile("" : "+s"(p)); return p; }
; __device__ __forceinline__ char* upin(char* p) { asm volatile("" : "+s"(p)); return p; }
; template <bool GDN> __device__ __forceinline__ void scan_finish(const Frame& F, int b, int h, int dir, const ScanLane& L, int s, float* PEND, const f32x4 (&Oin)[4], const ScanFin& f) {
;     ...
;         f32x4 O[4]; float ss[4] = {0.f, 0.f, 0.f, 0.f};
; #pragma unroll
;         for (int t = 0; t < 4; ++t)
;             { const f32x4 pv = unpack4(f.pend[t]);
; #pragma unroll
;             for (int i = 0; i < 4; ++i) { O[t][i] = Oin[t][i] + pv[i]; ss[i] += O[t][i] * O[t][i]; } }
; #pragma unroll
;         for (int i = 0; i < 4; ++i) ss[i] = frsq(row16_sum(ss[i]) * (1.f / 64.f) + EPS);
;         char* mp = (char*)F.MIX + ((size_t)row0 * 1024 + (GDN ? 0 : 768) + h * 64) * 2;
; #pragma unroll
;         for (int i = 0; i < 4; ++i) { const f32x4 g = unpack4(f.gz[i]); f32x4 ov;
; #pragma unroll
;             for (int t = 0; t < 4; ++t) ov[t] = O[t][i] * ss[i] * g[t];
;             stu<v2u>(upin(mp + i * 2048), L.mix, pack4(ov)); }
.LBB0_434:
	s_waitcnt vmcnt(63)
	v_lshlrev_b32_e32 v83, 16, v6
	v_lshlrev_b32_e32 v82, 16, v4
	v_mov_b32_e32 v84, v50
	v_mov_b32_e32 v85, v112
	s_waitcnt vmcnt(63)
	v_lshlrev_b32_e32 v77, 16, v10
	v_lshlrev_b32_e32 v76, 16, v8
	v_mov_b32_e32 v78, v56
	v_mov_b32_e32 v79, v114
	v_pk_add_f32 v[82:83], v[84:85], v[82:83]
	v_pk_add_f32 v[76:77], v[78:79], v[76:77]
	v_pk_mul_f32 v[84:85], v[82:83], v[82:83]
	v_pk_mul_f32 v[78:79], v[76:77], v[76:77]
	v_add_f32_e32 v81, v85, v84
	v_add_f32_e32 v78, v78, v81
	v_add_f32_e32 v78, v79, v78
	s_lshl_b32 s3, s4, 6
	s_cmp_lt_i32 s4, 4
	v_add_f32_dpp v78, v78, v78 quad_perm:[1,0,3,2] row_mask:0xf bank_mask:0xf bound_ctrl:1
	s_cselect_b32 s5, s63, s33
	s_add_i32 s6, s5, s3
	v_add_f32_dpp v78, v78, v78 quad_perm:[2,3,0,1] row_mask:0xf bank_mask:0xf bound_ctrl:1
	s_ashr_i32 s7, s6, 31
	s_lshl_b64 s[6:7], s[6:7], 11
	v_add_f32_dpp v78, v78, v78 row_half_mirror row_mask:0xf bank_mask:0xf bound_ctrl:1
	s_add_u32 s3, s26, s6
	s_addc_u32 s5, s27, s7
	v_add_f32_dpp v78, v78, v78 row_mirror row_mask:0xf bank_mask:0xf bound_ctrl:1
	v_fmamk_f32 v78, v78, 0x3c800000, v231
	v_rsq_f32_e32 v78, v78
	s_waitcnt vmcnt(63)
	v_lshlrev_b32_e32 v80, 16, v123
	v_and_b32_e32 v81, 0xffff0000, v123
	v_lshlrev_b32_e32 v84, 16, v122
	v_and_b32_e32 v85, 0xffff0000, v122
	v_pk_mul_f32 v[82:83], v[82:83], v[78:79] op_sel_hi:[1,0]
	v_pk_mul_f32 v[76:77], v[76:77], v[78:79] op_sel_hi:[1,0]
	s_add_u32 s6, s3, 0x600
	v_pk_mul_f32 v[82:83], v[82:83], v[84:85]
	v_pk_mul_f32 v[76:77], v[76:77], v[80:81]
	s_addc_u32 s7, s5, 0
	v_cvt_pk_bf16_f32 v78, v82, v83
	v_cvt_pk_bf16_f32 v79, v76, v77
	v_and_b32_e32 v83, 0xffff0000, v6
	v_and_b32_e32 v82, 0xffff0000, v4
	v_mov_b32_e32 v84, v51
	v_mov_b32_e32 v85, v113
	global_store_dwordx2 v75, v[78:79], s[6:7]
	v_and_b32_e32 v77, 0xffff0000, v10
	v_and_b32_e32 v76, 0xffff0000, v8
	v_mov_b32_e32 v78, v57
	v_mov_b32_e32 v79, v115
	v_pk_add_f32 v[82:83], v[84:85], v[82:83]
	v_pk_add_f32 v[76:77], v[78:79], v[76:77]
	v_pk_mul_f32 v[84:85], v[82:83], v[82:83]
	v_pk_mul_f32 v[78:79], v[76:77], v[76:77]
	v_add_f32_e32 v81, v85, v84
	v_add_f32_e32 v78, v78, v81
	v_add_f32_e32 v78, v79, v78
	s_waitcnt vmcnt(63)
	v_lshlrev_b32_e32 v80, 16, v125
	v_and_b32_e32 v81, 0xffff0000, v125
	v_add_f32_dpp v78, v78, v78 quad_perm:[1,0,3,2] row_mask:0xf bank_mask:0xf bound_ctrl:1
	v_lshlrev_b32_e32 v84, 16, v124
	v_and_b32_e32 v85, 0xffff0000, v124
	v_add_f32_dpp v78, v78, v78 quad_perm:[2,3,0,1] row_mask:0xf bank_mask:0xf bound_ctrl:1
	s_add_u32 s6, s3, 0xe00
	s_addc_u32 s7, s5, 0
	v_add_f32_dpp v78, v78, v78 row_half_mirror row_mask:0xf bank_mask:0xf bound_ctrl:1
	s_nop 1
	v_add_f32_dpp v78, v78, v78 row_mirror row_mask:0xf bank_mask:0xf bound_ctrl:1
	v_fmamk_f32 v78, v78, 0x3c800000, v231
	v_rsq_f32_e32 v78, v78
	s_nop 0
	v_pk_mul_f32 v[82:83], v[82:83], v[78:79] op_sel_hi:[1,0]
	v_pk_mul_f32 v[76:77], v[76:77], v[78:79] op_sel_hi:[1,0]
	v_pk_mul_f32 v[82:83], v[82:83], v[84:85]
	v_pk_mul_f32 v[76:77], v[76:77], v[80:81]
	v_cvt_pk_bf16_f32 v78, v82, v83
	v_cvt_pk_bf16_f32 v79, v76, v77
	v_lshlrev_b32_e32 v83, 16, v7
	v_lshlrev_b32_e32 v82, 16, v5
	v_mov_b32_e32 v84, v2
	v_mov_b32_e32 v85, v118
	global_store_dwordx2 v75, v[78:79], s[6:7]
	v_lshlrev_b32_e32 v77, 16, v11
	v_lshlrev_b32_e32 v76, 16, v9
	v_mov_b32_e32 v78, v48
	v_mov_b32_e32 v79, v116
	v_pk_add_f32 v[82:83], v[84:85], v[82:83]
	v_pk_add_f32 v[76:77], v[78:79], v[76:77]
	v_pk_mul_f32 v[84:85], v[82:83], v[82:83]
	v_pk_mul_f32 v[78:79], v[76:77], v[76:77]
	v_add_f32_e32 v81, v85, v84
	v_add_f32_e32 v78, v78, v81
	v_add_f32_e32 v78, v79, v78
	s_waitcnt vmcnt(63)
	v_lshlrev_b32_e32 v80, 16, v127
	v_and_b32_e32 v81, 0xffff0000, v127
	v_add_f32_dpp v78, v78, v78 quad_perm:[1,0,3,2] row_mask:0xf bank_mask:0xf bound_ctrl:1
	v_lshlrev_b32_e32 v84, 16, v126
	v_and_b32_e32 v85, 0xffff0000, v126
	v_add_f32_dpp v78, v78, v78 quad_perm:[2,3,0,1] row_mask:0xf bank_mask:0xf bound_ctrl:1
	s_add_u32 s6, s3, 0x1600
	s_addc_u32 s7, s5, 0
	v_add_f32_dpp v78, v78, v78 row_half_mirror row_mask:0xf bank_mask:0xf bound_ctrl:1
	s_nop 1
	v_add_f32_dpp v78, v78, v78 row_mirror row_mask:0xf bank_mask:0xf bound_ctrl:1
	v_fmamk_f32 v78, v78, 0x3c800000, v231
	v_rsq_f32_e32 v78, v78
	s_nop 0
	v_pk_mul_f32 v[82:83], v[82:83], v[78:79] op_sel_hi:[1,0]
	v_pk_mul_f32 v[76:77], v[76:77], v[78:79] op_sel_hi:[1,0]
	v_pk_mul_f32 v[82:83], v[82:83], v[84:85]
	v_pk_mul_f32 v[76:77], v[76:77], v[80:81]
	v_cvt_pk_bf16_f32 v78, v82, v83
	v_cvt_pk_bf16_f32 v79, v76, v77
	v_and_b32_e32 v83, 0xffff0000, v7
	v_and_b32_e32 v82, 0xffff0000, v5
	v_mov_b32_e32 v84, v3
	v_mov_b32_e32 v85, v119
	global_store_dwordx2 v75, v[78:79], s[6:7]
	v_and_b32_e32 v77, 0xffff0000, v11
	v_and_b32_e32 v76, 0xffff0000, v9
	v_mov_b32_e32 v78, v49
	v_mov_b32_e32 v79, v117
	v_pk_add_f32 v[82:83], v[84:85], v[82:83]
	v_pk_add_f32 v[76:77], v[78:79], v[76:77]
	v_pk_mul_f32 v[84:85], v[82:83], v[82:83]
	v_pk_mul_f32 v[78:79], v[76:77], v[76:77]
	v_add_f32_e32 v81, v85, v84
	v_add_f32_e32 v78, v78, v81
	v_add_f32_e32 v78, v79, v78
	s_waitcnt vmcnt(63)
	v_lshlrev_b32_e32 v80, 16, v129
	v_and_b32_e32 v81, 0xffff0000, v129
	v_add_f32_dpp v78, v78, v78 quad_perm:[1,0,3,2] row_mask:0xf bank_mask:0xf bound_ctrl:1
	v_lshlrev_b32_e32 v84, 16, v128
	v_and_b32_e32 v85, 0xffff0000, v128
	v_add_f32_dpp v78, v78, v78 quad_perm:[2,3,0,1] row_mask:0xf bank_mask:0xf bound_ctrl:1
	s_add_u32 s6, s3, 0x1e00
	s_addc_u32 s7, s5, 0
	v_add_f32_dpp v78, v78, v78 row_half_mirror row_mask:0xf bank_mask:0xf bound_ctrl:1
	s_nop 1
	v_add_f32_dpp v78, v78, v78 row_mirror row_mask:0xf bank_mask:0xf bound_ctrl:1
	v_fmamk_f32 v78, v78, 0x3c800000, v231
	v_rsq_f32_e32 v78, v78
	s_nop 0
	v_pk_mul_f32 v[82:83], v[82:83], v[78:79] op_sel_hi:[1,0]
	v_pk_mul_f32 v[76:77], v[76:77], v[78:79] op_sel_hi:[1,0]
	v_pk_mul_f32 v[82:83], v[82:83], v[84:85]
	v_pk_mul_f32 v[76:77], v[76:77], v[80:81]
	v_cvt_pk_bf16_f32 v78, v82, v83
	v_cvt_pk_bf16_f32 v79, v76, v77
	global_store_dwordx2 v75, v[78:79], s[6:7]
	s_cbranch_execz .LBB0_450

; template <bool GDN, int NT> __device__ __forceinline__ void scan_load(const Frame& F, int b, int h, int dir, const ScanLane& L, int s, ScanOps<NT>& o) {
;     ...
;         const char* zq = upin((const char*)F.Z + ((size_t)chunk_row0(b, cidx) * ZW + ZC_LQ + h * 64) * 2);
; #pragma unroll
;         for (int ks = 0; ks < 2; ++ks) { o.Qf[ks] = ldu<bf16x8>(zq + ks * 64, L.zq); o.Mf[ks] = o.Qf[ks]; }
;         const char* base = (const char*)F.PM + (size_t)ud * 20480;
;         const char* bO = upin(base); const char* bB = upin(base + 10240);
; #pragma unroll
;         for (int pr = 0; pr < 2; ++pr) { const v4u qb = ldun<v4u>(bB + pr * 1024, L.o16p), qo = ldun<v4u>(bO + pr * 1024, L.o16p);
;             o.bv[2 * pr] = (v2u){qb.x, qb.y}; o.bv[2 * pr + 1] = (v2u){qb.z, qb.w}; o.ov[2 * pr] = (v2u){qo.x, qo.y}; o.ov[2 * pr + 1] = (v2u){qo.z, qo.w}; }
;         o.bv[4] = ldun<v2u>(bB + 2048, L.o8); o.ov[4] = ldun<v2u>(bO + 2048, L.o8);
;         o.wi = ldu<f32x4>(upin((const char*)F.WI + (size_t)ud * 256), L.wi);
;     ...
;     const float gl = ((const LAS float*)(St + 4 * 80 * 72))[(dir ? (s < 4 ? 3 - s : 39 - s) : s) * 2 + dir];
;     f32x4 O[NT];
; #pragma unroll
;     for (int t = 0; t < NT; ++t) {
;         const LAS bf16_t* sp2 = Sb + (16 * t + lr) * 72 + 8 * lq;
;         const bf16x8 s0 = *(const LAS bf16x8*)sp2, s1 = *(const LAS bf16x8*)(sp2 + 32);
;         const f32x4 bv = unpack4(use.bv[t]), ov = unpack4(use.ov[t]);
;         if (GDN) {
;             f32x4 o = ov, sn = S[t] * gl + bv;
;             o = __builtin_amdgcn_mfma_f32_16x16x32_bf16(use.Qf[0], s0, o, 0, 0, 0); o = __builtin_amdgcn_mfma_f32_16x16x32_bf16(use.Qf[1], s1, o, 0, 0, 0);
;             sn = __builtin_amdgcn_mfma_f32_16x16x32_bf16(use.Mf[0], s0, sn, 0, 0, 0); sn = __builtin_amdgcn_mfma_f32_16x16x32_bf16(use.Mf[1], s1, sn, 0, 0, 0);
;             S[t] = sn; O[t] = o;
;         } else {
;             f32x4 o = {0.f, 0.f, 0.f, 0.f};
;             o = __builtin_amdgcn_mfma_f32_16x16x32_bf16(use.Qf[0], s0, o, 0, 0, 0); o = __builtin_amdgcn_mfma_f32_16x16x32_bf16(use.Qf[1], s1, o, 0, 0, 0);
;             S[t] = S[t] * gl + bv; O[t] = o * use.wi + ov; }
;     }
;     if (!GDN) {
; #pragma unroll
;         for (int i = 0; i < 4; ++i) { const float den = row16_bcast<0>(O[NT - 1][i]), fl = row16_bcast<1>(O[NT - 1][i]); const float dv = frcp(fmaxf(fabsf(den), fl));
; #pragma unroll
.LBB0_437:
	s_add_i32 s8, s25, 3
	s_min_u32 s4, s8, 33
	s_add_i32 s6, s4, 2
	s_sub_i32 s7, 37, s4
	s_and_b64 s[4:5], s[90:91], exec
	s_cselect_b32 s4, s6, s7
	s_lshl_b32 s5, s4, 6
	s_add_i32 s5, s5, s33
	s_add_i32 s4, s4, s31
	s_lshl_b32 s4, s4, 1
	s_mulk_i32 s5, 0xd00
	s_add_i32 s92, s4, s68
	s_or_b32 s4, s36, s5
	s_mov_b32 s5, s37
	s_lshl_b64 s[4:5], s[4:5], 1
	s_add_u32 s4, s16, s4
	s_addc_u32 s5, s17, s5
	global_load_dwordx4 v[56:59], v74, s[4:5]
	global_load_dwordx4 v[48:51], v74, s[4:5] offset:64
	s_mul_i32 s4, s92, 0x5000
	v_readlane_b32 s6, v254, 46
	s_mul_hi_u32 s5, s92, 0x5000
	s_add_u32 s4, s6, s4
	v_readlane_b32 s6, v254, 47
	s_addc_u32 s5, s6, s5
	s_mov_b64 s[6:7], s[4:5]
	s_add_u32 s4, s4, 0x2800
	s_addc_u32 s5, s5, 0
	global_load_dwordx4 v[84:87], v73, s[4:5] nt
	global_load_dwordx4 v[76:79], v73, s[4:5] offset:1024 nt
	global_load_dwordx4 v[88:91], v73, s[6:7] nt
	global_load_dwordx4 v[80:83], v73, s[6:7] offset:1024 nt
	global_load_dwordx2 v[144:145], v72, s[4:5] offset:2048 nt
	global_load_dwordx2 v[2:3], v72, s[6:7] offset:2048 nt
	s_lshl_b64 s[4:5], s[92:93], 8
	v_readlane_b32 s6, v254, 52
	v_readlane_b32 s7, v254, 53
	s_add_u32 s4, s6, s4
	s_addc_u32 s5, s7, s5
	global_load_dwordx4 v[72:75], v0, s[4:5]
	s_add_i32 s1, s1, s24
	s_and_b64 s[4:5], s[90:91], exec
	s_cselect_b32 s1, s8, s1
	ds_read_b128 v[104:107], v203 offset:11520
	s_lshl_b32 s4, s1, 3
	s_add_i32 s4, s34, s4
	v_mov_b32_e32 v0, s4
	ds_read_b32 v0, v0 offset:46080
	ds_read_b128 v[108:111], v203 offset:11584
	s_waitcnt lgkmcnt(2)
	v_mfma_f32_16x16x32_bf16 v[104:107], v[40:43], v[104:107], 0
	s_waitcnt vmcnt(63)
	v_lshlrev_b32_e32 v112, 16, v92
	v_and_b32_e32 v113, 0xffff0000, v92
	v_lshlrev_b32_e32 v114, 16, v93
	s_waitcnt lgkmcnt(0)
	v_mfma_f32_16x16x32_bf16 v[104:107], v[36:39], v[108:111], v[104:107]
	ds_read_b128 v[108:111], v203 offset:13824
	v_and_b32_e32 v115, 0xffff0000, v93
	v_pk_fma_f32 v[192:193], v[180:181], v[0:1], v[114:115] op_sel_hi:[1,0,1]
	v_pk_fma_f32 v[190:191], v[182:183], v[0:1], v[112:113] op_sel_hi:[1,0,1]
	ds_read_b128 v[112:115], v203 offset:13888
	s_waitcnt lgkmcnt(1)
	v_mfma_f32_16x16x32_bf16 v[108:111], v[40:43], v[108:111], 0
	v_lshlrev_b32_e32 v116, 16, v94
	v_and_b32_e32 v117, 0xffff0000, v94
	v_lshlrev_b32_e32 v118, 16, v95
	s_waitcnt lgkmcnt(0)
	v_mfma_f32_16x16x32_bf16 v[108:111], v[36:39], v[112:115], v[108:111]
	ds_read_b128 v[112:115], v203 offset:16128
	v_and_b32_e32 v119, 0xffff0000, v95
	v_pk_fma_f32 v[188:189], v[150:151], v[0:1], v[118:119] op_sel_hi:[1,0,1]
	v_pk_fma_f32 v[154:155], v[154:155], v[0:1], v[116:117] op_sel_hi:[1,0,1]
	ds_read_b128 v[116:119], v203 offset:16192
	s_waitcnt lgkmcnt(1)
	v_mfma_f32_16x16x32_bf16 v[112:115], v[40:43], v[112:115], 0
	s_waitcnt vmcnt(63)
	v_lshlrev_b32_e32 v150, 16, v64
	v_and_b32_e32 v151, 0xffff0000, v64
	v_lshlrev_b32_e32 v162, 16, v65
	s_waitcnt lgkmcnt(0)
	v_mfma_f32_16x16x32_bf16 v[112:115], v[36:39], v[116:119], v[112:115]
	ds_read_b128 v[116:119], v203 offset:18432
	v_and_b32_e32 v163, 0xffff0000, v65
	v_pk_fma_f32 v[186:187], v[148:149], v[0:1], v[162:163] op_sel_hi:[1,0,1]
	v_pk_fma_f32 v[182:183], v[152:153], v[0:1], v[150:151] op_sel_hi:[1,0,1]
	ds_read_b128 v[148:151], v203 offset:18496
	s_waitcnt lgkmcnt(1)
	v_mfma_f32_16x16x32_bf16 v[116:119], v[40:43], v[116:119], 0
	v_lshlrev_b32_e32 v152, 16, v66
	v_and_b32_e32 v153, 0xffff0000, v66
	s_waitcnt vmcnt(63)
	v_lshlrev_b32_e32 v168, 16, v142
	s_waitcnt lgkmcnt(0)
	v_mfma_f32_16x16x32_bf16 v[116:119], v[36:39], v[148:151], v[116:119]
	ds_read_b128 v[148:151], v203 offset:20736
	ds_read_b128 v[164:167], v203 offset:20800
	v_and_b32_e32 v169, 0xffff0000, v142
	v_lshlrev_b32_e32 v170, 16, v143
	s_waitcnt lgkmcnt(1)
	v_mfma_f32_16x16x32_bf16 v[148:151], v[40:43], v[148:151], 0
	v_and_b32_e32 v171, 0xffff0000, v143
	v_lshlrev_b32_e32 v162, 16, v67
	v_and_b32_e32 v163, 0xffff0000, v67
	s_waitcnt lgkmcnt(0)
	v_mfma_f32_16x16x32_bf16 v[148:151], v[36:39], v[164:167], v[148:151]
	v_fma_f32 v178, v160, v0, v152
	v_fma_f32 v179, v161, v0, v153
	v_lshlrev_b32_e32 v152, 16, v146
	v_and_b32_e32 v153, 0xffff0000, v146
	v_lshlrev_b32_e32 v160, 16, v147
	v_and_b32_e32 v161, 0xffff0000, v147
	s_waitcnt vmcnt(63)
	s_nop 0
	v_pk_fma_f32 v[150:151], v[62:63], v[150:151], v[170:171]
	v_pk_fma_f32 v[148:149], v[60:61], v[148:149], v[168:169]
	v_pk_fma_f32 v[162:163], v[184:185], v[0:1], v[162:163] op_sel_hi:[1,0,1]
	v_pk_fma_f32 v[164:165], v[156:157], v[0:1], v[160:161] op_sel_hi:[1,0,1]
	v_pk_fma_f32 v[180:181], v[158:159], v[0:1], v[152:153] op_sel_hi:[1,0,1]
	v_mov_b32_dpp v184, v148 row_newbcast:0 row_mask:0xf bank_mask:0xf bound_ctrl:1
	v_mov_b32_dpp v185, v148 row_newbcast:1 row_mask:0xf bank_mask:0xf bound_ctrl:1
	v_mov_b32_dpp v160, v149 row_newbcast:0 row_mask:0xf bank_mask:0xf bound_ctrl:1
	v_mov_b32_dpp v161, v149 row_newbcast:1 row_mask:0xf bank_mask:0xf bound_ctrl:1
	v_mov_b32_dpp v158, v150 row_newbcast:0 row_mask:0xf bank_mask:0xf bound_ctrl:1
	v_mov_b32_dpp v159, v150 row_newbcast:1 row_mask:0xf bank_mask:0xf bound_ctrl:1
	v_mov_b32_dpp v156, v151 row_newbcast:0 row_mask:0xf bank_mask:0xf bound_ctrl:1
	v_mov_b32_dpp v157, v151 row_newbcast:1 row_mask:0xf bank_mask:0xf bound_ctrl:1
	v_mov_b32_e32 v148, v194
	v_mov_b32_e32 v150, v196
	v_mov_b32_e32 v152, v199
	v_mov_b32_e32 v166, v198
	v_mov_b32_e32 v153, v200
	v_mov_b32_e32 v149, v195
	v_mov_b32_e32 v0, v120
	v_mov_b32_e32 v151, v197
	s_cmp_gt_u32 s25, 31
	s_cbranch_scc1 .LBB0_451
	v_cvt_pk_bf16_f32 v166, v190, v191
	v_cvt_pk_bf16_f32 v167, v192, v193
	ds_write_b64 v202, v[166:167]
	v_cvt_pk_bf16_f32 v166, v154, v155
	v_cvt_pk_bf16_f32 v167, v188, v189
	ds_write_b64 v202, v[166:167] offset:2304
	v_cvt_pk_bf16_f32 v166, v182, v183
	v_cvt_pk_bf16_f32 v167, v186, v187
	ds_write_b64 v202, v[166:167] offset:4608
	v_cvt_pk_bf16_f32 v166, v178, v179
	v_cvt_pk_bf16_f32 v167, v162, v163
	ds_write_b64 v202, v[166:167] offset:6912
	v_cvt_pk_bf16_f32 v166, v180, v181
	v_cvt_pk_bf16_f32 v167, v164, v165
	ds_write_b64 v202, v[166:167] offset:9216
	s_sub_i32 s4, s25, 17
	s_cmp_gt_u32 s4, 14
	s_mov_b64 s[10:11], -1
	s_cbranch_scc1 .LBB0_452

; __device__ __forceinline__ const char* upin(const char* p) { asm volatile("" : "+s"(p)); return p; }
; __device__ __forceinline__ char* upin(char* p) { asm volatile("" : "+s"(p)); return p; }
; template <bool GDN> __device__ __forceinline__ void scan_fin_load(const Frame& F, int b, int h, int dir, const ScanLane& L, int s, const float* PEND, ScanFin& f) {
;     const int cidx = dir ? (s < 4 ? 3 - s : 39 - s) : s; const int row0 = chunk_row0(b, cidx);
;     const char* pp = upin((const char*)PEND + (size_t)((b * 4 + h) * 36 + cidx) * 16384);
;     const char* gp = (const char*)F.Z + ((size_t)row0 * ZW + (GDN ? ZC_GZ : ZC_LO) + h * 64) * 2;
; #pragma unroll
;     for (int pr = 0; pr < 2; ++pr) { const v4u qp = ldu<v4u>(pp + pr * 1024, L.pend); f.pend[2 * pr] = (v2u){qp.x, qp.y}; f.pend[2 * pr + 1] = (v2u){qp.z, qp.w}; }
; #pragma unroll
;     for (int t = 0; t < 4; ++t) f.gz[t] = ldu<v2u>(upin(gp + (size_t)t * ZW * 2), L.gz);
; }
.LBB0_448:
	s_add_i32 s4, s1, s24
	s_add_i32 s6, s4, 1
	s_and_b64 s[4:5], s[90:91], exec
	s_cselect_b32 s4, s3, s6
	s_lshl_b32 s3, s4, 6
	s_or_b32 s5, s3, s63
	s_add_i32 s3, s3, s33
	s_cmp_lt_u32 s4, 4
	s_cselect_b32 s3, s5, s3
	s_add_i32 s92, s4, s31
	s_lshl_b64 s[6:7], s[92:93], 14
	v_readlane_b32 s10, v253, 25
	s_add_u32 s6, s22, s6
	s_mul_hi_u32 s9, s3, 0xd00
	s_mul_i32 s8, s3, 0xd00
	v_readlane_b32 s11, v253, 26
	s_addc_u32 s7, s23, s7
	s_or_b64 s[8:9], s[8:9], s[10:11]
	s_waitcnt vmcnt(0)
	s_lshl_b64 s[8:9], s[8:9], 1
	global_load_dwordx4 v[4:7], v59, s[6:7]
	global_load_dwordx4 v[8:11], v59, s[6:7] offset:1024
	s_add_u32 s6, s16, s8
	s_addc_u32 s7, s17, s9
	s_mov_b64 s[8:9], s[6:7]
	global_load_dwordx2 v[122:123], v58, s[8:9]
	s_add_u32 s8, s6, 0x1a00
	s_addc_u32 s9, s7, 0
	global_load_dwordx2 v[124:125], v58, s[8:9]
	s_add_u32 s8, s6, 0x3400
	s_addc_u32 s9, s7, 0
	s_add_u32 s6, s6, 0x4e00
	s_addc_u32 s7, s7, 0
	global_load_dwordx2 v[126:127], v58, s[8:9]
	global_load_dwordx2 v[128:129], v58, s[6:7]
	s_waitcnt vmcnt(0)
	s_cmp_lt_u32 s0, 17
	s_mov_b64 s[10:11], -1
	s_cbranch_scc0 .LBB0_434

; __device__ __forceinline__ float row16_sum(float v) { v += dppf<0xB1>(v); v += dppf<0x4E>(v); v += dppf<0x141>(v); v += dppf<0x140>(v); return v; }
; __device__ __forceinline__ float frsq(float x) { return __builtin_amdgcn_rsqf(x); }
; __device__ __forceinline__ v2u pack4(const f32x4 v) { v2u r; r.x = pk2(v[0], v[1]); r.y = pk2(v[2], v[3]); return r; }
; __device__ __forceinline__ f32x4 unpack4(const v2u w) { f32x4 r; r[0] = bflo(w.x); r[1] = bfhi(w.x); r[2] = bflo(w.y); r[3] = bfhi(w.y); return r; }
; __device__ __forceinline__ const char* upin(const char* p) { asm volatile("" : "+s"(p)); return p; }
; __device__ __forceinline__ char* upin(char* p) { asm volatile("" : "+s"(p)); return p; }
; template <bool GDN> __device__ __forceinline__ void scan_finish(const Frame& F, int b, int h, int dir, const ScanLane& L, int s, float* PEND, const f32x4 (&Oin)[4], const ScanFin& f) {
;     ...
;         f32x4 O[4]; float ss[4] = {0.f, 0.f, 0.f, 0.f};
; #pragma unroll
;         for (int t = 0; t < 4; ++t)
;             { const f32x4 pv = unpack4(f.pend[t]);
; #pragma unroll
;             for (int i = 0; i < 4; ++i) { O[t][i] = Oin[t][i] + pv[i]; ss[i] += O[t][i] * O[t][i]; } }
; #pragma unroll
;         for (int i = 0; i < 4; ++i) ss[i] = frsq(row16_sum(ss[i]) * (1.f / 64.f) + EPS);
;         char* mp = (char*)F.MIX + ((size_t)row0 * 1024 + (GDN ? 0 : 768) + h * 64) * 2;
; #pragma unroll
;         for (int i = 0; i < 4; ++i) { const f32x4 g = unpack4(f.gz[i]); f32x4 ov;
; #pragma unroll
;             for (int t = 0; t < 4; ++t) ov[t] = O[t][i] * ss[i] * g[t];
;             stu<v2u>(upin(mp + i * 2048), L.mix, pack4(ov)); }
.LBB0_469:
	s_waitcnt vmcnt(63)
	v_lshlrev_b32_e32 v53, 16, v6
	v_lshlrev_b32_e32 v52, 16, v4
	v_mov_b32_e32 v54, v24
	v_mov_b32_e32 v55, v104
	s_waitcnt vmcnt(63)
	v_lshlrev_b32_e32 v35, 16, v10
	v_lshlrev_b32_e32 v34, 16, v8
	v_mov_b32_e32 v44, v26
	v_mov_b32_e32 v45, v106
	v_pk_add_f32 v[52:53], v[54:55], v[52:53]
	v_pk_add_f32 v[34:35], v[44:45], v[34:35]
	v_pk_mul_f32 v[54:55], v[52:53], v[52:53]
	v_pk_mul_f32 v[44:45], v[34:35], v[34:35]
	v_add_f32_e32 v33, v55, v54
	v_add_f32_e32 v33, v44, v33
	v_add_f32_e32 v33, v45, v33
	s_lshl_b32 s1, s0, 6
	s_cmp_lt_i32 s0, 4
	v_add_f32_dpp v33, v33, v33 quad_perm:[1,0,3,2] row_mask:0xf bank_mask:0xf bound_ctrl:1
	s_cselect_b32 s3, s63, s33
	s_add_i32 s4, s3, s1
	v_add_f32_dpp v33, v33, v33 quad_perm:[2,3,0,1] row_mask:0xf bank_mask:0xf bound_ctrl:1
	s_ashr_i32 s5, s4, 31
	s_lshl_b64 s[4:5], s[4:5], 11
	v_add_f32_dpp v33, v33, v33 row_half_mirror row_mask:0xf bank_mask:0xf bound_ctrl:1
	s_add_u32 s1, s26, s4
	s_addc_u32 s3, s27, s5
	v_add_f32_dpp v33, v33, v33 row_mirror row_mask:0xf bank_mask:0xf bound_ctrl:1
	v_fmamk_f32 v33, v33, 0x3c800000, v231
	v_rsq_f32_e32 v44, v33
	s_waitcnt vmcnt(63)
	v_lshlrev_b32_e32 v46, 16, v123
	v_and_b32_e32 v47, 0xffff0000, v123
	v_lshlrev_b32_e32 v54, 16, v122
	v_and_b32_e32 v55, 0xffff0000, v122
	v_pk_mul_f32 v[52:53], v[52:53], v[44:45] op_sel_hi:[1,0]
	v_pk_mul_f32 v[34:35], v[34:35], v[44:45] op_sel_hi:[1,0]
	s_add_u32 s4, s1, 0x600
	v_pk_mul_f32 v[52:53], v[52:53], v[54:55]
	v_pk_mul_f32 v[34:35], v[34:35], v[46:47]
	s_addc_u32 s5, s3, 0
	v_cvt_pk_bf16_f32 v44, v52, v53
	v_cvt_pk_bf16_f32 v45, v34, v35
	v_and_b32_e32 v53, 0xffff0000, v6
	v_and_b32_e32 v52, 0xffff0000, v4
	v_mov_b32_e32 v54, v25
	v_mov_b32_e32 v55, v105
	global_store_dwordx2 v31, v[44:45], s[4:5]
	v_and_b32_e32 v35, 0xffff0000, v10
	v_and_b32_e32 v34, 0xffff0000, v8
	v_mov_b32_e32 v44, v27
	v_mov_b32_e32 v45, v107
	v_pk_add_f32 v[52:53], v[54:55], v[52:53]
	v_pk_add_f32 v[34:35], v[44:45], v[34:35]
	v_pk_mul_f32 v[54:55], v[52:53], v[52:53]
	v_pk_mul_f32 v[44:45], v[34:35], v[34:35]
	v_add_f32_e32 v33, v55, v54
	v_add_f32_e32 v33, v44, v33
	v_add_f32_e32 v33, v45, v33
	s_waitcnt vmcnt(63)
	v_lshlrev_b32_e32 v46, 16, v125
	v_and_b32_e32 v47, 0xffff0000, v125
	v_add_f32_dpp v33, v33, v33 quad_perm:[1,0,3,2] row_mask:0xf bank_mask:0xf bound_ctrl:1
	v_lshlrev_b32_e32 v54, 16, v124
	v_and_b32_e32 v55, 0xffff0000, v124
	v_add_f32_dpp v33, v33, v33 quad_perm:[2,3,0,1] row_mask:0xf bank_mask:0xf bound_ctrl:1
	s_add_u32 s4, s1, 0xe00
	s_addc_u32 s5, s3, 0
	v_add_f32_dpp v33, v33, v33 row_half_mirror row_mask:0xf bank_mask:0xf bound_ctrl:1
	s_nop 1
	v_add_f32_dpp v33, v33, v33 row_mirror row_mask:0xf bank_mask:0xf bound_ctrl:1
	v_fmamk_f32 v33, v33, 0x3c800000, v231
	v_rsq_f32_e32 v44, v33
	s_nop 0
	v_pk_mul_f32 v[52:53], v[52:53], v[44:45] op_sel_hi:[1,0]
	v_pk_mul_f32 v[34:35], v[34:35], v[44:45] op_sel_hi:[1,0]
	v_pk_mul_f32 v[52:53], v[52:53], v[54:55]
	v_pk_mul_f32 v[34:35], v[34:35], v[46:47]
	v_cvt_pk_bf16_f32 v44, v52, v53
	v_cvt_pk_bf16_f32 v45, v34, v35
	v_lshlrev_b32_e32 v53, 16, v7
	v_lshlrev_b32_e32 v52, 16, v5
	v_mov_b32_e32 v54, v20
	v_mov_b32_e32 v55, v110
	global_store_dwordx2 v31, v[44:45], s[4:5]
	v_lshlrev_b32_e32 v35, 16, v11
	v_lshlrev_b32_e32 v34, 16, v9
	v_mov_b32_e32 v44, v22
	v_mov_b32_e32 v45, v108
	v_pk_add_f32 v[52:53], v[54:55], v[52:53]
	v_pk_add_f32 v[34:35], v[44:45], v[34:35]
	v_pk_mul_f32 v[54:55], v[52:53], v[52:53]
	v_pk_mul_f32 v[44:45], v[34:35], v[34:35]
	v_add_f32_e32 v33, v55, v54
	v_add_f32_e32 v33, v44, v33
	v_add_f32_e32 v33, v45, v33
	s_waitcnt vmcnt(63)
	v_lshlrev_b32_e32 v46, 16, v127
	v_and_b32_e32 v47, 0xffff0000, v127
	v_add_f32_dpp v33, v33, v33 quad_perm:[1,0,3,2] row_mask:0xf bank_mask:0xf bound_ctrl:1
	v_lshlrev_b32_e32 v54, 16, v126
	v_and_b32_e32 v55, 0xffff0000, v126
	v_add_f32_dpp v33, v33, v33 quad_perm:[2,3,0,1] row_mask:0xf bank_mask:0xf bound_ctrl:1
	s_add_u32 s4, s1, 0x1600
	s_addc_u32 s5, s3, 0
	v_add_f32_dpp v33, v33, v33 row_half_mirror row_mask:0xf bank_mask:0xf bound_ctrl:1
	s_nop 1
	v_add_f32_dpp v33, v33, v33 row_mirror row_mask:0xf bank_mask:0xf bound_ctrl:1
	v_fmamk_f32 v33, v33, 0x3c800000, v231
	v_rsq_f32_e32 v44, v33
	s_nop 0
	v_pk_mul_f32 v[52:53], v[52:53], v[44:45] op_sel_hi:[1,0]
	v_pk_mul_f32 v[34:35], v[34:35], v[44:45] op_sel_hi:[1,0]
	v_pk_mul_f32 v[52:53], v[52:53], v[54:55]
	v_pk_mul_f32 v[34:35], v[34:35], v[46:47]
	v_cvt_pk_bf16_f32 v44, v52, v53
	v_cvt_pk_bf16_f32 v45, v34, v35
	v_and_b32_e32 v53, 0xffff0000, v7
	v_and_b32_e32 v52, 0xffff0000, v5
	v_mov_b32_e32 v54, v21
	v_mov_b32_e32 v55, v111
	global_store_dwordx2 v31, v[44:45], s[4:5]
	v_and_b32_e32 v35, 0xffff0000, v11
	v_and_b32_e32 v34, 0xffff0000, v9
	v_mov_b32_e32 v44, v23
	v_mov_b32_e32 v45, v109
	v_pk_add_f32 v[52:53], v[54:55], v[52:53]
	v_pk_add_f32 v[34:35], v[44:45], v[34:35]
	v_pk_mul_f32 v[54:55], v[52:53], v[52:53]
	v_pk_mul_f32 v[44:45], v[34:35], v[34:35]
	v_add_f32_e32 v33, v55, v54
	v_add_f32_e32 v33, v44, v33
	v_add_f32_e32 v33, v45, v33
	s_waitcnt vmcnt(63)
	v_lshlrev_b32_e32 v46, 16, v129
	v_and_b32_e32 v47, 0xffff0000, v129
	v_add_f32_dpp v33, v33, v33 quad_perm:[1,0,3,2] row_mask:0xf bank_mask:0xf bound_ctrl:1
	v_lshlrev_b32_e32 v54, 16, v128
	v_and_b32_e32 v55, 0xffff0000, v128
	v_add_f32_dpp v33, v33, v33 quad_perm:[2,3,0,1] row_mask:0xf bank_mask:0xf bound_ctrl:1
	s_add_u32 s4, s1, 0x1e00
	s_addc_u32 s5, s3, 0
	v_add_f32_dpp v33, v33, v33 row_half_mirror row_mask:0xf bank_mask:0xf bound_ctrl:1
	s_nop 1
	v_add_f32_dpp v33, v33, v33 row_mirror row_mask:0xf bank_mask:0xf bound_ctrl:1
	v_fmamk_f32 v33, v33, 0x3c800000, v231
	v_rsq_f32_e32 v44, v33
	s_nop 0
	v_pk_mul_f32 v[52:53], v[52:53], v[44:45] op_sel_hi:[1,0]
	v_pk_mul_f32 v[34:35], v[34:35], v[44:45] op_sel_hi:[1,0]
	v_pk_mul_f32 v[52:53], v[52:53], v[54:55]
	v_pk_mul_f32 v[34:35], v[34:35], v[46:47]
	v_cvt_pk_bf16_f32 v44, v52, v53
	v_cvt_pk_bf16_f32 v45, v34, v35
	global_store_dwordx2 v31, v[44:45], s[4:5]
	s_cbranch_execz .LBB0_474

; __device__ __forceinline__ const char* upin(const char* p) { asm volatile("" : "+s"(p)); return p; }
; __device__ __forceinline__ char* upin(char* p) { asm volatile("" : "+s"(p)); return p; }
; template <bool GDN> __device__ __forceinline__ void scan_fin_load(const Frame& F, int b, int h, int dir, const ScanLane& L, int s, const float* PEND, ScanFin& f) {
;     const int cidx = dir ? (s < 4 ? 3 - s : 39 - s) : s; const int row0 = chunk_row0(b, cidx);
;     const char* pp = upin((const char*)PEND + (size_t)((b * 4 + h) * 36 + cidx) * 16384);
;     const char* gp = (const char*)F.Z + ((size_t)row0 * ZW + (GDN ? ZC_GZ : ZC_LO) + h * 64) * 2;
; #pragma unroll
;     for (int pr = 0; pr < 2; ++pr) { const v4u qp = ldu<v4u>(pp + pr * 1024, L.pend); f.pend[2 * pr] = (v2u){qp.x, qp.y}; f.pend[2 * pr + 1] = (v2u){qp.z, qp.w}; }
; #pragma unroll
;     for (int t = 0; t < 4; ++t) f.gz[t] = ldu<v2u>(upin(gp + (size_t)t * ZW * 2), L.gz);
; }
.LBB0_472:
	s_add_i32 s4, s24, 38
	s_and_b64 s[0:1], s[90:91], exec
	s_cselect_b32 s0, s3, s4
	s_lshl_b32 s1, s0, 6
	s_add_i32 s92, s0, s31
	s_add_i32 s1, s1, s33
	s_lshl_b64 s[4:5], s[92:93], 14
	v_readlane_b32 s8, v253, 25
	s_add_u32 s4, s22, s4
	s_mul_hi_u32 s7, s1, 0xd00
	s_mul_i32 s6, s1, 0xd00
	v_readlane_b32 s9, v253, 26
	s_addc_u32 s5, s23, s5
	s_or_b64 s[6:7], s[6:7], s[8:9]
	s_waitcnt vmcnt(0)
	s_lshl_b64 s[6:7], s[6:7], 1
	global_load_dwordx4 v[4:7], v30, s[4:5]
	global_load_dwordx4 v[8:11], v30, s[4:5] offset:1024
	s_add_u32 s4, s16, s6
	s_addc_u32 s5, s17, s7
	s_mov_b64 s[6:7], s[4:5]
	global_load_dwordx2 v[122:123], v29, s[6:7]
	s_add_u32 s6, s4, 0x1a00
	s_addc_u32 s7, s5, 0
	global_load_dwordx2 v[124:125], v29, s[6:7]
	s_add_u32 s6, s4, 0x3400
	s_addc_u32 s7, s5, 0
	s_add_u32 s4, s4, 0x4e00
	s_addc_u32 s5, s5, 0
	global_load_dwordx2 v[126:127], v29, s[6:7]
	global_load_dwordx2 v[128:129], v29, s[4:5]
	s_waitcnt vmcnt(0)
	s_cmp_lt_u32 s25, 16
	s_mov_b64 s[10:11], -1
	s_cbranch_scc0 .LBB0_469

; #define LAS __attribute__((address_space(3)))
; __device__ __forceinline__ f32x4 unpack4(const v2u w) { f32x4 r; r[0] = bflo(w.x); r[1] = bfhi(w.x); r[2] = bflo(w.y); r[3] = bfhi(w.y); return r; }
; template <class T> __device__ __forceinline__ T ldun(const void* ubase, unsigned boff) { return __builtin_nontemporal_load((const GAS T*)((const GAS char*)ubase + boff)); }
; __device__ __forceinline__ const char* upin(const char* p) { asm volatile("" : "+s"(p)); return p; }
; __device__ __forceinline__ char* upin(char* p) { asm volatile("" : "+s"(p)); return p; }
; template <bool GDN, int NT> __device__ __forceinline__ void scan_load(const Frame& F, int b, int h, int dir, const ScanLane& L, int s, ScanOps<NT>& o) {
;     ...
;         const char* base = (const char*)F.PG + (size_t)ud * 32768;
;         const char* bM = upin(base); const char* bB = upin(base + 8192); const char* bQ = upin(base + 16384); const char* bO = upin(base + 24576);
; #pragma unroll
;         for (int ks = 0; ks < 2; ++ks) { o.Mf[ks] = ldun<bf16x8>(bM + ks * 1024, L.o16); o.Qf[ks] = ldun<bf16x8>(bQ + ks * 1024, L.o16); }
; #pragma unroll
;         for (int pr = 0; pr < 2; ++pr) { const v4u qb = ldun<v4u>(bB + pr * 1024, L.o16p), qo = ldun<v4u>(bO + pr * 1024, L.o16p);
;             o.bv[2 * pr] = (v2u){qb.x, qb.y}; o.bv[2 * pr + 1] = (v2u){qb.z, qb.w}; o.ov[2 * pr] = (v2u){qo.x, qo.y}; o.ov[2 * pr + 1] = (v2u){qo.z, qo.w}; }
;         o.wi = (f32x4){1.f, 1.f, 1.f, 1.f};
;     ...
;     for (int t = 0; t < NT; ++t) {
;         const LAS bf16_t* sp2 = Sb + (16 * t + lr) * 72 + 8 * lq;
;         const bf16x8 s0 = *(const LAS bf16x8*)sp2, s1 = *(const LAS bf16x8*)(sp2 + 32);
;         const f32x4 bv = unpack4(use.bv[t]), ov = unpack4(use.ov[t]);
;         if (GDN) {
;             f32x4 o = ov, sn = S[t] * gl + bv;
;             o = __builtin_amdgcn_mfma_f32_16x16x32_bf16(use.Qf[0], s0, o, 0, 0, 0); o = __builtin_amdgcn_mfma_f32_16x16x32_bf16(use.Qf[1], s1, o, 0, 0, 0);
;             sn = __builtin_amdgcn_mfma_f32_16x16x32_bf16(use.Mf[0], s0, sn, 0, 0, 0); sn = __builtin_amdgcn_mfma_f32_16x16x32_bf16(use.Mf[1], s1, sn, 0, 0, 0);
;             S[t] = sn; O[t] = o;
.LBB0_481:
	s_add_i32 s0, s23, 5
	s_min_u32 s3, s0, 33
	s_add_i32 s6, s3, 2
	s_sub_i32 s3, 37, s3
	s_and_b64 s[4:5], s[90:91], exec
	s_cselect_b32 s3, s6, s3
	s_add_i32 s3, s3, s30
	s_lshl_b32 s3, s3, 1
	s_add_i32 s4, s3, s68
	s_ashr_i32 s5, s4, 31
	s_lshl_b64 s[4:5], s[4:5], 15
	s_add_u32 s4, s35, s4
	s_addc_u32 s5, s43, s5
	s_add_u32 s8, s4, 0x2000
	s_addc_u32 s9, s5, 0
	s_add_u32 s10, s4, 0x4000
	s_addc_u32 s11, s5, 0
	s_mov_b64 s[6:7], s[4:5]
	s_add_u32 s4, s4, 0x6000
	s_addc_u32 s5, s5, 0
	global_load_dwordx4 v[70:73], v18, s[8:9] nt
	global_load_dwordx4 v[66:69], v18, s[4:5] nt
	global_load_dwordx4 v[22:25], v18, s[8:9] offset:1024 nt
	s_nop 0
	global_load_dwordx4 v[18:21], v18, s[4:5] offset:1024 nt
	s_add_i32 s3, s22, 37
	s_and_b64 s[4:5], s[90:91], exec
	s_cselect_b32 s0, s0, s3
	s_lshl_b32 s0, s0, 3
	s_add_i32 s0, s34, s0
	v_lshl_add_u64 v[146:147], s[6:7], 0, v[0:1]
	v_lshl_add_u64 v[148:149], s[10:11], 0, v[0:1]
	v_mov_b32_e32 v0, s0
	ds_read_b32 v0, v0 offset:46080
	ds_read_b128 v[98:101], v200 offset:11520
	ds_read_b128 v[102:105], v200 offset:11584
	s_waitcnt vmcnt(63)
	v_lshlrev_b32_e32 v110, 16, v94
	v_and_b32_e32 v111, 0xffff0000, v94
	v_lshlrev_b32_e32 v112, 16, v95
	v_and_b32_e32 v113, 0xffff0000, v95
	s_waitcnt vmcnt(63)
	v_lshlrev_b32_e32 v106, 16, v86
	v_and_b32_e32 v107, 0xffff0000, v86
	v_lshlrev_b32_e32 v108, 16, v87
	v_and_b32_e32 v109, 0xffff0000, v87
	s_waitcnt lgkmcnt(2)
	v_pk_fma_f32 v[112:113], v[128:129], v[0:1], v[112:113] op_sel_hi:[1,0,1]
	v_pk_fma_f32 v[110:111], v[126:127], v[0:1], v[110:111] op_sel_hi:[1,0,1]
	s_waitcnt lgkmcnt(1)
	v_mfma_f32_16x16x32_bf16 v[106:109], v[46:49], v[98:101], v[106:109]
	s_mov_b64 s[6:7], 0x400
	v_lshl_add_u64 v[150:151], v[146:147], 0, s[6:7]
	v_lshl_add_u64 v[152:153], v[148:149], 0, s[6:7]
	v_mfma_f32_16x16x32_bf16 v[98:101], v[30:33], v[98:101], v[110:113]
	s_add_i32 s3, s22, -6
	s_mov_b64 s[20:21], 0
	s_waitcnt lgkmcnt(0)
	v_mfma_f32_16x16x32_bf16 v[130:133], v[34:37], v[102:105], v[106:109]
	v_lshlrev_b32_e32 v110, 16, v96
	v_and_b32_e32 v111, 0xffff0000, v96
	v_lshlrev_b32_e32 v112, 16, v97
	v_mfma_f32_16x16x32_bf16 v[126:129], v[26:29], v[102:105], v[98:101]
	s_nop 2
	ds_read_b128 v[98:101], v200 offset:13824
	ds_read_b128 v[102:105], v200 offset:13888
	v_and_b32_e32 v113, 0xffff0000, v97
	v_lshlrev_b32_e32 v106, 16, v88
	v_and_b32_e32 v107, 0xffff0000, v88
	v_lshlrev_b32_e32 v108, 16, v89
	v_and_b32_e32 v109, 0xffff0000, v89
	v_pk_fma_f32 v[112:113], v[124:125], v[0:1], v[112:113] op_sel_hi:[1,0,1]
	v_pk_fma_f32 v[110:111], v[122:123], v[0:1], v[110:111] op_sel_hi:[1,0,1]
	s_waitcnt lgkmcnt(1)
	v_mfma_f32_16x16x32_bf16 v[106:109], v[46:49], v[98:101], v[106:109]
	v_mfma_f32_16x16x32_bf16 v[98:101], v[30:33], v[98:101], v[110:113]
	s_waitcnt lgkmcnt(0)
	v_mfma_f32_16x16x32_bf16 v[134:137], v[34:37], v[102:105], v[106:109]
	s_waitcnt vmcnt(63)
	v_lshlrev_b32_e32 v110, 16, v78
	v_and_b32_e32 v111, 0xffff0000, v78
	v_lshlrev_b32_e32 v112, 16, v79
	v_mfma_f32_16x16x32_bf16 v[122:125], v[26:29], v[102:105], v[98:101]
	s_nop 2
	ds_read_b128 v[98:101], v200 offset:16128
	ds_read_b128 v[102:105], v200 offset:16192
	v_and_b32_e32 v113, 0xffff0000, v79
	s_waitcnt vmcnt(63)
	v_lshlrev_b32_e32 v106, 16, v74
	v_and_b32_e32 v107, 0xffff0000, v74
	v_lshlrev_b32_e32 v108, 16, v75
	v_and_b32_e32 v109, 0xffff0000, v75
	v_pk_fma_f32 v[112:113], v[116:117], v[0:1], v[112:113] op_sel_hi:[1,0,1]
	v_pk_fma_f32 v[110:111], v[114:115], v[0:1], v[110:111] op_sel_hi:[1,0,1]
	s_waitcnt lgkmcnt(1)
	v_mfma_f32_16x16x32_bf16 v[106:109], v[46:49], v[98:101], v[106:109]
	v_mfma_f32_16x16x32_bf16 v[98:101], v[30:33], v[98:101], v[110:113]
	s_waitcnt lgkmcnt(0)
	v_mfma_f32_16x16x32_bf16 v[138:141], v[34:37], v[102:105], v[106:109]
	s_nop 0
	v_lshlrev_b32_e32 v110, 16, v80
	v_and_b32_e32 v111, 0xffff0000, v80
	v_lshlrev_b32_e32 v112, 16, v81
	v_mfma_f32_16x16x32_bf16 v[114:117], v[26:29], v[102:105], v[98:101]
	s_nop 2
	ds_read_b128 v[98:101], v200 offset:18432
	ds_read_b128 v[102:105], v200 offset:18496
	v_and_b32_e32 v113, 0xffff0000, v81
	v_lshlrev_b32_e32 v106, 16, v76
	v_and_b32_e32 v107, 0xffff0000, v76
	v_lshlrev_b32_e32 v108, 16, v77
	v_and_b32_e32 v109, 0xffff0000, v77
	v_pk_fma_f32 v[112:113], v[120:121], v[0:1], v[112:113] op_sel_hi:[1,0,1]
	v_pk_fma_f32 v[110:111], v[118:119], v[0:1], v[110:111] op_sel_hi:[1,0,1]
	s_waitcnt lgkmcnt(1)
	v_mfma_f32_16x16x32_bf16 v[106:109], v[46:49], v[98:101], v[106:109]
	v_mfma_f32_16x16x32_bf16 v[98:101], v[30:33], v[98:101], v[110:113]
	s_waitcnt lgkmcnt(0)
	v_mfma_f32_16x16x32_bf16 v[142:145], v[34:37], v[102:105], v[106:109]
	v_mfma_f32_16x16x32_bf16 v[118:121], v[26:29], v[102:105], v[98:101]

; __device__ __forceinline__ float row16_sum(float v) { v += dppf<0xB1>(v); v += dppf<0x4E>(v); v += dppf<0x141>(v); v += dppf<0x140>(v); return v; }
; __device__ __forceinline__ float frsq(float x) { return __builtin_amdgcn_rsqf(x); }
; __device__ __forceinline__ v2u pack4(const f32x4 v) { v2u r; r.x = pk2(v[0], v[1]); r.y = pk2(v[2], v[3]); return r; }
; __device__ __forceinline__ f32x4 unpack4(const v2u w) { f32x4 r; r[0] = bflo(w.x); r[1] = bfhi(w.x); r[2] = bflo(w.y); r[3] = bfhi(w.y); return r; }
; __device__ __forceinline__ const char* upin(const char* p) { asm volatile("" : "+s"(p)); return p; }
; __device__ __forceinline__ char* upin(char* p) { asm volatile("" : "+s"(p)); return p; }
; template <bool GDN> __device__ __forceinline__ void scan_finish(const Frame& F, int b, int h, int dir, const ScanLane& L, int s, float* PEND, const f32x4 (&Oin)[4], const ScanFin& f) {
;     ...
;         f32x4 O[4]; float ss[4] = {0.f, 0.f, 0.f, 0.f};
; #pragma unroll
;         for (int t = 0; t < 4; ++t)
;             { const f32x4 pv = unpack4(f.pend[t]);
; #pragma unroll
;             for (int i = 0; i < 4; ++i) { O[t][i] = Oin[t][i] + pv[i]; ss[i] += O[t][i] * O[t][i]; } }
; #pragma unroll
;         for (int i = 0; i < 4; ++i) ss[i] = frsq(row16_sum(ss[i]) * (1.f / 64.f) + EPS);
;         char* mp = (char*)F.MIX + ((size_t)row0 * 1024 + (GDN ? 0 : 768) + h * 64) * 2;
; #pragma unroll
;         for (int i = 0; i < 4; ++i) { const f32x4 g = unpack4(f.gz[i]); f32x4 ov;
; #pragma unroll
;             for (int t = 0; t < 4; ++t) ov[t] = O[t][i] * ss[i] * g[t];
;             stu<v2u>(upin(mp + i * 2048), L.mix, pack4(ov)); }
;     ...
;     if (s == 21 || s == 3) asm volatile("s_waitcnt vmcnt(0)" ::: "memory");
;     else if (scan_needfin(s - 1)) { if (GDN) asm volatile("s_waitcnt vmcnt(14)" ::: "memory"); else asm volatile("s_waitcnt vmcnt(15)" ::: "memory"); }
;     else { if (GDN) asm volatile("s_waitcnt vmcnt(8)" ::: "memory"); else asm volatile("s_waitcnt vmcnt(9)" ::: "memory"); }
;     __syncthreads();
;     if (s > 0) {
;         const int sp = s - 1;
;         if (sp == 20 || sp == 2) { asm volatile("s_waitcnt vmcnt(0)" ::: "memory"); scan_fin_load<GDN>(F, b, h, dir, L, sp, PEND, fin); }
;         if (!nofin) scan_finish<GDN>(F, b, h, dir, L, sp, PEND, Oprev, fin);
;     }
.LBB0_486:
	s_waitcnt vmcnt(18)
.LBB0_487:
	s_add_i32 s0, s23, -1
	s_cmp_eq_u32 s23, 0
	s_cselect_b64 s[10:11], -1, 0
	s_and_b64 vcc, exec, s[10:11]
	s_waitcnt lgkmcnt(0)
	s_barrier
	s_cbranch_vccnz .LBB0_492
	s_add_i32 s1, s22, 43
	s_and_b64 s[4:5], s[90:91], exec
	s_cselect_b32 s1, s0, s1
	s_cmp_lt_u32 s23, 5
	s_cselect_b32 s3, 2, 20
	s_cmp_lt_u32 s0, s3
	s_mov_b64 s[12:13], -1
	s_cbranch_scc1 .LBB0_490
	s_waitcnt vmcnt(63)
	v_lshlrev_b32_e32 v169, 16, v12
	v_lshlrev_b32_e32 v168, 16, v10
	v_mov_b32_e32 v170, v130
	v_mov_b32_e32 v171, v134
	s_waitcnt vmcnt(63)
	v_lshlrev_b32_e32 v151, 16, v16
	v_lshlrev_b32_e32 v150, 16, v14
	v_mov_b32_e32 v152, v138
	v_mov_b32_e32 v153, v142
	v_pk_add_f32 v[168:169], v[170:171], v[168:169]
	v_pk_add_f32 v[150:151], v[152:153], v[150:151]
	v_pk_mul_f32 v[170:171], v[168:169], v[168:169]
	v_pk_mul_f32 v[152:153], v[150:151], v[150:151]
	v_add_f32_e32 v167, v171, v170
	v_add_f32_e32 v152, v152, v167
	v_add_f32_e32 v152, v153, v152
	s_cmp_lt_i32 s1, 4
	s_cselect_b32 s3, s25, s24
	v_add_f32_dpp v152, v152, v152 quad_perm:[1,0,3,2] row_mask:0xf bank_mask:0xf bound_ctrl:1
	s_lshl_b32 s4, s1, 6
	s_add_i32 s4, s3, s4
	v_add_f32_dpp v152, v152, v152 quad_perm:[2,3,0,1] row_mask:0xf bank_mask:0xf bound_ctrl:1
	s_ashr_i32 s5, s4, 31
	s_lshl_b64 s[4:5], s[4:5], 11
	v_add_f32_dpp v152, v152, v152 row_half_mirror row_mask:0xf bank_mask:0xf bound_ctrl:1
	s_add_u32 s18, s26, s4
	s_waitcnt vmcnt(63)
	v_lshlrev_b32_e32 v166, 16, v165
	v_add_f32_dpp v152, v152, v152 row_mirror row_mask:0xf bank_mask:0xf bound_ctrl:1
	v_fmamk_f32 v152, v152, 0x3c800000, v231
	v_rsq_f32_e32 v152, v152
	v_and_b32_e32 v167, 0xffff0000, v165
	v_lshlrev_b32_e32 v170, 16, v164
	v_and_b32_e32 v171, 0xffff0000, v164
	v_pk_mul_f32 v[168:169], v[168:169], v[152:153] op_sel_hi:[1,0]
	v_pk_mul_f32 v[150:151], v[150:151], v[152:153] op_sel_hi:[1,0]
	s_addc_u32 s19, s27, s5
	v_pk_mul_f32 v[168:169], v[168:169], v[170:171]
	v_pk_mul_f32 v[150:151], v[150:151], v[166:167]
	s_mov_b64 s[4:5], s[18:19]
	v_cvt_pk_bf16_f32 v152, v168, v169
	v_cvt_pk_bf16_f32 v153, v150, v151
	v_and_b32_e32 v169, 0xffff0000, v12
	v_and_b32_e32 v168, 0xffff0000, v10
	v_mov_b32_e32 v170, v131
	v_mov_b32_e32 v171, v135
	global_store_dwordx2 v149, v[152:153], s[4:5]
	v_and_b32_e32 v151, 0xffff0000, v16
	v_and_b32_e32 v150, 0xffff0000, v14
	v_mov_b32_e32 v152, v139
	v_mov_b32_e32 v153, v143
	v_pk_add_f32 v[168:169], v[170:171], v[168:169]
	v_pk_add_f32 v[150:151], v[152:153], v[150:151]
	v_pk_mul_f32 v[170:171], v[168:169], v[168:169]
	v_pk_mul_f32 v[152:153], v[150:151], v[150:151]
	v_add_f32_e32 v167, v171, v170
	v_add_f32_e32 v152, v152, v167
	v_add_f32_e32 v152, v153, v152
	s_waitcnt vmcnt(63)
	v_lshlrev_b32_e32 v166, 16, v179
	v_and_b32_e32 v167, 0xffff0000, v179
	v_add_f32_dpp v152, v152, v152 quad_perm:[1,0,3,2] row_mask:0xf bank_mask:0xf bound_ctrl:1
	v_lshlrev_b32_e32 v170, 16, v178
	v_and_b32_e32 v171, 0xffff0000, v178
	v_add_f32_dpp v152, v152, v152 quad_perm:[2,3,0,1] row_mask:0xf bank_mask:0xf bound_ctrl:1
	s_add_u32 s4, s18, 0x800
	s_addc_u32 s5, s19, 0
	v_add_f32_dpp v152, v152, v152 row_half_mirror row_mask:0xf bank_mask:0xf bound_ctrl:1
	s_mov_b64 s[12:13], 0
	s_nop 0
	v_add_f32_dpp v152, v152, v152 row_mirror row_mask:0xf bank_mask:0xf bound_ctrl:1
	v_fmamk_f32 v152, v152, 0x3c800000, v231
	v_rsq_f32_e32 v152, v152
	s_nop 0
	v_pk_mul_f32 v[168:169], v[168:169], v[152:153] op_sel_hi:[1,0]
	v_pk_mul_f32 v[150:151], v[150:151], v[152:153] op_sel_hi:[1,0]
	v_pk_mul_f32 v[168:169], v[168:169], v[170:171]
	v_pk_mul_f32 v[150:151], v[150:151], v[166:167]
	v_cvt_pk_bf16_f32 v152, v168, v169
	v_cvt_pk_bf16_f32 v153, v150, v151
	v_lshlrev_b32_e32 v169, 16, v13
	v_lshlrev_b32_e32 v168, 16, v11
	v_mov_b32_e32 v170, v132
	v_mov_b32_e32 v171, v136
	global_store_dwordx2 v149, v[152:153], s[4:5]
	v_lshlrev_b32_e32 v151, 16, v17
	v_lshlrev_b32_e32 v150, 16, v15
	v_mov_b32_e32 v152, v140
	v_mov_b32_e32 v153, v144
	v_pk_add_f32 v[168:169], v[170:171], v[168:169]
	v_pk_add_f32 v[150:151], v[152:153], v[150:151]
	v_pk_mul_f32 v[170:171], v[168:169], v[168:169]
	v_pk_mul_f32 v[152:153], v[150:151], v[150:151]
	v_add_f32_e32 v167, v171, v170
	v_add_f32_e32 v152, v152, v167
	v_add_f32_e32 v152, v153, v152
	s_waitcnt vmcnt(63)
	v_lshlrev_b32_e32 v166, 16, v181
	v_and_b32_e32 v167, 0xffff0000, v181
	v_add_f32_dpp v152, v152, v152 quad_perm:[1,0,3,2] row_mask:0xf bank_mask:0xf bound_ctrl:1
	v_lshlrev_b32_e32 v170, 16, v180
	v_and_b32_e32 v171, 0xffff0000, v180
	v_add_f32_dpp v152, v152, v152 quad_perm:[2,3,0,1] row_mask:0xf bank_mask:0xf bound_ctrl:1
	s_add_u32 s4, s18, 0x1000
	s_addc_u32 s5, s19, 0
	v_add_f32_dpp v152, v152, v152 row_half_mirror row_mask:0xf bank_mask:0xf bound_ctrl:1
	s_nop 1
	v_add_f32_dpp v152, v152, v152 row_mirror row_mask:0xf bank_mask:0xf bound_ctrl:1
	v_fmamk_f32 v152, v152, 0x3c800000, v231
	v_rsq_f32_e32 v152, v152
	s_nop 0
	v_pk_mul_f32 v[168:169], v[168:169], v[152:153] op_sel_hi:[1,0]
	v_pk_mul_f32 v[150:151], v[150:151], v[152:153] op_sel_hi:[1,0]
	v_pk_mul_f32 v[168:169], v[168:169], v[170:171]
	v_pk_mul_f32 v[150:151], v[150:151], v[166:167]
	v_cvt_pk_bf16_f32 v152, v168, v169
	v_cvt_pk_bf16_f32 v153, v150, v151
	v_and_b32_e32 v169, 0xffff0000, v13
	v_and_b32_e32 v168, 0xffff0000, v11
	v_mov_b32_e32 v170, v133
	v_mov_b32_e32 v171, v137
	global_store_dwordx2 v149, v[152:153], s[4:5]
	v_and_b32_e32 v151, 0xffff0000, v17
	v_and_b32_e32 v150, 0xffff0000, v15
	v_mov_b32_e32 v152, v141
	v_mov_b32_e32 v153, v145
	v_pk_add_f32 v[168:169], v[170:171], v[168:169]
	v_pk_add_f32 v[150:151], v[152:153], v[150:151]
	v_pk_mul_f32 v[170:171], v[168:169], v[168:169]
	v_pk_mul_f32 v[152:153], v[150:151], v[150:151]
	v_add_f32_e32 v167, v171, v170
	v_add_f32_e32 v152, v152, v167
	v_add_f32_e32 v152, v153, v152
	s_waitcnt vmcnt(63)
	v_lshlrev_b32_e32 v166, 16, v183
	v_and_b32_e32 v167, 0xffff0000, v183
	v_add_f32_dpp v152, v152, v152 quad_perm:[1,0,3,2] row_mask:0xf bank_mask:0xf bound_ctrl:1
	v_lshlrev_b32_e32 v170, 16, v182
	v_and_b32_e32 v171, 0xffff0000, v182
	v_add_f32_dpp v152, v152, v152 quad_perm:[2,3,0,1] row_mask:0xf bank_mask:0xf bound_ctrl:1
	s_add_u32 s4, s18, 0x1800
	s_addc_u32 s5, s19, 0
	v_add_f32_dpp v152, v152, v152 row_half_mirror row_mask:0xf bank_mask:0xf bound_ctrl:1
	s_nop 1
	v_add_f32_dpp v152, v152, v152 row_mirror row_mask:0xf bank_mask:0xf bound_ctrl:1
	v_fmamk_f32 v152, v152, 0x3c800000, v231
	v_rsq_f32_e32 v152, v152
	s_nop 0
	v_pk_mul_f32 v[168:169], v[168:169], v[152:153] op_sel_hi:[1,0]
	v_pk_mul_f32 v[150:151], v[150:151], v[152:153] op_sel_hi:[1,0]
	v_pk_mul_f32 v[168:169], v[168:169], v[170:171]
	v_pk_mul_f32 v[150:151], v[150:151], v[166:167]
	v_cvt_pk_bf16_f32 v152, v168, v169
	v_cvt_pk_bf16_f32 v153, v150, v151
	global_store_dwordx2 v149, v[152:153], s[4:5]

; #define LAS __attribute__((address_space(3)))
; __device__ __forceinline__ v2u pack4(const f32x4 v) { v2u r; r.x = pk2(v[0], v[1]); r.y = pk2(v[2], v[3]); return r; }
; __device__ __forceinline__ f32x4 unpack4(const v2u w) { f32x4 r; r[0] = bflo(w.x); r[1] = bfhi(w.x); r[2] = bflo(w.y); r[3] = bfhi(w.y); return r; }
; template <class T> __device__ __forceinline__ T ldun(const void* ubase, unsigned boff) { return __builtin_nontemporal_load((const GAS T*)((const GAS char*)ubase + boff)); }
; __device__ __forceinline__ const char* upin(const char* p) { asm volatile("" : "+s"(p)); return p; }
; template <bool GDN, int NT> __device__ __forceinline__ void scan_load(const Frame& F, int b, int h, int dir, const ScanLane& L, int s, ScanOps<NT>& o) {
;     ...
;         const char* base = (const char*)F.PG + (size_t)ud * 32768;
;         const char* bM = upin(base); const char* bB = upin(base + 8192); const char* bQ = upin(base + 16384); const char* bO = upin(base + 24576);
; #pragma unroll
;         for (int ks = 0; ks < 2; ++ks) { o.Mf[ks] = ldun<bf16x8>(bM + ks * 1024, L.o16); o.Qf[ks] = ldun<bf16x8>(bQ + ks * 1024, L.o16); }
; #pragma unroll
;         for (int pr = 0; pr < 2; ++pr) { const v4u qb = ldun<v4u>(bB + pr * 1024, L.o16p), qo = ldun<v4u>(bO + pr * 1024, L.o16p);
;             o.bv[2 * pr] = (v2u){qb.x, qb.y}; o.bv[2 * pr + 1] = (v2u){qb.z, qb.w}; o.ov[2 * pr] = (v2u){qo.x, qo.y}; o.ov[2 * pr + 1] = (v2u){qo.z, qo.w}; }
;         o.wi = (f32x4){1.f, 1.f, 1.f, 1.f};
;     ...
;     if (s < 36) {
; #pragma unroll
;         for (int t = 0; t < NT; ++t) *(LAS v2u*)(Sb + (16 * t + lr) * 72 + 16 * wq + 4 * lq) = pack4(S[t]); }
;     ...
;     for (int t = 0; t < NT; ++t) {
;         const LAS bf16_t* sp2 = Sb + (16 * t + lr) * 72 + 8 * lq;
;         const bf16x8 s0 = *(const LAS bf16x8*)sp2, s1 = *(const LAS bf16x8*)(sp2 + 32);
;         const f32x4 bv = unpack4(use.bv[t]), ov = unpack4(use.ov[t]);
;         if (GDN) {
;             f32x4 o = ov, sn = S[t] * gl + bv;
;             o = __builtin_amdgcn_mfma_f32_16x16x32_bf16(use.Qf[0], s0, o, 0, 0, 0); o = __builtin_amdgcn_mfma_f32_16x16x32_bf16(use.Qf[1], s1, o, 0, 0, 0);
;             sn = __builtin_amdgcn_mfma_f32_16x16x32_bf16(use.Mf[0], s0, sn, 0, 0, 0); sn = __builtin_amdgcn_mfma_f32_16x16x32_bf16(use.Mf[1], s1, sn, 0, 0, 0);
;             S[t] = sn; O[t] = o;
.LBB0_496:
	s_min_u32 s1, s23, 33
	s_add_i32 s1, s1, 2
	s_and_b64 s[4:5], exec, s[10:11]
	s_cselect_b32 s3, 3, 39
	s_sub_i32 s3, s3, s1
	s_and_b64 s[4:5], s[90:91], exec
	s_cselect_b32 s1, s1, s3
	s_add_i32 s1, s1, s30
	s_lshl_b32 s1, s1, 1
	s_add_i32 s4, s1, s68
	s_ashr_i32 s5, s4, 31
	s_lshl_b64 s[4:5], s[4:5], 15
	s_add_u32 s4, s35, s4
	s_addc_u32 s5, s43, s5
	s_add_u32 s8, s4, 0x2000
	s_addc_u32 s9, s5, 0
	s_add_u32 s12, s4, 0x4000
	s_addc_u32 s13, s5, 0
	s_mov_b64 s[6:7], s[4:5]
	s_add_u32 s4, s4, 0x6000
	s_addc_u32 s5, s5, 0
	global_load_dwordx4 v[30:33], v146, s[6:7] nt
	global_load_dwordx4 v[46:49], v146, s[12:13] nt
	global_load_dwordx4 v[26:29], v146, s[6:7] offset:1024 nt
	global_load_dwordx4 v[34:37], v146, s[12:13] offset:1024 nt
	global_load_dwordx4 v[94:97], v0, s[8:9] nt
	global_load_dwordx4 v[86:89], v0, s[4:5] nt
	global_load_dwordx4 v[78:81], v0, s[8:9] offset:1024 nt
	global_load_dwordx4 v[74:77], v0, s[4:5] offset:1024 nt
	s_cmp_gt_u32 s23, 3
	s_cselect_b32 s1, 39, 3
	s_add_i32 s1, s1, s22
	s_add_i32 s1, s1, 3
	s_and_b64 s[4:5], s[90:91], exec
	s_cselect_b32 s1, s23, s1
	s_lshl_b32 s1, s1, 3
	s_add_i32 s1, s34, s1
	v_mov_b32_e32 v0, s1
	ds_read_b32 v0, v0 offset:46080
	v_add_u32_e32 v146, v198, v155
	ds_read_b128 v[134:137], v146
	ds_read_b128 v[138:141], v146 offset:64
	s_waitcnt vmcnt(63)
	v_lshlrev_b32_e32 v142, 16, v90
	v_and_b32_e32 v143, 0xffff0000, v90
	v_lshlrev_b32_e32 v90, 16, v91
	v_and_b32_e32 v91, 0xffff0000, v91
	s_waitcnt vmcnt(63)
	v_lshlrev_b32_e32 v130, 16, v82
	v_and_b32_e32 v131, 0xffff0000, v82
	v_lshlrev_b32_e32 v132, 16, v83
	v_and_b32_e32 v133, 0xffff0000, v83
	s_waitcnt lgkmcnt(2)
	v_pk_fma_f32 v[128:129], v[128:129], v[0:1], v[90:91] op_sel_hi:[1,0,1]
	v_pk_fma_f32 v[126:127], v[126:127], v[0:1], v[142:143] op_sel_hi:[1,0,1]
	s_waitcnt lgkmcnt(1)
	v_mfma_f32_16x16x32_bf16 v[130:133], v[58:61], v[134:137], v[130:133]
	v_lshlrev_b32_e32 v82, 16, v84
	v_and_b32_e32 v83, 0xffff0000, v84
	v_lshlrev_b32_e32 v84, 16, v85
	v_mfma_f32_16x16x32_bf16 v[126:129], v[42:45], v[134:137], v[126:129]
	v_and_b32_e32 v85, 0xffff0000, v85
	v_lshlrev_b32_e32 v90, 16, v92
	v_and_b32_e32 v91, 0xffff0000, v92
	s_waitcnt lgkmcnt(0)
	v_mfma_f32_16x16x32_bf16 v[130:133], v[50:53], v[138:141], v[130:133]
	v_lshlrev_b32_e32 v92, 16, v93
	v_and_b32_e32 v93, 0xffff0000, v93
	v_pk_fma_f32 v[92:93], v[124:125], v[0:1], v[92:93] op_sel_hi:[1,0,1]
	v_mfma_f32_16x16x32_bf16 v[126:129], v[38:41], v[138:141], v[126:129]
	ds_read_b128 v[138:141], v146 offset:2304
	ds_read_b128 v[142:145], v146 offset:2368
	v_pk_fma_f32 v[90:91], v[122:123], v[0:1], v[90:91] op_sel_hi:[1,0,1]
	s_waitcnt lgkmcnt(1)
	v_mfma_f32_16x16x32_bf16 v[82:85], v[58:61], v[138:141], v[82:85]
	s_waitcnt lgkmcnt(0)
	v_mfma_f32_16x16x32_bf16 v[134:137], v[50:53], v[142:145], v[82:85]
	v_mfma_f32_16x16x32_bf16 v[82:85], v[42:45], v[138:141], v[90:93]
	s_waitcnt vmcnt(63)
	v_lshlrev_b32_e32 v138, 16, v54
	v_and_b32_e32 v139, 0xffff0000, v54
	v_lshlrev_b32_e32 v140, 16, v55
	v_mfma_f32_16x16x32_bf16 v[122:125], v[38:41], v[142:145], v[82:85]
	s_nop 2
	ds_read_b128 v[82:85], v146 offset:4608
	ds_read_b128 v[90:93], v146 offset:4672
	v_lshlrev_b32_e32 v142, 16, v62
	v_and_b32_e32 v143, 0xffff0000, v62
	v_lshlrev_b32_e32 v62, 16, v63
	v_and_b32_e32 v63, 0xffff0000, v63
	v_and_b32_e32 v141, 0xffff0000, v55
	v_pk_fma_f32 v[116:117], v[116:117], v[0:1], v[62:63] op_sel_hi:[1,0,1]
	v_pk_fma_f32 v[114:115], v[114:115], v[0:1], v[142:143] op_sel_hi:[1,0,1]
	s_waitcnt lgkmcnt(1)
	v_mfma_f32_16x16x32_bf16 v[138:141], v[58:61], v[82:85], v[138:141]
	v_lshlrev_b32_e32 v62, 16, v64
	v_and_b32_e32 v63, 0xffff0000, v64
	v_lshlrev_b32_e32 v64, 16, v65
	v_mfma_f32_16x16x32_bf16 v[82:85], v[42:45], v[82:85], v[114:117]
	v_and_b32_e32 v65, 0xffff0000, v65
	v_lshlrev_b32_e32 v54, 16, v56
	v_and_b32_e32 v55, 0xffff0000, v56
	s_waitcnt lgkmcnt(0)
	v_mfma_f32_16x16x32_bf16 v[138:141], v[50:53], v[90:93], v[138:141]
	v_lshlrev_b32_e32 v56, 16, v57
	v_and_b32_e32 v57, 0xffff0000, v57
	v_pk_fma_f32 v[64:65], v[120:121], v[0:1], v[64:65] op_sel_hi:[1,0,1]
	v_mfma_f32_16x16x32_bf16 v[114:117], v[38:41], v[90:93], v[82:85]
	s_nop 2
	ds_read_b128 v[82:85], v146 offset:6912
	ds_read_b128 v[90:93], v146 offset:6976
	v_pk_fma_f32 v[62:63], v[118:119], v[0:1], v[62:63] op_sel_hi:[1,0,1]
	s_waitcnt lgkmcnt(1)
	v_mfma_f32_16x16x32_bf16 v[54:57], v[58:61], v[82:85], v[54:57]
	v_mfma_f32_16x16x32_bf16 v[42:45], v[42:45], v[82:85], v[62:65]
	s_waitcnt lgkmcnt(0)
	v_mfma_f32_16x16x32_bf16 v[142:145], v[50:53], v[90:93], v[54:57]
	v_mfma_f32_16x16x32_bf16 v[118:121], v[38:41], v[90:93], v[42:45]
.LBB0_497:
	s_mov_b64 s[20:21], -1
	v_readfirstlane_b32 s1, v0
	s_andn2_b64 vcc, exec, s[18:19]
	v_readfirstlane_b32 s3, v0
	s_cbranch_vccnz .LBB0_482
	s_waitcnt vmcnt(63)
	v_mov_b32_e32 v50, v154
	v_mov_b32_e32 v40, v197
	v_mov_b32_e32 v0, v192
	v_mov_b32_e32 v39, v192
	v_mov_b32_e32 v41, v196
	v_mov_b32_e32 v38, v194
	v_mov_b32_e32 v42, v193
	v_mov_b32_e32 v43, v195
	s_add_i32 s4, s23, 1
	v_cvt_pk_bf16_f32 v42, v126, v127
	v_cvt_pk_bf16_f32 v43, v128, v129
	ds_write_b64 v199, v[42:43] offset:11520
	v_cvt_pk_bf16_f32 v42, v122, v123
	v_cvt_pk_bf16_f32 v43, v124, v125
	ds_write_b64 v199, v[42:43] offset:13824
	v_cvt_pk_bf16_f32 v42, v114, v115
	v_cvt_pk_bf16_f32 v43, v116, v117
	ds_write_b64 v199, v[42:43] offset:16128
	v_cvt_pk_bf16_f32 v42, v118, v119
	v_cvt_pk_bf16_f32 v43, v120, v121
	s_cmp_lt_i32 s4, 21
	ds_write_b64 v199, v[42:43] offset:18432
	s_cbranch_scc1 .LBB0_502
	s_cmp_lg_u32 s4, 21
	s_mov_b64 s[12:13], -1
	s_cselect_b64 s[14:15], -1, 0
	s_cbranch_execz .LBB0_503
	s_branch .LBB0_504

; __device__ __forceinline__ bool scan_needfin(int s) { return s >= 0 && s < 35 && !scan_first(s + 1) && s + 1 != 20 && s + 1 != 2; }
;     ...
;     if (s == 21 || s == 3) asm volatile("s_waitcnt vmcnt(0)" ::: "memory");
;     else if (scan_needfin(s - 1)) { if (GDN) asm volatile("s_waitcnt vmcnt(14)" ::: "memory"); else asm volatile("s_waitcnt vmcnt(15)" ::: "memory"); }
;     else { if (GDN) asm volatile("s_waitcnt vmcnt(8)" ::: "memory"); else asm volatile("s_waitcnt vmcnt(9)" ::: "memory"); }
;     __syncthreads();
.LBB0_507:
	s_andn2_b64 vcc, exec, s[12:13]
	s_cbranch_vccnz .LBB0_509
	s_waitcnt vmcnt(18)

; __device__ __forceinline__ const char* upin(const char* p) { asm volatile("" : "+s"(p)); return p; }
; __device__ __forceinline__ char* upin(char* p) { asm volatile("" : "+s"(p)); return p; }
; template <bool GDN> __device__ __forceinline__ void scan_fin_load(const Frame& F, int b, int h, int dir, const ScanLane& L, int s, const float* PEND, ScanFin& f) {
;     const int cidx = dir ? (s < 4 ? 3 - s : 39 - s) : s; const int row0 = chunk_row0(b, cidx);
;     const char* pp = upin((const char*)PEND + (size_t)((b * 4 + h) * 36 + cidx) * 16384);
;     const char* gp = (const char*)F.Z + ((size_t)row0 * ZW + (GDN ? ZC_GZ : ZC_LO) + h * 64) * 2;
; #pragma unroll
;     for (int pr = 0; pr < 2; ++pr) { const v4u qp = ldu<v4u>(pp + pr * 1024, L.pend); f.pend[2 * pr] = (v2u){qp.x, qp.y}; f.pend[2 * pr + 1] = (v2u){qp.z, qp.w}; }
; #pragma unroll
;     for (int t = 0; t < 4; ++t) f.gz[t] = ldu<v2u>(upin(gp + (size_t)t * ZW * 2), L.gz);
; }
.LBB0_519:
	s_cmp_gt_u32 s23, 3
	s_cselect_b32 s1, 39, 3
	s_add_i32 s1, s1, s22
	s_add_i32 s1, s1, 3
	s_and_b64 s[6:7], s[90:91], exec
	s_cselect_b32 s1, s23, s1
	s_lshl_b32 s3, s1, 6
	s_or_b32 s5, s3, s25
	s_add_i32 s3, s3, s24
	s_cmp_lt_u32 s1, 4
	s_cselect_b32 s3, s5, s3
	s_add_i32 s6, s1, s30
	s_ashr_i32 s7, s6, 31
	s_lshl_b64 s[6:7], s[6:7], 14
	s_add_u32 s6, s96, s6
	s_mul_hi_i32 s9, s3, 0xd00
	s_mul_i32 s8, s3, 0xd00
	s_addc_u32 s7, s97, s7
	s_or_b64 s[8:9], s[8:9], s[38:39]
	s_waitcnt vmcnt(0)
	s_lshl_b64 s[8:9], s[8:9], 1
	global_load_dwordx4 v[2:5], v39, s[6:7]
	global_load_dwordx4 v[6:9], v39, s[6:7] offset:1024
	s_add_u32 s6, s16, s8
	s_addc_u32 s7, s17, s9
	s_mov_b64 s[8:9], s[6:7]
	global_load_dwordx2 v[156:157], v38, s[8:9]
	s_add_u32 s8, s6, 0x1a00
	s_addc_u32 s9, s7, 0
	global_load_dwordx2 v[158:159], v38, s[8:9]
	s_add_u32 s8, s6, 0x3400
	s_addc_u32 s9, s7, 0
	s_add_u32 s6, s6, 0x4e00
	s_addc_u32 s7, s7, 0
	global_load_dwordx2 v[160:161], v38, s[8:9]
	global_load_dwordx2 v[162:163], v38, s[6:7]
	s_waitcnt vmcnt(0)
; __device__ __forceinline__ float row16_sum(float v) { v += dppf<0xB1>(v); v += dppf<0x4E>(v); v += dppf<0x141>(v); v += dppf<0x140>(v); return v; }
; __device__ __forceinline__ float frsq(float x) { return __builtin_amdgcn_rsqf(x); }
; __device__ __forceinline__ v2u pack4(const f32x4 v) { v2u r; r.x = pk2(v[0], v[1]); r.y = pk2(v[2], v[3]); return r; }
; __device__ __forceinline__ f32x4 unpack4(const v2u w) { f32x4 r; r[0] = bflo(w.x); r[1] = bfhi(w.x); r[2] = bflo(w.y); r[3] = bfhi(w.y); return r; }
; __device__ __forceinline__ const char* upin(const char* p) { asm volatile("" : "+s"(p)); return p; }
; __device__ __forceinline__ char* upin(char* p) { asm volatile("" : "+s"(p)); return p; }
; template <bool GDN> __device__ __forceinline__ void scan_finish(const Frame& F, int b, int h, int dir, const ScanLane& L, int s, float* PEND, const f32x4 (&Oin)[4], const ScanFin& f) {
;     ...
;         f32x4 O[4]; float ss[4] = {0.f, 0.f, 0.f, 0.f};
; #pragma unroll
;         for (int t = 0; t < 4; ++t)
;             { const f32x4 pv = unpack4(f.pend[t]);
; #pragma unroll
;             for (int i = 0; i < 4; ++i) { O[t][i] = Oin[t][i] + pv[i]; ss[i] += O[t][i] * O[t][i]; } }
; #pragma unroll
;         for (int i = 0; i < 4; ++i) ss[i] = frsq(row16_sum(ss[i]) * (1.f / 64.f) + EPS);
;         char* mp = (char*)F.MIX + ((size_t)row0 * 1024 + (GDN ? 0 : 768) + h * 64) * 2;
; #pragma unroll
;         for (int i = 0; i < 4; ++i) { const f32x4 g = unpack4(f.gz[i]); f32x4 ov;
; #pragma unroll
;             for (int t = 0; t < 4; ++t) ov[t] = O[t][i] * ss[i] * g[t];
;             stu<v2u>(upin(mp + i * 2048), L.mix, pack4(ov)); }
.LBB0_520:
	s_cmp_gt_u32 s23, 3
	s_cselect_b32 s5, 39, 3
	s_add_i32 s5, s5, s22
	s_add_i32 s1, s5, 3
	s_and_b64 s[6:7], s[90:91], exec
	s_cselect_b32 s1, s23, s1
	s_cmp_lt_u32 s4, 5
	s_cselect_b32 s3, 2, 20
	s_cmp_lt_u32 s23, s3
	s_mov_b64 s[12:13], -1
	s_cbranch_scc1 .LBB0_522
	s_waitcnt vmcnt(63)
	v_lshlrev_b32_e32 v55, 16, v4
	v_lshlrev_b32_e32 v54, 16, v2
	v_mov_b32_e32 v56, v130
	v_mov_b32_e32 v57, v134
	s_waitcnt vmcnt(63)
	v_lshlrev_b32_e32 v43, 16, v8
	v_lshlrev_b32_e32 v42, 16, v6
	v_mov_b32_e32 v44, v138
	v_mov_b32_e32 v45, v142
	v_pk_add_f32 v[54:55], v[56:57], v[54:55]
	v_pk_add_f32 v[42:43], v[44:45], v[42:43]
	v_pk_mul_f32 v[56:57], v[54:55], v[54:55]
	v_pk_mul_f32 v[44:45], v[42:43], v[42:43]
	v_add_f32_e32 v41, v57, v56
	v_add_f32_e32 v41, v44, v41
	v_add_f32_e32 v41, v45, v41
	s_cmp_lt_i32 s1, 4
	s_cselect_b32 s3, s25, s24
	v_add_f32_dpp v41, v41, v41 quad_perm:[1,0,3,2] row_mask:0xf bank_mask:0xf bound_ctrl:1
	s_lshl_b32 s6, s1, 6
	s_add_i32 s6, s3, s6
	v_add_f32_dpp v41, v41, v41 quad_perm:[2,3,0,1] row_mask:0xf bank_mask:0xf bound_ctrl:1
	s_ashr_i32 s7, s6, 31
	s_lshl_b64 s[6:7], s[6:7], 11
	v_add_f32_dpp v41, v41, v41 row_half_mirror row_mask:0xf bank_mask:0xf bound_ctrl:1
	s_add_u32 s18, s26, s6
	s_waitcnt vmcnt(63)
	v_lshlrev_b32_e32 v52, 16, v157
	v_add_f32_dpp v41, v41, v41 row_mirror row_mask:0xf bank_mask:0xf bound_ctrl:1
	v_fmamk_f32 v41, v41, 0x3c800000, v231
	v_rsq_f32_e32 v44, v41
	v_and_b32_e32 v53, 0xffff0000, v157
	v_lshlrev_b32_e32 v56, 16, v156
	v_and_b32_e32 v57, 0xffff0000, v156
	v_pk_mul_f32 v[54:55], v[54:55], v[44:45] op_sel_hi:[1,0]
	v_pk_mul_f32 v[42:43], v[42:43], v[44:45] op_sel_hi:[1,0]
	s_addc_u32 s19, s27, s7
	v_pk_mul_f32 v[54:55], v[54:55], v[56:57]
	v_pk_mul_f32 v[42:43], v[42:43], v[52:53]
	s_mov_b64 s[6:7], s[18:19]
	v_cvt_pk_bf16_f32 v44, v54, v55
	v_cvt_pk_bf16_f32 v45, v42, v43
	v_and_b32_e32 v55, 0xffff0000, v4
	v_and_b32_e32 v54, 0xffff0000, v2
	v_mov_b32_e32 v56, v131
	v_mov_b32_e32 v57, v135
	global_store_dwordx2 v40, v[44:45], s[6:7]
	v_and_b32_e32 v43, 0xffff0000, v8
	v_and_b32_e32 v42, 0xffff0000, v6
	v_mov_b32_e32 v44, v139
	v_mov_b32_e32 v45, v143
	v_pk_add_f32 v[54:55], v[56:57], v[54:55]
	v_pk_add_f32 v[42:43], v[44:45], v[42:43]
	v_pk_mul_f32 v[56:57], v[54:55], v[54:55]
	v_pk_mul_f32 v[44:45], v[42:43], v[42:43]
	v_add_f32_e32 v41, v57, v56
	v_add_f32_e32 v41, v44, v41
	v_add_f32_e32 v41, v45, v41
	s_waitcnt vmcnt(63)
	v_lshlrev_b32_e32 v52, 16, v159
	v_and_b32_e32 v53, 0xffff0000, v159
	v_add_f32_dpp v41, v41, v41 quad_perm:[1,0,3,2] row_mask:0xf bank_mask:0xf bound_ctrl:1
	v_lshlrev_b32_e32 v56, 16, v158
	v_and_b32_e32 v57, 0xffff0000, v158
	v_add_f32_dpp v41, v41, v41 quad_perm:[2,3,0,1] row_mask:0xf bank_mask:0xf bound_ctrl:1
	s_add_u32 s6, s18, 0x800
	s_addc_u32 s7, s19, 0
	v_add_f32_dpp v41, v41, v41 row_half_mirror row_mask:0xf bank_mask:0xf bound_ctrl:1
	s_mov_b64 s[12:13], 0
	s_nop 0
	v_add_f32_dpp v41, v41, v41 row_mirror row_mask:0xf bank_mask:0xf bound_ctrl:1
	v_fmamk_f32 v41, v41, 0x3c800000, v231
	v_rsq_f32_e32 v44, v41
	s_nop 0
	v_pk_mul_f32 v[54:55], v[54:55], v[44:45] op_sel_hi:[1,0]
	v_pk_mul_f32 v[42:43], v[42:43], v[44:45] op_sel_hi:[1,0]
	v_pk_mul_f32 v[54:55], v[54:55], v[56:57]
	v_pk_mul_f32 v[42:43], v[42:43], v[52:53]
	v_cvt_pk_bf16_f32 v44, v54, v55
	v_cvt_pk_bf16_f32 v45, v42, v43
	v_lshlrev_b32_e32 v55, 16, v5
	v_lshlrev_b32_e32 v54, 16, v3
	v_mov_b32_e32 v56, v132
	v_mov_b32_e32 v57, v136
	global_store_dwordx2 v40, v[44:45], s[6:7]
	v_lshlrev_b32_e32 v43, 16, v9
	v_lshlrev_b32_e32 v42, 16, v7
	v_mov_b32_e32 v44, v140
	v_mov_b32_e32 v45, v144
	v_pk_add_f32 v[54:55], v[56:57], v[54:55]
	v_pk_add_f32 v[42:43], v[44:45], v[42:43]
	v_pk_mul_f32 v[56:57], v[54:55], v[54:55]
	v_pk_mul_f32 v[44:45], v[42:43], v[42:43]
	v_add_f32_e32 v41, v57, v56
	v_add_f32_e32 v41, v44, v41
	v_add_f32_e32 v41, v45, v41
	s_waitcnt vmcnt(63)
	v_lshlrev_b32_e32 v52, 16, v161
	v_and_b32_e32 v53, 0xffff0000, v161
	v_add_f32_dpp v41, v41, v41 quad_perm:[1,0,3,2] row_mask:0xf bank_mask:0xf bound_ctrl:1
	v_lshlrev_b32_e32 v56, 16, v160
	v_and_b32_e32 v57, 0xffff0000, v160
	v_add_f32_dpp v41, v41, v41 quad_perm:[2,3,0,1] row_mask:0xf bank_mask:0xf bound_ctrl:1
	s_add_u32 s6, s18, 0x1000
	s_addc_u32 s7, s19, 0
	v_add_f32_dpp v41, v41, v41 row_half_mirror row_mask:0xf bank_mask:0xf bound_ctrl:1
	s_nop 1
	v_add_f32_dpp v41, v41, v41 row_mirror row_mask:0xf bank_mask:0xf bound_ctrl:1
	v_fmamk_f32 v41, v41, 0x3c800000, v231
	v_rsq_f32_e32 v44, v41
	s_nop 0
	v_pk_mul_f32 v[54:55], v[54:55], v[44:45] op_sel_hi:[1,0]
	v_pk_mul_f32 v[42:43], v[42:43], v[44:45] op_sel_hi:[1,0]
	v_pk_mul_f32 v[54:55], v[54:55], v[56:57]
	v_pk_mul_f32 v[42:43], v[42:43], v[52:53]
	v_cvt_pk_bf16_f32 v44, v54, v55
	v_cvt_pk_bf16_f32 v45, v42, v43
	v_and_b32_e32 v55, 0xffff0000, v5
	v_and_b32_e32 v54, 0xffff0000, v3
	v_mov_b32_e32 v56, v133
	v_mov_b32_e32 v57, v137
	global_store_dwordx2 v40, v[44:45], s[6:7]
	v_and_b32_e32 v43, 0xffff0000, v9
	v_and_b32_e32 v42, 0xffff0000, v7
	v_mov_b32_e32 v44, v141
	v_mov_b32_e32 v45, v145
	v_pk_add_f32 v[54:55], v[56:57], v[54:55]
	v_pk_add_f32 v[42:43], v[44:45], v[42:43]
	v_pk_mul_f32 v[56:57], v[54:55], v[54:55]
	v_pk_mul_f32 v[44:45], v[42:43], v[42:43]
	v_add_f32_e32 v41, v57, v56
	v_add_f32_e32 v41, v44, v41
	v_add_f32_e32 v41, v45, v41
	s_waitcnt vmcnt(63)
	v_lshlrev_b32_e32 v52, 16, v163
	v_and_b32_e32 v53, 0xffff0000, v163
	v_add_f32_dpp v41, v41, v41 quad_perm:[1,0,3,2] row_mask:0xf bank_mask:0xf bound_ctrl:1
	v_lshlrev_b32_e32 v56, 16, v162
	v_and_b32_e32 v57, 0xffff0000, v162
	v_add_f32_dpp v41, v41, v41 quad_perm:[2,3,0,1] row_mask:0xf bank_mask:0xf bound_ctrl:1
	s_add_u32 s6, s18, 0x1800
	s_addc_u32 s7, s19, 0
	v_add_f32_dpp v41, v41, v41 row_half_mirror row_mask:0xf bank_mask:0xf bound_ctrl:1
	s_nop 1
	v_add_f32_dpp v41, v41, v41 row_mirror row_mask:0xf bank_mask:0xf bound_ctrl:1
	v_fmamk_f32 v41, v41, 0x3c800000, v231
	v_rsq_f32_e32 v44, v41
	s_nop 0
	v_pk_mul_f32 v[54:55], v[54:55], v[44:45] op_sel_hi:[1,0]
	v_pk_mul_f32 v[42:43], v[42:43], v[44:45] op_sel_hi:[1,0]
	v_pk_mul_f32 v[54:55], v[54:55], v[56:57]
	v_pk_mul_f32 v[42:43], v[42:43], v[52:53]
	v_cvt_pk_bf16_f32 v44, v54, v55
	v_cvt_pk_bf16_f32 v45, v42, v43
	global_store_dwordx2 v40, v[44:45], s[6:7]

; #define LAS __attribute__((address_space(3)))
; __device__ __forceinline__ f32x4 unpack4(const v2u w) { f32x4 r; r[0] = bflo(w.x); r[1] = bfhi(w.x); r[2] = bflo(w.y); r[3] = bfhi(w.y); return r; }
; template <class T> __device__ __forceinline__ T ldun(const void* ubase, unsigned boff) { return __builtin_nontemporal_load((const GAS T*)((const GAS char*)ubase + boff)); }
; __device__ __forceinline__ const char* upin(const char* p) { asm volatile("" : "+s"(p)); return p; }
; __device__ __forceinline__ char* upin(char* p) { asm volatile("" : "+s"(p)); return p; }
; template <bool GDN, int NT> __device__ __forceinline__ void scan_load(const Frame& F, int b, int h, int dir, const ScanLane& L, int s, ScanOps<NT>& o) {
;     ...
;         const char* base = (const char*)F.PG + (size_t)ud * 32768;
;         const char* bM = upin(base); const char* bB = upin(base + 8192); const char* bQ = upin(base + 16384); const char* bO = upin(base + 24576);
; #pragma unroll
;         for (int ks = 0; ks < 2; ++ks) { o.Mf[ks] = ldun<bf16x8>(bM + ks * 1024, L.o16); o.Qf[ks] = ldun<bf16x8>(bQ + ks * 1024, L.o16); }
; #pragma unroll
;         for (int pr = 0; pr < 2; ++pr) { const v4u qb = ldun<v4u>(bB + pr * 1024, L.o16p), qo = ldun<v4u>(bO + pr * 1024, L.o16p);
;             o.bv[2 * pr] = (v2u){qb.x, qb.y}; o.bv[2 * pr + 1] = (v2u){qb.z, qb.w}; o.ov[2 * pr] = (v2u){qo.x, qo.y}; o.ov[2 * pr + 1] = (v2u){qo.z, qo.w}; }
;         o.wi = (f32x4){1.f, 1.f, 1.f, 1.f};
;     ...
;     for (int t = 0; t < NT; ++t) {
;         const LAS bf16_t* sp2 = Sb + (16 * t + lr) * 72 + 8 * lq;
;         const bf16x8 s0 = *(const LAS bf16x8*)sp2, s1 = *(const LAS bf16x8*)(sp2 + 32);
;         const f32x4 bv = unpack4(use.bv[t]), ov = unpack4(use.ov[t]);
;         if (GDN) {
;             f32x4 o = ov, sn = S[t] * gl + bv;
;             o = __builtin_amdgcn_mfma_f32_16x16x32_bf16(use.Qf[0], s0, o, 0, 0, 0); o = __builtin_amdgcn_mfma_f32_16x16x32_bf16(use.Qf[1], s1, o, 0, 0, 0);
;             sn = __builtin_amdgcn_mfma_f32_16x16x32_bf16(use.Mf[0], s0, sn, 0, 0, 0); sn = __builtin_amdgcn_mfma_f32_16x16x32_bf16(use.Mf[1], s1, sn, 0, 0, 0);
;             S[t] = sn; O[t] = o;
.LBB0_531:
	s_min_u32 s1, s4, 33
	s_add_i32 s8, s1, 2
	s_and_b64 s[6:7], exec, s[10:11]
	s_cselect_b32 s1, 3, 39
	s_sub_i32 s9, s1, s8
	s_and_b64 s[6:7], s[90:91], exec
	s_cselect_b32 s6, s8, s9
	s_add_i32 s6, s6, s30
	s_lshl_b32 s6, s6, 1
	s_add_i32 s6, s6, s68
	s_ashr_i32 s7, s6, 31
	s_lshl_b64 s[6:7], s[6:7], 15
	s_add_u32 s6, s35, s6
	s_addc_u32 s7, s43, s7
	s_add_u32 s10, s6, 0x2000
	s_addc_u32 s11, s7, 0
	s_add_u32 s12, s6, 0x4000
	s_addc_u32 s13, s7, 0
	s_mov_b64 s[8:9], s[6:7]
	s_add_u32 s6, s6, 0x6000
	s_addc_u32 s7, s7, 0
	global_load_dwordx4 v[42:45], v50, s[8:9] nt
	global_load_dwordx4 v[58:61], v50, s[12:13] nt
	global_load_dwordx4 v[38:41], v50, s[8:9] offset:1024 nt
	s_nop 0
	global_load_dwordx4 v[50:53], v50, s[12:13] offset:1024 nt
	s_nop 0
	global_load_dwordx4 v[90:93], v0, s[10:11] nt
	global_load_dwordx4 v[82:85], v0, s[6:7] nt
	global_load_dwordx4 v[62:65], v0, s[10:11] offset:1024 nt
	global_load_dwordx4 v[54:57], v0, s[6:7] offset:1024 nt
	s_add_i32 s5, s5, 2
	s_and_b64 s[6:7], s[90:91], exec
	s_cselect_b32 s5, s4, s5
	s_lshl_b32 s6, s5, 3
	s_add_i32 s6, s34, s6
	v_mov_b32_e32 v0, s6
	ds_read_b32 v0, v0 offset:46080
	v_add_u32_e32 v200, v198, v155
	ds_read_b128 v[134:137], v200 offset:11520
	ds_read_b128 v[138:141], v200 offset:11584
	s_waitcnt vmcnt(63)
	v_lshlrev_b32_e32 v142, 16, v70
	v_and_b32_e32 v143, 0xffff0000, v70
	v_lshlrev_b32_e32 v144, 16, v71
	v_and_b32_e32 v145, 0xffff0000, v71
	s_waitcnt vmcnt(63)
	v_lshlrev_b32_e32 v130, 16, v66
	v_and_b32_e32 v131, 0xffff0000, v66
	v_lshlrev_b32_e32 v132, 16, v67
	v_and_b32_e32 v133, 0xffff0000, v67
	s_waitcnt lgkmcnt(2)
	v_pk_fma_f32 v[128:129], v[128:129], v[0:1], v[144:145] op_sel_hi:[1,0,1]
	v_pk_fma_f32 v[126:127], v[126:127], v[0:1], v[142:143] op_sel_hi:[1,0,1]
	s_waitcnt lgkmcnt(1)
	v_mfma_f32_16x16x32_bf16 v[130:133], v[110:113], v[134:137], v[130:133]
	v_lshlrev_b32_e32 v146, 16, v72
	v_and_b32_e32 v147, 0xffff0000, v72
	v_lshlrev_b32_e32 v148, 16, v73
	v_mfma_f32_16x16x32_bf16 v[126:129], v[102:105], v[134:137], v[126:129]
	v_and_b32_e32 v149, 0xffff0000, v73
	v_lshlrev_b32_e32 v134, 16, v68
	v_and_b32_e32 v135, 0xffff0000, v68
	s_waitcnt lgkmcnt(0)
	v_mfma_f32_16x16x32_bf16 v[130:133], v[106:109], v[138:141], v[130:133]
	v_lshlrev_b32_e32 v136, 16, v69
	v_and_b32_e32 v137, 0xffff0000, v69
	v_pk_fma_f32 v[124:125], v[124:125], v[0:1], v[148:149] op_sel_hi:[1,0,1]
	v_mfma_f32_16x16x32_bf16 v[126:129], v[98:101], v[138:141], v[126:129]
	ds_read_b128 v[138:141], v200 offset:13824
	ds_read_b128 v[142:145], v200 offset:13888
	v_pk_fma_f32 v[122:123], v[122:123], v[0:1], v[146:147] op_sel_hi:[1,0,1]
	v_lshlrev_b32_e32 v150, 16, v22
	s_waitcnt lgkmcnt(1)
	v_mfma_f32_16x16x32_bf16 v[134:137], v[110:113], v[138:141], v[134:137]
	v_and_b32_e32 v151, 0xffff0000, v22
	v_lshlrev_b32_e32 v152, 16, v23
	v_and_b32_e32 v153, 0xffff0000, v23
	v_mfma_f32_16x16x32_bf16 v[122:125], v[102:105], v[138:141], v[122:125]
	v_lshlrev_b32_e32 v138, 16, v18
	v_and_b32_e32 v139, 0xffff0000, v18
	v_lshlrev_b32_e32 v140, 16, v19
	s_waitcnt lgkmcnt(0)
	v_mfma_f32_16x16x32_bf16 v[134:137], v[106:109], v[142:145], v[134:137]
	v_and_b32_e32 v141, 0xffff0000, v19
	v_pk_fma_f32 v[116:117], v[116:117], v[0:1], v[152:153] op_sel_hi:[1,0,1]
	v_pk_fma_f32 v[114:115], v[114:115], v[0:1], v[150:151] op_sel_hi:[1,0,1]
	v_mfma_f32_16x16x32_bf16 v[122:125], v[98:101], v[142:145], v[122:125]
	ds_read_b128 v[142:145], v200 offset:16128
	ds_read_b128 v[146:149], v200 offset:16192
	v_lshlrev_b32_e32 v166, 16, v24
	v_and_b32_e32 v167, 0xffff0000, v24
	s_waitcnt lgkmcnt(1)
	v_mfma_f32_16x16x32_bf16 v[138:141], v[110:113], v[142:145], v[138:141]
	v_lshlrev_b32_e32 v168, 16, v25
	v_and_b32_e32 v169, 0xffff0000, v25
	v_pk_fma_f32 v[120:121], v[120:121], v[0:1], v[168:169] op_sel_hi:[1,0,1]
	v_mfma_f32_16x16x32_bf16 v[114:117], v[102:105], v[142:145], v[114:117]
	v_lshlrev_b32_e32 v142, 16, v20
	v_and_b32_e32 v143, 0xffff0000, v20
	v_lshlrev_b32_e32 v144, 16, v21
	s_waitcnt lgkmcnt(0)
	v_mfma_f32_16x16x32_bf16 v[138:141], v[106:109], v[146:149], v[138:141]
	v_and_b32_e32 v145, 0xffff0000, v21
	v_pk_fma_f32 v[118:119], v[118:119], v[0:1], v[166:167] op_sel_hi:[1,0,1]
	v_mov_b32_e32 v201, v154
	v_mfma_f32_16x16x32_bf16 v[114:117], v[98:101], v[146:149], v[114:117]
	ds_read_b128 v[146:149], v200 offset:18432
	ds_read_b128 v[150:153], v200 offset:18496
	v_mov_b32_e32 v0, v192
	v_mov_b32_e32 v202, v194
	s_waitcnt lgkmcnt(1)
	v_mfma_f32_16x16x32_bf16 v[142:145], v[110:113], v[146:149], v[142:145]
	s_cmp_gt_u32 s23, 33
	v_mfma_f32_16x16x32_bf16 v[118:121], v[102:105], v[146:149], v[118:121]
	v_mov_b32_e32 v147, v193
	v_mov_b32_e32 v148, v195
	v_mov_b32_e32 v146, v197
	s_waitcnt lgkmcnt(0)
	v_mfma_f32_16x16x32_bf16 v[142:145], v[106:109], v[150:153], v[142:145]
	v_mov_b32_e32 v149, v196
	v_mfma_f32_16x16x32_bf16 v[118:121], v[98:101], v[150:153], v[118:121]
	v_mov_b32_e32 v152, v192
	s_cbranch_scc1 .LBB0_533
	v_cvt_pk_bf16_f32 v148, v126, v127
	v_cvt_pk_bf16_f32 v149, v128, v129
	ds_write_b64 v199, v[148:149]
	v_cvt_pk_bf16_f32 v148, v122, v123
	v_cvt_pk_bf16_f32 v149, v124, v125
	ds_write_b64 v199, v[148:149] offset:2304
	v_cvt_pk_bf16_f32 v148, v114, v115
	v_cvt_pk_bf16_f32 v149, v116, v117
	ds_write_b64 v199, v[148:149] offset:4608
	v_cvt_pk_bf16_f32 v148, v118, v119
	v_cvt_pk_bf16_f32 v149, v120, v121
	ds_write_b64 v199, v[148:149] offset:6912

; __device__ __forceinline__ bool scan_needfin(int s) { return s >= 0 && s < 35 && !scan_first(s + 1) && s + 1 != 20 && s + 1 != 2; }
;     ...
;     if (s == 21 || s == 3) asm volatile("s_waitcnt vmcnt(0)" ::: "memory");
;     else if (scan_needfin(s - 1)) { if (GDN) asm volatile("s_waitcnt vmcnt(14)" ::: "memory"); else asm volatile("s_waitcnt vmcnt(15)" ::: "memory"); }
;     else { if (GDN) asm volatile("s_waitcnt vmcnt(8)" ::: "memory"); else asm volatile("s_waitcnt vmcnt(9)" ::: "memory"); }
;     __syncthreads();
.LBB0_535:
	s_andn2_b64 vcc, exec, s[10:11]
	s_cbranch_vccnz .LBB0_537
	s_waitcnt vmcnt(18)

; __device__ __forceinline__ const char* upin(const char* p) { asm volatile("" : "+s"(p)); return p; }
; __device__ __forceinline__ char* upin(char* p) { asm volatile("" : "+s"(p)); return p; }
; template <bool GDN> __device__ __forceinline__ void scan_fin_load(const Frame& F, int b, int h, int dir, const ScanLane& L, int s, const float* PEND, ScanFin& f) {
;     const int cidx = dir ? (s < 4 ? 3 - s : 39 - s) : s; const int row0 = chunk_row0(b, cidx);
;     const char* pp = upin((const char*)PEND + (size_t)((b * 4 + h) * 36 + cidx) * 16384);
;     const char* gp = (const char*)F.Z + ((size_t)row0 * ZW + (GDN ? ZC_GZ : ZC_LO) + h * 64) * 2;
; #pragma unroll
;     for (int pr = 0; pr < 2; ++pr) { const v4u qp = ldu<v4u>(pp + pr * 1024, L.pend); f.pend[2 * pr] = (v2u){qp.x, qp.y}; f.pend[2 * pr + 1] = (v2u){qp.z, qp.w}; }
; #pragma unroll
;     for (int t = 0; t < 4; ++t) f.gz[t] = ldu<v2u>(upin(gp + (size_t)t * ZW * 2), L.gz);
; }
.LBB0_542:
	s_cmp_gt_u32 s23, 32
	s_cselect_b64 s[4:5], -1, 0
	s_cmp_lt_u32 s0, 16
	s_cselect_b64 s[6:7], -1, 0
	s_or_b64 s[4:5], s[4:5], s[6:7]
	s_andn2_b64 vcc, exec, s[4:5]
	s_mov_b64 s[10:11], -1
	s_cbranch_vccz .LBB0_544
	s_add_i32 s5, s23, 3
	s_add_i32 s4, s1, s22
	s_and_b64 s[6:7], s[90:91], exec
	s_cselect_b32 s5, s5, s4
	s_lshl_b32 s6, s5, 6
	s_or_b32 s7, s6, s25
	s_add_i32 s6, s6, s24
	s_cmp_lt_u32 s5, 4
	s_cselect_b32 s8, s7, s6
	s_add_i32 s6, s5, s30
	s_ashr_i32 s7, s6, 31
	s_lshl_b64 s[6:7], s[6:7], 14
	s_add_u32 s6, s96, s6
	s_mul_hi_i32 s9, s8, 0xd00
	s_mulk_i32 s8, 0xd00
	s_addc_u32 s7, s97, s7
	s_or_b64 s[8:9], s[8:9], s[38:39]
	s_lshl_b64 s[8:9], s[8:9], 1
	global_load_dwordx4 v[10:13], v152, s[6:7]
	s_nop 0
	global_load_dwordx4 v[14:17], v152, s[6:7] offset:1024
	s_add_u32 s6, s16, s8
	s_addc_u32 s7, s17, s9
	s_mov_b64 s[8:9], s[6:7]
	global_load_dwordx2 v[164:165], v202, s[8:9]
	s_add_u32 s8, s6, 0x1a00
	s_addc_u32 s9, s7, 0
	global_load_dwordx2 v[178:179], v202, s[8:9]
	s_add_u32 s8, s6, 0x3400
	s_addc_u32 s9, s7, 0
	s_add_u32 s6, s6, 0x4e00
	s_addc_u32 s7, s7, 0
	global_load_dwordx2 v[180:181], v202, s[8:9]
	global_load_dwordx2 v[182:183], v202, s[6:7]
	s_mov_b64 s[10:11], 0

; #define LAS __attribute__((address_space(3)))
; __device__ __forceinline__ f32x4 unpack4(const v2u w) { f32x4 r; r[0] = bflo(w.x); r[1] = bfhi(w.x); r[2] = bflo(w.y); r[3] = bfhi(w.y); return r; }
; template <class T> __device__ __forceinline__ T ldun(const void* ubase, unsigned boff) { return __builtin_nontemporal_load((const GAS T*)((const GAS char*)ubase + boff)); }
; __device__ __forceinline__ const char* upin(const char* p) { asm volatile("" : "+s"(p)); return p; }
; __device__ __forceinline__ char* upin(char* p) { asm volatile("" : "+s"(p)); return p; }
; template <bool GDN, int NT> __device__ __forceinline__ void scan_load(const Frame& F, int b, int h, int dir, const ScanLane& L, int s, ScanOps<NT>& o) {
;     ...
;         const char* base = (const char*)F.PG + (size_t)ud * 32768;
;         const char* bM = upin(base); const char* bB = upin(base + 8192); const char* bQ = upin(base + 16384); const char* bO = upin(base + 24576);
; #pragma unroll
;         for (int ks = 0; ks < 2; ++ks) { o.Mf[ks] = ldun<bf16x8>(bM + ks * 1024, L.o16); o.Qf[ks] = ldun<bf16x8>(bQ + ks * 1024, L.o16); }
; #pragma unroll
;         for (int pr = 0; pr < 2; ++pr) { const v4u qb = ldun<v4u>(bB + pr * 1024, L.o16p), qo = ldun<v4u>(bO + pr * 1024, L.o16p);
;             o.bv[2 * pr] = (v2u){qb.x, qb.y}; o.bv[2 * pr + 1] = (v2u){qb.z, qb.w}; o.ov[2 * pr] = (v2u){qo.x, qo.y}; o.ov[2 * pr + 1] = (v2u){qo.z, qo.w}; }
;         o.wi = (f32x4){1.f, 1.f, 1.f, 1.f};
;     ...
;     for (int t = 0; t < NT; ++t) {
;         const LAS bf16_t* sp2 = Sb + (16 * t + lr) * 72 + 8 * lq;
;         const bf16x8 s0 = *(const LAS bf16x8*)sp2, s1 = *(const LAS bf16x8*)(sp2 + 32);
;         const f32x4 bv = unpack4(use.bv[t]), ov = unpack4(use.ov[t]);
;         if (GDN) {
;             f32x4 o = ov, sn = S[t] * gl + bv;
;             o = __builtin_amdgcn_mfma_f32_16x16x32_bf16(use.Qf[0], s0, o, 0, 0, 0); o = __builtin_amdgcn_mfma_f32_16x16x32_bf16(use.Qf[1], s1, o, 0, 0, 0);
;             sn = __builtin_amdgcn_mfma_f32_16x16x32_bf16(use.Mf[0], s0, sn, 0, 0, 0); sn = __builtin_amdgcn_mfma_f32_16x16x32_bf16(use.Mf[1], s1, sn, 0, 0, 0);
;             S[t] = sn; O[t] = o;
.LBB0_546:
	s_min_u32 s5, s3, 33
	s_add_i32 s8, s5, 2
	s_sub_i32 s5, 37, s5
	s_and_b64 s[6:7], s[90:91], exec
	s_cselect_b32 s5, s8, s5
	s_add_i32 s5, s5, s30
	s_lshl_b32 s5, s5, 1
	s_add_i32 s6, s5, s68
	s_ashr_i32 s7, s6, 31
	s_lshl_b64 s[6:7], s[6:7], 15
	s_add_u32 s6, s35, s6
	s_addc_u32 s7, s43, s7
	s_add_u32 s10, s6, 0x2000
	s_addc_u32 s11, s7, 0
	s_add_u32 s12, s6, 0x4000
	s_addc_u32 s13, s7, 0
	s_mov_b64 s[8:9], s[6:7]
	s_add_u32 s6, s6, 0x6000
	s_addc_u32 s7, s7, 0
	global_load_dwordx4 v[102:105], v201, s[8:9] nt
	global_load_dwordx4 v[110:113], v201, s[12:13] nt
	global_load_dwordx4 v[98:101], v201, s[8:9] offset:1024 nt
	global_load_dwordx4 v[106:109], v201, s[12:13] offset:1024 nt
	global_load_dwordx4 v[70:73], v0, s[10:11] nt
	global_load_dwordx4 v[66:69], v0, s[6:7] nt
	global_load_dwordx4 v[22:25], v0, s[10:11] offset:1024 nt
	global_load_dwordx4 v[18:21], v0, s[6:7] offset:1024 nt
	s_add_i32 s6, s4, 1
	s_and_b64 s[4:5], s[90:91], exec
	s_cselect_b32 s4, s3, s6
	s_lshl_b32 s4, s4, 3
	s_add_i32 s4, s34, s4
	v_mov_b32_e32 v0, s4
	ds_read_b32 v0, v0 offset:46080
	ds_read_b128 v[204:207], v200
	ds_read_b128 v[208:211], v200 offset:64
	v_lshlrev_b32_e32 v134, 16, v94
	v_and_b32_e32 v135, 0xffff0000, v94
	v_lshlrev_b32_e32 v94, 16, v95
	v_and_b32_e32 v95, 0xffff0000, v95
	v_lshlrev_b32_e32 v130, 16, v86
	v_and_b32_e32 v131, 0xffff0000, v86
	v_lshlrev_b32_e32 v132, 16, v87
	v_and_b32_e32 v133, 0xffff0000, v87
	s_waitcnt lgkmcnt(2)
	v_pk_fma_f32 v[128:129], v[128:129], v[0:1], v[94:95] op_sel_hi:[1,0,1]
	v_pk_fma_f32 v[126:127], v[126:127], v[0:1], v[134:135] op_sel_hi:[1,0,1]
	s_waitcnt lgkmcnt(1)
	v_mfma_f32_16x16x32_bf16 v[130:133], v[46:49], v[204:207], v[130:133]
	v_lshlrev_b32_e32 v94, 16, v96
	v_and_b32_e32 v95, 0xffff0000, v96
	v_lshlrev_b32_e32 v96, 16, v97
	v_mfma_f32_16x16x32_bf16 v[204:207], v[30:33], v[204:207], v[126:129]
	v_and_b32_e32 v97, 0xffff0000, v97
	v_lshlrev_b32_e32 v86, 16, v88
	v_and_b32_e32 v87, 0xffff0000, v88
	s_waitcnt lgkmcnt(0)
	v_mfma_f32_16x16x32_bf16 v[130:133], v[34:37], v[208:211], v[130:133]
	v_lshlrev_b32_e32 v88, 16, v89
	v_and_b32_e32 v89, 0xffff0000, v89
	v_pk_fma_f32 v[96:97], v[124:125], v[0:1], v[96:97] op_sel_hi:[1,0,1]
	v_mfma_f32_16x16x32_bf16 v[126:129], v[26:29], v[208:211], v[204:207]
	s_nop 2
	ds_read_b128 v[204:207], v200 offset:2304
	ds_read_b128 v[208:211], v200 offset:2368
	v_pk_fma_f32 v[94:95], v[122:123], v[0:1], v[94:95] op_sel_hi:[1,0,1]
	s_waitcnt lgkmcnt(1)
	v_mfma_f32_16x16x32_bf16 v[86:89], v[46:49], v[204:207], v[86:89]
	s_nop 0
	v_mfma_f32_16x16x32_bf16 v[204:207], v[30:33], v[204:207], v[94:97]
	s_waitcnt lgkmcnt(0)
	v_mfma_f32_16x16x32_bf16 v[134:137], v[34:37], v[208:211], v[86:89]
	s_nop 0
	v_lshlrev_b32_e32 v94, 16, v78
	v_and_b32_e32 v95, 0xffff0000, v78
	v_lshlrev_b32_e32 v78, 16, v79
	v_mfma_f32_16x16x32_bf16 v[122:125], v[26:29], v[208:211], v[204:207]
	s_nop 2
	ds_read_b128 v[204:207], v200 offset:4608
	ds_read_b128 v[208:211], v200 offset:4672
	v_and_b32_e32 v79, 0xffff0000, v79
	v_lshlrev_b32_e32 v86, 16, v74
	v_and_b32_e32 v87, 0xffff0000, v74
	v_lshlrev_b32_e32 v88, 16, v75
	v_and_b32_e32 v89, 0xffff0000, v75
	v_pk_fma_f32 v[96:97], v[116:117], v[0:1], v[78:79] op_sel_hi:[1,0,1]
	v_pk_fma_f32 v[94:95], v[114:115], v[0:1], v[94:95] op_sel_hi:[1,0,1]
	s_waitcnt lgkmcnt(1)
	v_mfma_f32_16x16x32_bf16 v[86:89], v[46:49], v[204:207], v[86:89]
	v_lshlrev_b32_e32 v78, 16, v80
	v_and_b32_e32 v79, 0xffff0000, v80
	v_lshlrev_b32_e32 v80, 16, v81
	v_mfma_f32_16x16x32_bf16 v[204:207], v[30:33], v[204:207], v[94:97]
	v_and_b32_e32 v81, 0xffff0000, v81
	v_lshlrev_b32_e32 v74, 16, v76
	v_and_b32_e32 v75, 0xffff0000, v76
	s_waitcnt lgkmcnt(0)
	v_mfma_f32_16x16x32_bf16 v[138:141], v[34:37], v[208:211], v[86:89]
	v_lshlrev_b32_e32 v76, 16, v77
	v_and_b32_e32 v77, 0xffff0000, v77
	v_pk_fma_f32 v[80:81], v[120:121], v[0:1], v[80:81] op_sel_hi:[1,0,1]
	v_mfma_f32_16x16x32_bf16 v[114:117], v[26:29], v[208:211], v[204:207]
	s_nop 2
	ds_read_b128 v[204:207], v200 offset:6912
	ds_read_b128 v[208:211], v200 offset:6976
	v_pk_fma_f32 v[78:79], v[118:119], v[0:1], v[78:79] op_sel_hi:[1,0,1]
	s_waitcnt lgkmcnt(1)
	v_mfma_f32_16x16x32_bf16 v[46:49], v[46:49], v[204:207], v[74:77]
	v_mfma_f32_16x16x32_bf16 v[204:207], v[30:33], v[204:207], v[78:81]
	s_waitcnt lgkmcnt(0)
	v_mfma_f32_16x16x32_bf16 v[142:145], v[34:37], v[208:211], v[46:49]
	v_mfma_f32_16x16x32_bf16 v[118:121], v[26:29], v[208:211], v[204:207]

; __device__ __forceinline__ float row16_sum(float v) { v += dppf<0xB1>(v); v += dppf<0x4E>(v); v += dppf<0x141>(v); v += dppf<0x140>(v); return v; }
; __device__ __forceinline__ float frsq(float x) { return __builtin_amdgcn_rsqf(x); }
; __device__ __forceinline__ v2u pack4(const f32x4 v) { v2u r; r.x = pk2(v[0], v[1]); r.y = pk2(v[2], v[3]); return r; }
; __device__ __forceinline__ f32x4 unpack4(const v2u w) { f32x4 r; r[0] = bflo(w.x); r[1] = bfhi(w.x); r[2] = bflo(w.y); r[3] = bfhi(w.y); return r; }
; __device__ __forceinline__ const char* upin(const char* p) { asm volatile("" : "+s"(p)); return p; }
; __device__ __forceinline__ char* upin(char* p) { asm volatile("" : "+s"(p)); return p; }
; template <bool GDN> __device__ __forceinline__ void scan_finish(const Frame& F, int b, int h, int dir, const ScanLane& L, int s, float* PEND, const f32x4 (&Oin)[4], const ScanFin& f) {
;     ...
;         f32x4 O[4]; float ss[4] = {0.f, 0.f, 0.f, 0.f};
; #pragma unroll
;         for (int t = 0; t < 4; ++t)
;             { const f32x4 pv = unpack4(f.pend[t]);
; #pragma unroll
;             for (int i = 0; i < 4; ++i) { O[t][i] = Oin[t][i] + pv[i]; ss[i] += O[t][i] * O[t][i]; } }
; #pragma unroll
;         for (int i = 0; i < 4; ++i) ss[i] = frsq(row16_sum(ss[i]) * (1.f / 64.f) + EPS);
;         char* mp = (char*)F.MIX + ((size_t)row0 * 1024 + (GDN ? 0 : 768) + h * 64) * 2;
; #pragma unroll
;         for (int i = 0; i < 4; ++i) { const f32x4 g = unpack4(f.gz[i]); f32x4 ov;
; #pragma unroll
;             for (int t = 0; t < 4; ++t) ov[t] = O[t][i] * ss[i] * g[t];
;             stu<v2u>(upin(mp + i * 2048), L.mix, pack4(ov)); }
.LBB0_568:
	s_waitcnt vmcnt(63)
	v_lshlrev_b32_e32 v47, 16, v4
	v_lshlrev_b32_e32 v46, 16, v2
	v_mov_b32_e32 v48, v130
	v_mov_b32_e32 v49, v134
	s_waitcnt vmcnt(63)
	v_lshlrev_b32_e32 v31, 16, v8
	v_lshlrev_b32_e32 v30, 16, v6
	v_mov_b32_e32 v32, v138
	v_mov_b32_e32 v33, v142
	v_pk_add_f32 v[46:47], v[48:49], v[46:47]
	v_pk_add_f32 v[30:31], v[32:33], v[30:31]
	v_pk_mul_f32 v[48:49], v[46:47], v[46:47]
	v_pk_mul_f32 v[32:33], v[30:31], v[30:31]
	v_add_f32_e32 v29, v49, v48
	v_add_f32_e32 v29, v32, v29
	v_add_f32_e32 v29, v33, v29
	s_cmp_lt_i32 s4, 4
	s_cselect_b32 s3, s25, s24
	v_add_f32_dpp v29, v29, v29 quad_perm:[1,0,3,2] row_mask:0xf bank_mask:0xf bound_ctrl:1
	s_lshl_b32 s5, s4, 6
	s_add_i32 s6, s3, s5
	v_add_f32_dpp v29, v29, v29 quad_perm:[2,3,0,1] row_mask:0xf bank_mask:0xf bound_ctrl:1
	s_ashr_i32 s7, s6, 31
	s_lshl_b64 s[6:7], s[6:7], 11
	v_add_f32_dpp v29, v29, v29 row_half_mirror row_mask:0xf bank_mask:0xf bound_ctrl:1
	s_add_u32 s10, s26, s6
	s_waitcnt vmcnt(63)
	v_lshlrev_b32_e32 v36, 16, v157
	v_add_f32_dpp v29, v29, v29 row_mirror row_mask:0xf bank_mask:0xf bound_ctrl:1
	v_fmamk_f32 v29, v29, 0x3c800000, v231
	v_rsq_f32_e32 v32, v29
	v_and_b32_e32 v37, 0xffff0000, v157
	v_lshlrev_b32_e32 v48, 16, v156
	v_and_b32_e32 v49, 0xffff0000, v156
	v_pk_mul_f32 v[46:47], v[46:47], v[32:33] op_sel_hi:[1,0]
	v_pk_mul_f32 v[30:31], v[30:31], v[32:33] op_sel_hi:[1,0]
	s_addc_u32 s11, s27, s7
	v_pk_mul_f32 v[46:47], v[46:47], v[48:49]
	v_pk_mul_f32 v[30:31], v[30:31], v[36:37]
	s_mov_b64 s[6:7], s[10:11]
	v_cvt_pk_bf16_f32 v32, v46, v47
	v_cvt_pk_bf16_f32 v33, v30, v31
	v_and_b32_e32 v47, 0xffff0000, v4
	v_and_b32_e32 v46, 0xffff0000, v2
	v_mov_b32_e32 v48, v131
	v_mov_b32_e32 v49, v135
	global_store_dwordx2 v28, v[32:33], s[6:7]
	v_and_b32_e32 v31, 0xffff0000, v8
	v_and_b32_e32 v30, 0xffff0000, v6
	v_mov_b32_e32 v32, v139
	v_mov_b32_e32 v33, v143
	v_pk_add_f32 v[46:47], v[48:49], v[46:47]
	v_pk_add_f32 v[30:31], v[32:33], v[30:31]
	v_pk_mul_f32 v[48:49], v[46:47], v[46:47]
	v_pk_mul_f32 v[32:33], v[30:31], v[30:31]
	v_add_f32_e32 v29, v49, v48
	v_add_f32_e32 v29, v32, v29
	v_add_f32_e32 v29, v33, v29
	s_waitcnt vmcnt(63)
	v_lshlrev_b32_e32 v36, 16, v159
	v_and_b32_e32 v37, 0xffff0000, v159
	v_add_f32_dpp v29, v29, v29 quad_perm:[1,0,3,2] row_mask:0xf bank_mask:0xf bound_ctrl:1
	v_lshlrev_b32_e32 v48, 16, v158
	v_and_b32_e32 v49, 0xffff0000, v158
	v_add_f32_dpp v29, v29, v29 quad_perm:[2,3,0,1] row_mask:0xf bank_mask:0xf bound_ctrl:1
	s_add_u32 s6, s10, 0x800
	s_addc_u32 s7, s11, 0
	v_add_f32_dpp v29, v29, v29 row_half_mirror row_mask:0xf bank_mask:0xf bound_ctrl:1
	s_nop 1
	v_add_f32_dpp v29, v29, v29 row_mirror row_mask:0xf bank_mask:0xf bound_ctrl:1
	v_fmamk_f32 v29, v29, 0x3c800000, v231
	v_rsq_f32_e32 v32, v29
	s_nop 0
	v_pk_mul_f32 v[46:47], v[46:47], v[32:33] op_sel_hi:[1,0]
	v_pk_mul_f32 v[30:31], v[30:31], v[32:33] op_sel_hi:[1,0]
	v_pk_mul_f32 v[46:47], v[46:47], v[48:49]
	v_pk_mul_f32 v[30:31], v[30:31], v[36:37]
	v_cvt_pk_bf16_f32 v32, v46, v47
	v_cvt_pk_bf16_f32 v33, v30, v31
	v_lshlrev_b32_e32 v47, 16, v5
	v_lshlrev_b32_e32 v46, 16, v3
	v_mov_b32_e32 v48, v132
	v_mov_b32_e32 v49, v136
	global_store_dwordx2 v28, v[32:33], s[6:7]
	v_lshlrev_b32_e32 v31, 16, v9
	v_lshlrev_b32_e32 v30, 16, v7
	v_mov_b32_e32 v32, v140
	v_mov_b32_e32 v33, v144
	v_pk_add_f32 v[46:47], v[48:49], v[46:47]
	v_pk_add_f32 v[30:31], v[32:33], v[30:31]
	v_pk_mul_f32 v[48:49], v[46:47], v[46:47]
	v_pk_mul_f32 v[32:33], v[30:31], v[30:31]
	v_add_f32_e32 v29, v49, v48
	v_add_f32_e32 v29, v32, v29
	v_add_f32_e32 v29, v33, v29
	s_waitcnt vmcnt(63)
	v_lshlrev_b32_e32 v36, 16, v161
	v_and_b32_e32 v37, 0xffff0000, v161
	v_add_f32_dpp v29, v29, v29 quad_perm:[1,0,3,2] row_mask:0xf bank_mask:0xf bound_ctrl:1
	v_lshlrev_b32_e32 v48, 16, v160
	v_and_b32_e32 v49, 0xffff0000, v160
	v_add_f32_dpp v29, v29, v29 quad_perm:[2,3,0,1] row_mask:0xf bank_mask:0xf bound_ctrl:1
	s_add_u32 s6, s10, 0x1000
	s_addc_u32 s7, s11, 0
	v_add_f32_dpp v29, v29, v29 row_half_mirror row_mask:0xf bank_mask:0xf bound_ctrl:1
	s_nop 1
	v_add_f32_dpp v29, v29, v29 row_mirror row_mask:0xf bank_mask:0xf bound_ctrl:1
	v_fmamk_f32 v29, v29, 0x3c800000, v231
	v_rsq_f32_e32 v32, v29
	s_nop 0
	v_pk_mul_f32 v[46:47], v[46:47], v[32:33] op_sel_hi:[1,0]
	v_pk_mul_f32 v[30:31], v[30:31], v[32:33] op_sel_hi:[1,0]
	v_pk_mul_f32 v[46:47], v[46:47], v[48:49]
	v_pk_mul_f32 v[30:31], v[30:31], v[36:37]
	v_cvt_pk_bf16_f32 v32, v46, v47
	v_cvt_pk_bf16_f32 v33, v30, v31
	v_and_b32_e32 v47, 0xffff0000, v5
	v_and_b32_e32 v46, 0xffff0000, v3
	v_mov_b32_e32 v48, v133
	v_mov_b32_e32 v49, v137
	global_store_dwordx2 v28, v[32:33], s[6:7]
	v_and_b32_e32 v31, 0xffff0000, v9
	v_and_b32_e32 v30, 0xffff0000, v7
	v_mov_b32_e32 v32, v141
	v_mov_b32_e32 v33, v145
	v_pk_add_f32 v[46:47], v[48:49], v[46:47]
	v_pk_add_f32 v[30:31], v[32:33], v[30:31]
	v_pk_mul_f32 v[48:49], v[46:47], v[46:47]
	v_pk_mul_f32 v[32:33], v[30:31], v[30:31]
	v_add_f32_e32 v29, v49, v48
	v_add_f32_e32 v29, v32, v29
	v_add_f32_e32 v29, v33, v29
	s_waitcnt vmcnt(63)
	v_lshlrev_b32_e32 v36, 16, v163
	v_and_b32_e32 v37, 0xffff0000, v163
	v_add_f32_dpp v29, v29, v29 quad_perm:[1,0,3,2] row_mask:0xf bank_mask:0xf bound_ctrl:1
	v_lshlrev_b32_e32 v48, 16, v162
	v_and_b32_e32 v49, 0xffff0000, v162
	v_add_f32_dpp v29, v29, v29 quad_perm:[2,3,0,1] row_mask:0xf bank_mask:0xf bound_ctrl:1
	s_add_u32 s6, s10, 0x1800
	s_addc_u32 s7, s11, 0
	v_add_f32_dpp v29, v29, v29 row_half_mirror row_mask:0xf bank_mask:0xf bound_ctrl:1
	s_nop 1
	v_add_f32_dpp v29, v29, v29 row_mirror row_mask:0xf bank_mask:0xf bound_ctrl:1
	v_fmamk_f32 v29, v29, 0x3c800000, v231
	v_rsq_f32_e32 v32, v29
	s_nop 0
	v_pk_mul_f32 v[46:47], v[46:47], v[32:33] op_sel_hi:[1,0]
	v_pk_mul_f32 v[30:31], v[30:31], v[32:33] op_sel_hi:[1,0]
	v_pk_mul_f32 v[46:47], v[46:47], v[48:49]
	v_pk_mul_f32 v[30:31], v[30:31], v[36:37]
	v_cvt_pk_bf16_f32 v32, v46, v47
	v_cvt_pk_bf16_f32 v33, v30, v31
	global_store_dwordx2 v28, v[32:33], s[6:7]
	s_cbranch_execz .LBB0_581

; #define LAS __attribute__((address_space(3)))
; __device__ __forceinline__ f32x4 unpack4(const v2u w) { f32x4 r; r[0] = bflo(w.x); r[1] = bfhi(w.x); r[2] = bflo(w.y); r[3] = bfhi(w.y); return r; }
; template <class T> __device__ __forceinline__ T ldun(const void* ubase, unsigned boff) { return __builtin_nontemporal_load((const GAS T*)((const GAS char*)ubase + boff)); }
; __device__ __forceinline__ const char* upin(const char* p) { asm volatile("" : "+s"(p)); return p; }
; __device__ __forceinline__ char* upin(char* p) { asm volatile("" : "+s"(p)); return p; }
; template <bool GDN, int NT> __device__ __forceinline__ void scan_load(const Frame& F, int b, int h, int dir, const ScanLane& L, int s, ScanOps<NT>& o) {
;     ...
;         const char* base = (const char*)F.PG + (size_t)ud * 32768;
;         const char* bM = upin(base); const char* bB = upin(base + 8192); const char* bQ = upin(base + 16384); const char* bO = upin(base + 24576);
; #pragma unroll
;         for (int ks = 0; ks < 2; ++ks) { o.Mf[ks] = ldun<bf16x8>(bM + ks * 1024, L.o16); o.Qf[ks] = ldun<bf16x8>(bQ + ks * 1024, L.o16); }
; #pragma unroll
;         for (int pr = 0; pr < 2; ++pr) { const v4u qb = ldun<v4u>(bB + pr * 1024, L.o16p), qo = ldun<v4u>(bO + pr * 1024, L.o16p);
;             o.bv[2 * pr] = (v2u){qb.x, qb.y}; o.bv[2 * pr + 1] = (v2u){qb.z, qb.w}; o.ov[2 * pr] = (v2u){qo.x, qo.y}; o.ov[2 * pr + 1] = (v2u){qo.z, qo.w}; }
;         o.wi = (f32x4){1.f, 1.f, 1.f, 1.f};
;     ...
;     for (int t = 0; t < NT; ++t) {
;         const LAS bf16_t* sp2 = Sb + (16 * t + lr) * 72 + 8 * lq;
;         const bf16x8 s0 = *(const LAS bf16x8*)sp2, s1 = *(const LAS bf16x8*)(sp2 + 32);
;         const f32x4 bv = unpack4(use.bv[t]), ov = unpack4(use.ov[t]);
;         if (GDN) {
;             f32x4 o = ov, sn = S[t] * gl + bv;
;             o = __builtin_amdgcn_mfma_f32_16x16x32_bf16(use.Qf[0], s0, o, 0, 0, 0); o = __builtin_amdgcn_mfma_f32_16x16x32_bf16(use.Qf[1], s1, o, 0, 0, 0);
;             sn = __builtin_amdgcn_mfma_f32_16x16x32_bf16(use.Mf[0], s0, sn, 0, 0, 0); sn = __builtin_amdgcn_mfma_f32_16x16x32_bf16(use.Mf[1], s1, sn, 0, 0, 0);
;             S[t] = sn; O[t] = o;
.LBB0_571:
	s_add_i32 s12, s23, 3
	s_min_u32 s4, s12, 33
	s_add_i32 s6, s4, 2
	s_sub_i32 s7, 37, s4
	s_and_b64 s[4:5], s[90:91], exec
	s_cselect_b32 s4, s6, s7
	s_add_i32 s4, s4, s30
	s_lshl_b32 s4, s4, 1
	s_add_i32 s4, s4, s68
	s_ashr_i32 s5, s4, 31
	s_lshl_b64 s[4:5], s[4:5], 15
	s_add_u32 s4, s35, s4
	s_addc_u32 s5, s43, s5
	s_add_u32 s8, s4, 0x2000
	s_addc_u32 s9, s5, 0
	s_add_u32 s10, s4, 0x4000
	s_addc_u32 s11, s5, 0
	s_mov_b64 s[6:7], s[4:5]
	s_add_u32 s4, s4, 0x6000
	s_addc_u32 s5, s5, 0
	global_load_dwordx4 v[30:33], v34, s[6:7] nt
	global_load_dwordx4 v[46:49], v34, s[10:11] nt
	global_load_dwordx4 v[26:29], v34, s[6:7] offset:1024 nt
	s_nop 0
	global_load_dwordx4 v[34:37], v34, s[10:11] offset:1024 nt
	s_nop 0
	global_load_dwordx4 v[94:97], v0, s[8:9] nt
	global_load_dwordx4 v[86:89], v0, s[4:5] nt
	global_load_dwordx4 v[78:81], v0, s[8:9] offset:1024 nt
	global_load_dwordx4 v[74:77], v0, s[4:5] offset:1024 nt
	s_add_i32 s1, s1, s22
	s_and_b64 s[4:5], s[90:91], exec
	s_cselect_b32 s1, s12, s1
	s_lshl_b32 s4, s1, 3
	s_add_i32 s4, s34, s4
	v_mov_b32_e32 v0, s4
	ds_read_b32 v0, v0 offset:46080
	ds_read_b128 v[134:137], v200 offset:11520
	ds_read_b128 v[138:141], v200 offset:11584
	s_waitcnt vmcnt(63)
	v_lshlrev_b32_e32 v142, 16, v90
	v_and_b32_e32 v143, 0xffff0000, v90
	v_lshlrev_b32_e32 v144, 16, v91
	v_and_b32_e32 v145, 0xffff0000, v91
	s_waitcnt vmcnt(63)
	v_lshlrev_b32_e32 v130, 16, v82
	v_and_b32_e32 v131, 0xffff0000, v82
	v_lshlrev_b32_e32 v132, 16, v83
	v_and_b32_e32 v133, 0xffff0000, v83
	s_waitcnt lgkmcnt(2)
	v_pk_fma_f32 v[128:129], v[128:129], v[0:1], v[144:145] op_sel_hi:[1,0,1]
	v_pk_fma_f32 v[126:127], v[126:127], v[0:1], v[142:143] op_sel_hi:[1,0,1]
	s_waitcnt lgkmcnt(1)
	v_mfma_f32_16x16x32_bf16 v[130:133], v[58:61], v[134:137], v[130:133]
	v_lshlrev_b32_e32 v146, 16, v92
	v_and_b32_e32 v147, 0xffff0000, v92
	v_lshlrev_b32_e32 v148, 16, v93
	v_mfma_f32_16x16x32_bf16 v[126:129], v[42:45], v[134:137], v[126:129]
	v_and_b32_e32 v149, 0xffff0000, v93
	v_lshlrev_b32_e32 v134, 16, v84
	v_and_b32_e32 v135, 0xffff0000, v84
	s_waitcnt lgkmcnt(0)
	v_mfma_f32_16x16x32_bf16 v[130:133], v[50:53], v[138:141], v[130:133]
	v_lshlrev_b32_e32 v136, 16, v85
	v_and_b32_e32 v137, 0xffff0000, v85
	v_pk_fma_f32 v[124:125], v[124:125], v[0:1], v[148:149] op_sel_hi:[1,0,1]
	v_mfma_f32_16x16x32_bf16 v[126:129], v[38:41], v[138:141], v[126:129]
	ds_read_b128 v[138:141], v200 offset:13824
	ds_read_b128 v[142:145], v200 offset:13888
	v_pk_fma_f32 v[122:123], v[122:123], v[0:1], v[146:147] op_sel_hi:[1,0,1]
	s_waitcnt vmcnt(63)
	v_lshlrev_b32_e32 v150, 16, v62
	s_waitcnt lgkmcnt(1)
	v_mfma_f32_16x16x32_bf16 v[134:137], v[58:61], v[138:141], v[134:137]
	v_and_b32_e32 v151, 0xffff0000, v62
	v_lshlrev_b32_e32 v152, 16, v63
	v_and_b32_e32 v153, 0xffff0000, v63
	v_mfma_f32_16x16x32_bf16 v[122:125], v[42:45], v[138:141], v[122:125]
	s_waitcnt vmcnt(63)
	v_lshlrev_b32_e32 v138, 16, v54
	v_and_b32_e32 v139, 0xffff0000, v54
	v_lshlrev_b32_e32 v140, 16, v55
	s_waitcnt lgkmcnt(0)
	v_mfma_f32_16x16x32_bf16 v[134:137], v[50:53], v[142:145], v[134:137]
	v_and_b32_e32 v141, 0xffff0000, v55
	v_pk_fma_f32 v[116:117], v[116:117], v[0:1], v[152:153] op_sel_hi:[1,0,1]
	v_pk_fma_f32 v[114:115], v[114:115], v[0:1], v[150:151] op_sel_hi:[1,0,1]
	v_mfma_f32_16x16x32_bf16 v[122:125], v[38:41], v[142:145], v[122:125]
	ds_read_b128 v[142:145], v200 offset:16128
	ds_read_b128 v[146:149], v200 offset:16192
	v_lshlrev_b32_e32 v166, 16, v64
	v_and_b32_e32 v167, 0xffff0000, v64
	s_waitcnt lgkmcnt(1)
	v_mfma_f32_16x16x32_bf16 v[138:141], v[58:61], v[142:145], v[138:141]
	v_lshlrev_b32_e32 v168, 16, v65
	v_and_b32_e32 v169, 0xffff0000, v65
	v_pk_fma_f32 v[120:121], v[120:121], v[0:1], v[168:169] op_sel_hi:[1,0,1]
	v_mfma_f32_16x16x32_bf16 v[114:117], v[42:45], v[142:145], v[114:117]
	v_lshlrev_b32_e32 v142, 16, v56
	v_and_b32_e32 v143, 0xffff0000, v56
	v_lshlrev_b32_e32 v144, 16, v57
	s_waitcnt lgkmcnt(0)
	v_mfma_f32_16x16x32_bf16 v[138:141], v[50:53], v[146:149], v[138:141]
	v_and_b32_e32 v145, 0xffff0000, v57
	v_pk_fma_f32 v[118:119], v[118:119], v[0:1], v[166:167] op_sel_hi:[1,0,1]
	v_mov_b32_e32 v0, v192
	v_mfma_f32_16x16x32_bf16 v[114:117], v[38:41], v[146:149], v[114:117]
	ds_read_b128 v[146:149], v200 offset:18432
	ds_read_b128 v[150:153], v200 offset:18496
	s_cmp_gt_u32 s23, 31
	s_waitcnt lgkmcnt(1)
	v_mfma_f32_16x16x32_bf16 v[142:145], v[58:61], v[146:149], v[142:145]
	v_mfma_f32_16x16x32_bf16 v[118:121], v[42:45], v[146:149], v[118:121]
	v_mov_b32_e32 v146, v154
	v_mov_b32_e32 v149, v197
	v_mov_b32_e32 v148, v192
	s_waitcnt lgkmcnt(0)
	v_mfma_f32_16x16x32_bf16 v[142:145], v[50:53], v[150:153], v[142:145]
	v_mov_b32_e32 v147, v194
	v_mfma_f32_16x16x32_bf16 v[118:121], v[38:41], v[150:153], v[118:121]
	v_mov_b32_e32 v150, v196
	v_mov_b32_e32 v151, v193
	v_mov_b32_e32 v152, v195
	s_cbranch_scc1 .LBB0_582
	v_cvt_pk_bf16_f32 v150, v126, v127
	v_cvt_pk_bf16_f32 v151, v128, v129
	ds_write_b64 v199, v[150:151]
	v_cvt_pk_bf16_f32 v150, v122, v123
	v_cvt_pk_bf16_f32 v151, v124, v125
	ds_write_b64 v199, v[150:151] offset:2304
	v_cvt_pk_bf16_f32 v150, v114, v115
	v_cvt_pk_bf16_f32 v151, v116, v117
	ds_write_b64 v199, v[150:151] offset:4608
	v_cvt_pk_bf16_f32 v150, v118, v119
	v_cvt_pk_bf16_f32 v151, v120, v121
	ds_write_b64 v199, v[150:151] offset:6912
	s_sub_i32 s4, s23, 17
	s_cmp_gt_u32 s4, 14
	s_mov_b64 s[10:11], -1
	s_cbranch_scc1 .LBB0_583

; __device__ __forceinline__ const char* upin(const char* p) { asm volatile("" : "+s"(p)); return p; }
; __device__ __forceinline__ char* upin(char* p) { asm volatile("" : "+s"(p)); return p; }
; template <bool GDN> __device__ __forceinline__ void scan_fin_load(const Frame& F, int b, int h, int dir, const ScanLane& L, int s, const float* PEND, ScanFin& f) {
;     const int cidx = dir ? (s < 4 ? 3 - s : 39 - s) : s; const int row0 = chunk_row0(b, cidx);
;     const char* pp = upin((const char*)PEND + (size_t)((b * 4 + h) * 36 + cidx) * 16384);
;     const char* gp = (const char*)F.Z + ((size_t)row0 * ZW + (GDN ? ZC_GZ : ZC_LO) + h * 64) * 2;
; #pragma unroll
;     for (int pr = 0; pr < 2; ++pr) { const v4u qp = ldu<v4u>(pp + pr * 1024, L.pend); f.pend[2 * pr] = (v2u){qp.x, qp.y}; f.pend[2 * pr + 1] = (v2u){qp.z, qp.w}; }
; #pragma unroll
;     for (int t = 0; t < 4; ++t) f.gz[t] = ldu<v2u>(upin(gp + (size_t)t * ZW * 2), L.gz);
; }
.LBB0_579:
	s_add_i32 s4, s1, s22
	s_add_i32 s6, s4, 1
	s_and_b64 s[4:5], s[90:91], exec
	s_cselect_b32 s4, s3, s6
	s_lshl_b32 s3, s4, 6
	s_or_b32 s5, s3, s25
	s_add_i32 s3, s3, s24
	s_cmp_lt_u32 s4, 4
	s_cselect_b32 s3, s5, s3
	s_add_i32 s6, s4, s30
	s_ashr_i32 s7, s6, 31
	s_lshl_b64 s[6:7], s[6:7], 14
	s_add_u32 s6, s96, s6
	s_mul_hi_i32 s9, s3, 0xd00
	s_mul_i32 s8, s3, 0xd00
	s_addc_u32 s7, s97, s7
	s_or_b64 s[8:9], s[8:9], s[38:39]
	s_waitcnt vmcnt(0)
	s_lshl_b64 s[8:9], s[8:9], 1
	global_load_dwordx4 v[2:5], v27, s[6:7]
	global_load_dwordx4 v[6:9], v27, s[6:7] offset:1024
	s_add_u32 s6, s16, s8
	s_addc_u32 s7, s17, s9
	s_mov_b64 s[8:9], s[6:7]
	global_load_dwordx2 v[156:157], v26, s[8:9]
	s_add_u32 s8, s6, 0x1a00
	s_addc_u32 s9, s7, 0
	global_load_dwordx2 v[158:159], v26, s[8:9]
	s_add_u32 s8, s6, 0x3400
	s_addc_u32 s9, s7, 0
	s_add_u32 s6, s6, 0x4e00
	s_addc_u32 s7, s7, 0
	global_load_dwordx2 v[160:161], v26, s[8:9]
	global_load_dwordx2 v[162:163], v26, s[6:7]
	s_waitcnt vmcnt(0)
	s_cmp_lt_u32 s0, 17
	s_mov_b64 s[10:11], -1
	s_cbranch_scc0 .LBB0_568

; __device__ __forceinline__ float row16_sum(float v) { v += dppf<0xB1>(v); v += dppf<0x4E>(v); v += dppf<0x141>(v); v += dppf<0x140>(v); return v; }
; __device__ __forceinline__ float frsq(float x) { return __builtin_amdgcn_rsqf(x); }
; __device__ __forceinline__ v2u pack4(const f32x4 v) { v2u r; r.x = pk2(v[0], v[1]); r.y = pk2(v[2], v[3]); return r; }
; __device__ __forceinline__ f32x4 unpack4(const v2u w) { f32x4 r; r[0] = bflo(w.x); r[1] = bfhi(w.x); r[2] = bflo(w.y); r[3] = bfhi(w.y); return r; }
; __device__ __forceinline__ const char* upin(const char* p) { asm volatile("" : "+s"(p)); return p; }
; __device__ __forceinline__ char* upin(char* p) { asm volatile("" : "+s"(p)); return p; }
; template <bool GDN> __device__ __forceinline__ void scan_finish(const Frame& F, int b, int h, int dir, const ScanLane& L, int s, float* PEND, const f32x4 (&Oin)[4], const ScanFin& f) {
;     ...
;         f32x4 O[4]; float ss[4] = {0.f, 0.f, 0.f, 0.f};
; #pragma unroll
;         for (int t = 0; t < 4; ++t)
;             { const f32x4 pv = unpack4(f.pend[t]);
; #pragma unroll
;             for (int i = 0; i < 4; ++i) { O[t][i] = Oin[t][i] + pv[i]; ss[i] += O[t][i] * O[t][i]; } }
; #pragma unroll
;         for (int i = 0; i < 4; ++i) ss[i] = frsq(row16_sum(ss[i]) * (1.f / 64.f) + EPS);
;         char* mp = (char*)F.MIX + ((size_t)row0 * 1024 + (GDN ? 0 : 768) + h * 64) * 2;
; #pragma unroll
;         for (int i = 0; i < 4; ++i) { const f32x4 g = unpack4(f.gz[i]); f32x4 ov;
; #pragma unroll
;             for (int t = 0; t < 4; ++t) ov[t] = O[t][i] * ss[i] * g[t];
;             stu<v2u>(upin(mp + i * 2048), L.mix, pack4(ov)); }
.LBB0_602:
	s_waitcnt vmcnt(63)
	v_lshlrev_b32_e32 v69, 16, v4
	v_lshlrev_b32_e32 v68, 16, v2
	v_mov_b32_e32 v70, v130
	v_mov_b32_e32 v71, v134
	s_waitcnt vmcnt(63)
	v_lshlrev_b32_e32 v23, 16, v8
	v_lshlrev_b32_e32 v22, 16, v6
	v_mov_b32_e32 v24, v138
	v_mov_b32_e32 v25, v142
	v_pk_add_f32 v[68:69], v[70:71], v[68:69]
	v_pk_add_f32 v[22:23], v[24:25], v[22:23]
	v_pk_mul_f32 v[70:71], v[68:69], v[68:69]
	v_pk_mul_f32 v[24:25], v[22:23], v[22:23]
	v_add_f32_e32 v67, v71, v70
	v_add_f32_e32 v24, v24, v67
	v_add_f32_e32 v24, v25, v24
	s_cmp_lt_i32 s0, 4
	s_cselect_b32 s1, s25, s24
	v_add_f32_dpp v24, v24, v24 quad_perm:[1,0,3,2] row_mask:0xf bank_mask:0xf bound_ctrl:1
	s_lshl_b32 s3, s0, 6
	s_add_i32 s4, s1, s3
	v_add_f32_dpp v24, v24, v24 quad_perm:[2,3,0,1] row_mask:0xf bank_mask:0xf bound_ctrl:1
	s_ashr_i32 s5, s4, 31
	s_lshl_b64 s[4:5], s[4:5], 11
	v_add_f32_dpp v24, v24, v24 row_half_mirror row_mask:0xf bank_mask:0xf bound_ctrl:1
	s_add_u32 s10, s26, s4
	s_waitcnt vmcnt(63)
	v_lshlrev_b32_e32 v66, 16, v157
	v_add_f32_dpp v24, v24, v24 row_mirror row_mask:0xf bank_mask:0xf bound_ctrl:1
	v_fmamk_f32 v24, v24, 0x3c800000, v231
	v_rsq_f32_e32 v24, v24
	v_and_b32_e32 v67, 0xffff0000, v157
	v_lshlrev_b32_e32 v70, 16, v156
	v_and_b32_e32 v71, 0xffff0000, v156
	v_pk_mul_f32 v[68:69], v[68:69], v[24:25] op_sel_hi:[1,0]
	v_pk_mul_f32 v[22:23], v[22:23], v[24:25] op_sel_hi:[1,0]
	s_addc_u32 s11, s27, s5
	v_pk_mul_f32 v[68:69], v[68:69], v[70:71]
	v_pk_mul_f32 v[22:23], v[22:23], v[66:67]
	s_mov_b64 s[4:5], s[10:11]
	v_cvt_pk_bf16_f32 v24, v68, v69
	v_cvt_pk_bf16_f32 v25, v22, v23
	v_and_b32_e32 v69, 0xffff0000, v4
	v_and_b32_e32 v68, 0xffff0000, v2
	v_mov_b32_e32 v70, v131
	v_mov_b32_e32 v71, v135
	global_store_dwordx2 v21, v[24:25], s[4:5]
	v_and_b32_e32 v23, 0xffff0000, v8
	v_and_b32_e32 v22, 0xffff0000, v6
	v_mov_b32_e32 v24, v139
	v_mov_b32_e32 v25, v143
	v_pk_add_f32 v[68:69], v[70:71], v[68:69]
	v_pk_add_f32 v[22:23], v[24:25], v[22:23]
	v_pk_mul_f32 v[70:71], v[68:69], v[68:69]
	v_pk_mul_f32 v[24:25], v[22:23], v[22:23]
	v_add_f32_e32 v67, v71, v70
	v_add_f32_e32 v24, v24, v67
	v_add_f32_e32 v24, v25, v24
	s_waitcnt vmcnt(63)
	v_lshlrev_b32_e32 v66, 16, v159
	v_and_b32_e32 v67, 0xffff0000, v159
	v_add_f32_dpp v24, v24, v24 quad_perm:[1,0,3,2] row_mask:0xf bank_mask:0xf bound_ctrl:1
	v_lshlrev_b32_e32 v70, 16, v158
	v_and_b32_e32 v71, 0xffff0000, v158
	v_add_f32_dpp v24, v24, v24 quad_perm:[2,3,0,1] row_mask:0xf bank_mask:0xf bound_ctrl:1
	s_add_u32 s4, s10, 0x800
	s_addc_u32 s5, s11, 0
	v_add_f32_dpp v24, v24, v24 row_half_mirror row_mask:0xf bank_mask:0xf bound_ctrl:1
	s_nop 1
	v_add_f32_dpp v24, v24, v24 row_mirror row_mask:0xf bank_mask:0xf bound_ctrl:1
	v_fmamk_f32 v24, v24, 0x3c800000, v231
	v_rsq_f32_e32 v24, v24
	s_nop 0
	v_pk_mul_f32 v[68:69], v[68:69], v[24:25] op_sel_hi:[1,0]
	v_pk_mul_f32 v[22:23], v[22:23], v[24:25] op_sel_hi:[1,0]
	v_pk_mul_f32 v[68:69], v[68:69], v[70:71]
	v_pk_mul_f32 v[22:23], v[22:23], v[66:67]
	v_cvt_pk_bf16_f32 v24, v68, v69
	v_cvt_pk_bf16_f32 v25, v22, v23
	v_lshlrev_b32_e32 v69, 16, v5
	v_lshlrev_b32_e32 v68, 16, v3
	v_mov_b32_e32 v70, v132
	v_mov_b32_e32 v71, v136
	global_store_dwordx2 v21, v[24:25], s[4:5]
	v_lshlrev_b32_e32 v23, 16, v9
	v_lshlrev_b32_e32 v22, 16, v7
	v_mov_b32_e32 v24, v140
	v_mov_b32_e32 v25, v144
	v_pk_add_f32 v[68:69], v[70:71], v[68:69]
	v_pk_add_f32 v[22:23], v[24:25], v[22:23]
	v_pk_mul_f32 v[70:71], v[68:69], v[68:69]
	v_pk_mul_f32 v[24:25], v[22:23], v[22:23]
	v_add_f32_e32 v67, v71, v70
	v_add_f32_e32 v24, v24, v67
	v_add_f32_e32 v24, v25, v24
	s_waitcnt vmcnt(63)
	v_lshlrev_b32_e32 v66, 16, v161
	v_and_b32_e32 v67, 0xffff0000, v161
	v_add_f32_dpp v24, v24, v24 quad_perm:[1,0,3,2] row_mask:0xf bank_mask:0xf bound_ctrl:1
	v_lshlrev_b32_e32 v70, 16, v160
	v_and_b32_e32 v71, 0xffff0000, v160
	v_add_f32_dpp v24, v24, v24 quad_perm:[2,3,0,1] row_mask:0xf bank_mask:0xf bound_ctrl:1
	s_add_u32 s4, s10, 0x1000
	s_addc_u32 s5, s11, 0
	v_add_f32_dpp v24, v24, v24 row_half_mirror row_mask:0xf bank_mask:0xf bound_ctrl:1
	s_nop 1
	v_add_f32_dpp v24, v24, v24 row_mirror row_mask:0xf bank_mask:0xf bound_ctrl:1
	v_fmamk_f32 v24, v24, 0x3c800000, v231
	v_rsq_f32_e32 v24, v24
	s_nop 0
	v_pk_mul_f32 v[68:69], v[68:69], v[24:25] op_sel_hi:[1,0]
	v_pk_mul_f32 v[22:23], v[22:23], v[24:25] op_sel_hi:[1,0]
	v_pk_mul_f32 v[68:69], v[68:69], v[70:71]
	v_pk_mul_f32 v[22:23], v[22:23], v[66:67]
	v_cvt_pk_bf16_f32 v24, v68, v69
	v_cvt_pk_bf16_f32 v25, v22, v23
	v_and_b32_e32 v69, 0xffff0000, v5
	v_and_b32_e32 v68, 0xffff0000, v3
	v_mov_b32_e32 v70, v133
	v_mov_b32_e32 v71, v137
	global_store_dwordx2 v21, v[24:25], s[4:5]
	v_and_b32_e32 v23, 0xffff0000, v9
	v_and_b32_e32 v22, 0xffff0000, v7
	v_mov_b32_e32 v24, v141
	v_mov_b32_e32 v25, v145
	v_pk_add_f32 v[68:69], v[70:71], v[68:69]
	v_pk_add_f32 v[22:23], v[24:25], v[22:23]
	v_pk_mul_f32 v[70:71], v[68:69], v[68:69]
	v_pk_mul_f32 v[24:25], v[22:23], v[22:23]
	v_add_f32_e32 v67, v71, v70
	v_add_f32_e32 v24, v24, v67
	v_add_f32_e32 v24, v25, v24
	s_waitcnt vmcnt(63)
	v_lshlrev_b32_e32 v66, 16, v163
	v_and_b32_e32 v67, 0xffff0000, v163
	v_add_f32_dpp v24, v24, v24 quad_perm:[1,0,3,2] row_mask:0xf bank_mask:0xf bound_ctrl:1
	v_lshlrev_b32_e32 v70, 16, v162
	v_and_b32_e32 v71, 0xffff0000, v162
	v_add_f32_dpp v24, v24, v24 quad_perm:[2,3,0,1] row_mask:0xf bank_mask:0xf bound_ctrl:1
	s_add_u32 s4, s10, 0x1800
	s_addc_u32 s5, s11, 0
	v_add_f32_dpp v24, v24, v24 row_half_mirror row_mask:0xf bank_mask:0xf bound_ctrl:1
	s_nop 1
	v_add_f32_dpp v24, v24, v24 row_mirror row_mask:0xf bank_mask:0xf bound_ctrl:1
	v_fmamk_f32 v24, v24, 0x3c800000, v231
	v_rsq_f32_e32 v24, v24
	s_nop 0
	v_pk_mul_f32 v[68:69], v[68:69], v[24:25] op_sel_hi:[1,0]
	v_pk_mul_f32 v[22:23], v[22:23], v[24:25] op_sel_hi:[1,0]
	v_pk_mul_f32 v[68:69], v[68:69], v[70:71]
	v_pk_mul_f32 v[22:23], v[22:23], v[66:67]
	v_cvt_pk_bf16_f32 v24, v68, v69
	v_cvt_pk_bf16_f32 v25, v22, v23
	global_store_dwordx2 v21, v[24:25], s[4:5]
	s_cbranch_execz .LBB0_607

; __device__ __forceinline__ const char* upin(const char* p) { asm volatile("" : "+s"(p)); return p; }
; __device__ __forceinline__ char* upin(char* p) { asm volatile("" : "+s"(p)); return p; }
; template <bool GDN> __device__ __forceinline__ void scan_fin_load(const Frame& F, int b, int h, int dir, const ScanLane& L, int s, const float* PEND, ScanFin& f) {
;     const int cidx = dir ? (s < 4 ? 3 - s : 39 - s) : s; const int row0 = chunk_row0(b, cidx);
;     const char* pp = upin((const char*)PEND + (size_t)((b * 4 + h) * 36 + cidx) * 16384);
;     const char* gp = (const char*)F.Z + ((size_t)row0 * ZW + (GDN ? ZC_GZ : ZC_LO) + h * 64) * 2;
; #pragma unroll
;     for (int pr = 0; pr < 2; ++pr) { const v4u qp = ldu<v4u>(pp + pr * 1024, L.pend); f.pend[2 * pr] = (v2u){qp.x, qp.y}; f.pend[2 * pr + 1] = (v2u){qp.z, qp.w}; }
; #pragma unroll
;     for (int t = 0; t < 4; ++t) f.gz[t] = ldu<v2u>(upin(gp + (size_t)t * ZW * 2), L.gz);
; }
.LBB0_605:
	s_add_i32 s4, s22, 38
	s_and_b64 s[0:1], s[90:91], exec
	s_cselect_b32 s0, s3, s4
	s_add_i32 s4, s0, s30
	s_lshl_b32 s1, s0, 6
	s_ashr_i32 s5, s4, 31
	s_add_i32 s1, s1, s24
	s_lshl_b64 s[4:5], s[4:5], 14
	s_add_u32 s4, s96, s4
	s_mul_hi_i32 s7, s1, 0xd00
	s_mul_i32 s6, s1, 0xd00
	s_addc_u32 s5, s97, s5
	s_or_b64 s[6:7], s[6:7], s[38:39]
	s_waitcnt vmcnt(0)
	s_lshl_b64 s[6:7], s[6:7], 1
	global_load_dwordx4 v[2:5], v20, s[4:5]
	global_load_dwordx4 v[6:9], v20, s[4:5] offset:1024
	s_add_u32 s4, s16, s6
	s_addc_u32 s5, s17, s7
	s_mov_b64 s[6:7], s[4:5]
	global_load_dwordx2 v[156:157], v19, s[6:7]
	s_add_u32 s6, s4, 0x1a00
	s_addc_u32 s7, s5, 0
	global_load_dwordx2 v[158:159], v19, s[6:7]
	s_add_u32 s6, s4, 0x3400
	s_addc_u32 s7, s5, 0
	s_add_u32 s4, s4, 0x4e00
	s_addc_u32 s5, s5, 0
	global_load_dwordx2 v[160:161], v19, s[6:7]
	global_load_dwordx2 v[162:163], v19, s[4:5]
	s_waitcnt vmcnt(0)
	s_cmp_lt_u32 s23, 16
	s_mov_b64 s[10:11], -1
	s_cbranch_scc0 .LBB0_602
